# nt cache policy on the once-written output stores of the first GEMM phase epilogue, stacked on v82
# baseline (speedup 1.0000x reference)
; #define EPI_GET(dst, ai, bj, m, s) do { _Pragma("unroll") for (int e_ = 0; e_ < 4; ++e_) { (dst)[e_] = acc[ai][bj][m][0][e_] * (s); (dst)[4 + e_] = acc[ai][bj][m][1][e_] * (s); } } while (0)
;     __device__ __forceinline__ void operator()(const f32x4 (&acc)[2][2][4][2], const Unit& u, int wr, int wc, int fr, int fq) const {
;         const int pn = u.pn; const int c8 = wc * 32 + 8 * fq; const bool samp = (u.pm >= 64);
; #pragma unroll
;         for (int ai = 0; ai < 2; ++ai) {
;             float rsa[4];
; #pragma unroll
;             for (int m = 0; m < 4; ++m) rsa[m] = rstd[EPI_ROWS(ai, m)];
; #pragma unroll
;             for (int m = 0; m < 4; ++m) {
;                 const int r = EPI_ROWS(ai, m); const float rs = rsa[m];
;                 float lo[8], hi[8]; EPI_GET(lo, ai, 0, m, rs); EPI_GET(hi, ai, 1, m, rs);
;                 const int rl = samp ? r - MP : r; const int pos = samp ? PAST + (rl & 7) : (rl & (SEQ - 1));
;                 if (pn < 2) {
;                     store8_bf16(cbb + (size_t)r * 512 + pn * 256 + c8, lo); store8_bf16(cbb + (size_t)r * 512 + pn * 256 + 128 + c8, hi);
;     ...
;                     } else if (wc == 1 && fq == 0) {
;                         store8_f32(iwf + (size_t)r * 8, lo);
;                     }
.LBB0_330:
	s_cmp_lt_i32 s8, 64
	s_cselect_b64 s[84:85], -1, 0
	s_cmp_gt_i32 s10, 1
	s_cselect_b64 s[12:13], -1, 0
	s_cmp_gt_u32 s10, 5
	s_cselect_b64 s[34:35], -1, 0
	s_cmp_lt_u32 s10, 10
	s_cselect_b64 s[24:25], -1, 0
	s_cmp_gt_u32 s10, 9
	s_cselect_b64 s[2:3], -1, 0
	s_and_b32 s6, s10, 0x7ffffffe
	s_cmp_lg_u32 s6, 12
	s_cselect_b64 s[6:7], -1, 0
	s_and_b64 s[20:21], s[2:3], s[6:7]
	s_cmp_gt_u32 s10, 11
	s_cselect_b64 s[16:17], -1, 0
	s_lshl_b32 s6, s10, 2
	s_and_b32 s6, s6, 4
	s_lshl_b32 s56, s10, 8
	s_or_b32 s6, s6, s33
	s_cmp_lt_i32 s10, 8
	s_cselect_b64 s[14:15], -1, 0
	s_cmp_gt_i32 s10, 7
	s_cselect_b64 s[94:95], -1, 0
	s_lshl_b32 s18, s6, 6
	s_cmp_gt_i32 s8, 63
	s_cselect_b64 s[6:7], -1, 0
	s_and_b64 s[26:27], s[6:7], exec
	s_mov_b32 s9, 0x2403400
	s_cselect_b32 s69, s9, 0x2100000
	s_mov_b32 s9, 0x2383400
	s_cselect_b32 s55, s9, 0x1900000
	s_mov_b32 s9, 0x2303400
	s_cselect_b32 s53, s9, 0x1100000
	s_lshl_b32 s58, s8, 8
	v_add_u32_e32 v178, s58, v185
	v_ashrrev_i32_e32 v179, 31, v178
	v_lshl_add_u64 v[128:129], v[178:179], 2, s[86:87]
	global_load_dword v130, v[128:129], off
	global_load_dword v186, v[128:129], off offset:64
	global_load_dword v184, v[128:129], off offset:128
	global_load_dword v180, v[128:129], off offset:192
	v_add_u32_e32 v176, s56, v194
	v_lshl_add_u32 v172, s10, 7, v195
	s_add_i32 s58, s58, s74
	v_ashrrev_i32_e32 v177, 31, v176
	v_lshl_add_u64 v[174:175], s[18:19], 0, v[154:155]
	v_ashrrev_i32_e32 v173, 31, v172
	v_or_b32_e32 v182, s58, v181
	s_mov_b64 s[8:9], -1
	s_and_b64 vcc, exec, s[12:13]
	s_waitcnt vmcnt(0)
	v_pk_mul_f32 v[124:125], v[124:125], v[130:131] op_sel_hi:[1,0]
	v_pk_mul_f32 v[116:117], v[116:117], v[130:131] op_sel_hi:[1,0]
	v_pk_mul_f32 v[120:121], v[120:121], v[130:131] op_sel_hi:[1,0]
	v_pk_mul_f32 v[112:113], v[112:113], v[130:131] op_sel_hi:[1,0]
	v_pk_mul_f32 v[126:127], v[126:127], v[130:131] op_sel_hi:[1,0]
	v_pk_mul_f32 v[118:119], v[118:119], v[130:131] op_sel_hi:[1,0]
	v_pk_mul_f32 v[122:123], v[122:123], v[130:131] op_sel_hi:[1,0]
	v_pk_mul_f32 v[114:115], v[114:115], v[130:131] op_sel_hi:[1,0]
	s_cbranch_vccz .LBB0_361
	v_add_u32_e32 v179, 0xffffc000, v182
	v_cndmask_b32_e64 v188, v182, v179, s[6:7]
	v_and_b32_e32 v202, 7, v188
	s_and_b64 vcc, exec, s[34:35]
	s_cbranch_vccz .LBB0_356
	v_or_b32_e32 v128, 0x800, v202
	v_and_b32_e32 v129, 0x1fcf, v182
	v_cndmask_b32_e64 v203, v129, v128, s[6:7]
	s_and_b64 vcc, exec, s[20:21]
	s_cbranch_vccz .LBB0_343
	s_and_b64 vcc, exec, s[16:17]
	s_cbranch_vccz .LBB0_340
	v_readlane_b32 s8, v249, 14
	v_readlane_b32 s9, v249, 15
	s_and_b64 vcc, exec, s[8:9]
	s_cbranch_vccz .LBB0_637
	s_mov_b64 s[8:9], exec
	v_readlane_b32 s10, v249, 16
	v_readlane_b32 s11, v249, 17
	s_and_b64 s[10:11], s[8:9], s[10:11]
	s_mov_b64 exec, s[10:11]
	s_cbranch_execz .LBB0_337
	v_ashrrev_i32_e32 v183, 31, v182
	v_readlane_b32 s10, v249, 12
	v_lshlrev_b64 v[128:129], 5, v[182:183]
	v_readlane_b32 s11, v249, 13
	s_nop 1
	v_lshl_add_u64 v[128:129], s[10:11], 0, v[128:129]
	global_store_dwordx4 v[128:129], v[124:127], off nt
	global_store_dwordx4 v[128:129], v[120:123], off offset:16 nt

;     __device__ __forceinline__ void operator()(const f32x4 (&acc)[2][2][4][2], const Unit& u, int wr, int wc, int fr, int fq) const {
;     ...
;                     if (wc == 0) {
;                         const int d0 = 8 * fq; float cs[8], sn[8]; load8_f32(cosT + (size_t)pos * 32 + d0, cs); load8_f32(sinT + (size_t)pos * 32 + d0, sn);
;                         float ol[8], oh[8];
; #pragma unroll
;                         for (int e = 0; e < 8; ++e) { ol[e] = lo[e] * cs[e] - hi[e] * sn[e]; oh[e] = hi[e] * cs[e] + lo[e] * sn[e]; }
;                         store8_bf16(kib + (size_t)r * 64 + d0, ol); store8_bf16(kib + (size_t)r * 64 + 32 + d0, oh);
;                         float* io = out + (samp ? OFF_IK_S : OFF_IK_P) + (size_t)rl * 64 + d0; store8_f32(io, ol); store8_f32(io + 32, oh);
.LBB0_338:
	v_lshlrev_b32_e32 v152, 7, v203
	v_lshl_add_u64 v[128:129], v[158:159], 0, v[152:153]
	v_lshl_add_u64 v[136:137], v[160:161], 0, v[152:153]
	global_load_dwordx4 v[140:143], v[128:129], off offset:16
	s_nop 0
	global_load_dwordx4 v[128:131], v[128:129], off
	s_nop 0
	global_load_dwordx4 v[132:135], v[136:137], off offset:16
	s_nop 0
	global_load_dwordx4 v[136:139], v[136:137], off
	v_mov_b32_e32 v190, v124
	v_mov_b32_e32 v191, v116
	v_mov_b32_e32 v204, v116
	v_mov_b32_e32 v205, v124
	v_ashrrev_i32_e32 v183, 31, v182
	v_readlane_b32 s60, v250, 0
	s_lshl_b32 s8, s69, 2
	v_readlane_b32 s62, v250, 2
	v_readlane_b32 s63, v250, 3
	s_add_u32 s8, s62, s8
	v_ashrrev_i32_e32 v189, 31, v188
	s_addc_u32 s9, s63, 0
	v_readlane_b32 s61, v250, 1
	v_readlane_b32 s64, v250, 4
	v_readlane_b32 s65, v250, 5
	v_readlane_b32 s66, v250, 6
	v_readlane_b32 s67, v250, 7
	s_waitcnt vmcnt(2)
	v_mov_b32_e32 v192, v128
	s_waitcnt vmcnt(0)
	v_mov_b32_e32 v193, v136
	v_pk_mul_f32 v[190:191], v[190:191], v[192:193]
	v_pk_mul_f32 v[192:193], v[204:205], v[192:193]
	v_mov_b32_e32 v204, v125
	v_mov_b32_e32 v205, v117
	v_mov_b32_e32 v136, v129
	v_pk_mul_f32 v[128:129], v[204:205], v[136:137]
	v_mov_b32_e32 v204, v190
	v_mov_b32_e32 v205, v128
	v_mov_b32_e32 v128, v191
	v_mov_b32_e32 v190, v117
	v_mov_b32_e32 v191, v125
	v_pk_mul_f32 v[136:137], v[190:191], v[136:137]
	v_mov_b32_e32 v190, v192
	v_mov_b32_e32 v191, v136
	v_mov_b32_e32 v136, v193
	v_pk_add_f32 v[128:129], v[204:205], v[128:129] neg_lo:[0,1] neg_hi:[0,1]
	v_pk_add_f32 v[136:137], v[190:191], v[136:137]
	v_mov_b32_e32 v190, v126
	v_mov_b32_e32 v191, v118
	v_mov_b32_e32 v192, v130
	v_mov_b32_e32 v193, v138
	v_mov_b32_e32 v204, v118
	v_mov_b32_e32 v205, v126
	v_pk_mul_f32 v[190:191], v[190:191], v[192:193]
	v_pk_mul_f32 v[192:193], v[204:205], v[192:193]
	v_mov_b32_e32 v204, v127
	v_mov_b32_e32 v205, v119
	v_mov_b32_e32 v138, v131
	v_pk_mul_f32 v[130:131], v[204:205], v[138:139]
	v_mov_b32_e32 v204, v190
	v_mov_b32_e32 v205, v130
	v_mov_b32_e32 v130, v191
	v_mov_b32_e32 v190, v119
	v_mov_b32_e32 v191, v127
	v_pk_mul_f32 v[138:139], v[190:191], v[138:139]
	v_mov_b32_e32 v190, v192
	v_mov_b32_e32 v191, v138
	v_mov_b32_e32 v138, v193
	v_pk_add_f32 v[130:131], v[204:205], v[130:131] neg_lo:[0,1] neg_hi:[0,1]
	v_pk_add_f32 v[138:139], v[190:191], v[138:139]
	v_mov_b32_e32 v190, v120
	v_mov_b32_e32 v191, v112
	v_mov_b32_e32 v192, v140
	v_mov_b32_e32 v193, v132
	v_mov_b32_e32 v204, v112
	v_mov_b32_e32 v205, v120
	v_pk_mul_f32 v[190:191], v[190:191], v[192:193]
	v_pk_mul_f32 v[192:193], v[204:205], v[192:193]
	v_mov_b32_e32 v204, v121
	v_mov_b32_e32 v205, v113
	v_mov_b32_e32 v132, v141
	v_pk_mul_f32 v[140:141], v[204:205], v[132:133]
	v_mov_b32_e32 v204, v190
	v_mov_b32_e32 v205, v140
	v_mov_b32_e32 v140, v191
	v_mov_b32_e32 v190, v113
	v_mov_b32_e32 v191, v121
	v_pk_mul_f32 v[132:133], v[190:191], v[132:133]
	v_mov_b32_e32 v190, v192
	v_mov_b32_e32 v191, v132
	v_mov_b32_e32 v132, v193
	v_pk_add_f32 v[140:141], v[204:205], v[140:141] neg_lo:[0,1] neg_hi:[0,1]
	v_pk_add_f32 v[132:133], v[190:191], v[132:133]
	v_mov_b32_e32 v190, v122
	v_mov_b32_e32 v191, v114
	v_mov_b32_e32 v192, v142
	v_mov_b32_e32 v193, v134
	v_mov_b32_e32 v204, v114
	v_mov_b32_e32 v205, v122
	v_pk_mul_f32 v[190:191], v[190:191], v[192:193]
	v_pk_mul_f32 v[192:193], v[204:205], v[192:193]
	v_mov_b32_e32 v204, v123
	v_mov_b32_e32 v205, v115
	v_mov_b32_e32 v134, v143
	v_pk_mul_f32 v[142:143], v[204:205], v[134:135]
	v_mov_b32_e32 v204, v190
	v_mov_b32_e32 v205, v142
	v_mov_b32_e32 v142, v191
	v_mov_b32_e32 v190, v115
	v_mov_b32_e32 v191, v123
	v_pk_mul_f32 v[134:135], v[190:191], v[134:135]
	v_mov_b32_e32 v190, v192
	v_mov_b32_e32 v191, v134
	v_mov_b32_e32 v134, v193
	v_pk_add_f32 v[134:135], v[190:191], v[134:135]
	v_lshlrev_b64 v[190:191], 7, v[182:183]
	v_pk_add_f32 v[142:143], v[204:205], v[142:143] neg_lo:[0,1] neg_hi:[0,1]
	v_lshl_add_u64 v[204:205], v[162:163], 0, v[190:191]
	v_cvt_pk_bf16_f32 v190, v128, v129
	v_cvt_pk_bf16_f32 v191, v130, v131
	v_cvt_pk_bf16_f32 v192, v140, v141
	v_cvt_pk_bf16_f32 v193, v142, v143
	global_store_dwordx4 v[204:205], v[190:193], off nt
	s_nop 1
	v_cvt_pk_bf16_f32 v190, v136, v137
	v_cvt_pk_bf16_f32 v191, v138, v139
	v_cvt_pk_bf16_f32 v192, v132, v133
	v_cvt_pk_bf16_f32 v193, v134, v135
	global_store_dwordx4 v[204:205], v[190:193], off offset:64 nt
	s_nop 1
	v_lshlrev_b64 v[190:191], 8, v[188:189]
	v_lshl_add_u64 v[190:191], s[8:9], 0, v[190:191]
	v_lshl_add_u64 v[190:191], v[154:155], 2, v[190:191]
	global_store_dwordx4 v[190:191], v[128:131], off nt
	global_store_dwordx4 v[190:191], v[140:143], off offset:16 nt
	global_store_dwordx4 v[190:191], v[136:139], off offset:128 nt
	global_store_dwordx4 v[190:191], v[132:135], off offset:144 nt

;     __device__ __forceinline__ void operator()(const f32x4 (&acc)[2][2][4][2], const Unit& u, int wr, int wc, int fr, int fq) const {
;     ...
;                 } else if (pn < 12) {
;                     const int c = 256 * (pn - 10) + c8;
;                     store8_bf16(vb + (size_t)r * 512 + c, lo); store8_bf16(vb + (size_t)r * 512 + c + 128, hi);
;                     float* vo = out + (samp ? OFF_V_S : OFF_V_P) + (size_t)rl * 512 + c; store8_f32(vo, lo); store8_f32(vo + 128, hi);
.LBB0_340:
	s_andn2_b64 vcc, exec, s[8:9]
	s_cbranch_vccnz .LBB0_342
	v_ashrrev_i32_e32 v183, 31, v182
	v_readlane_b32 s8, v249, 8
	v_lshlrev_b64 v[128:129], 10, v[182:183]
	v_readlane_b32 s9, v249, 9
	v_readlane_b32 s60, v250, 0
	v_readlane_b32 s62, v250, 2
	v_lshl_add_u64 v[128:129], s[8:9], 0, v[128:129]
	v_lshl_add_u64 v[132:133], v[176:177], 1, v[128:129]
	v_cvt_pk_bf16_f32 v128, v124, v125
	v_cvt_pk_bf16_f32 v129, v126, v127
	s_lshl_b32 s8, s55, 2
	v_cvt_pk_bf16_f32 v130, v120, v121
	v_cvt_pk_bf16_f32 v131, v122, v123
	global_store_dwordx4 v[132:133], v[128:131], off nt
	v_readlane_b32 s63, v250, 3
	s_add_u32 s8, s62, s8
	v_cvt_pk_bf16_f32 v128, v116, v117
	v_cvt_pk_bf16_f32 v129, v118, v119
	v_ashrrev_i32_e32 v189, 31, v188
	v_cvt_pk_bf16_f32 v130, v112, v113
	v_cvt_pk_bf16_f32 v131, v114, v115
	global_store_dwordx4 v[132:133], v[128:131], off offset:256 nt
	s_addc_u32 s9, s63, 0
	v_readlane_b32 s61, v250, 1
	v_lshlrev_b64 v[128:129], 11, v[188:189]
	v_lshl_add_u64 v[128:129], s[8:9], 0, v[128:129]
	v_lshl_add_u64 v[128:129], v[176:177], 2, v[128:129]
	v_readlane_b32 s64, v250, 4
	v_readlane_b32 s65, v250, 5
	v_readlane_b32 s66, v250, 6
	v_readlane_b32 s67, v250, 7
	global_store_dwordx4 v[128:129], v[124:127], off nt
	global_store_dwordx4 v[128:129], v[120:123], off offset:16 nt
	global_store_dwordx4 v[128:129], v[116:119], off offset:512 nt
	global_store_dwordx4 v[128:129], v[112:115], off offset:528 nt

;     __device__ __forceinline__ void operator()(const f32x4 (&acc)[2][2][4][2], const Unit& u, int wr, int wc, int fr, int fq) const {
;     ...
;                     float cs[8], sn[8]; load8_f32(cosT + (size_t)pos * 32 + d0, cs); load8_f32(sinT + (size_t)pos * 32 + d0, sn);
;                     float ol[8], oh[8];
; #pragma unroll
;                     for (int e = 0; e < 8; ++e) { ol[e] = lo[e] * cs[e] - hi[e] * sn[e]; oh[e] = hi[e] * cs[e] + lo[e] * sn[e]; }
;                     const size_t o512 = (size_t)r * 512 + head * 64 + d0;
;                     if (pn < 8) {
; #pragma unroll
;                         for (int e = 0; e < 8; ++e) { ol[e] *= 0.18033688011112042f; oh[e] *= 0.18033688011112042f; }
;                         store8_bf16(qb + o512, ol); store8_bf16(qb + o512 + 32, oh);
;                     } else if (pn < 10) {
;                         store8_bf16(kb + o512, ol); store8_bf16(kb + o512 + 32, oh);
;                         float* ko = out + (samp ? OFF_K_S : OFF_K_P) + (size_t)rl * 512 + head * 64 + d0; store8_f32(ko, ol); store8_f32(ko + 32, oh);
;                     } else {
;                         store8_bf16(qib + o512, ol); store8_bf16(qib + o512 + 32, oh);
;                     }
.LBB0_347:
	v_lshlrev_b32_e32 v152, 7, v203
	v_lshl_add_u64 v[132:133], v[158:159], 0, v[152:153]
	global_load_dwordx4 v[204:207], v[132:133], off offset:16
	global_load_dwordx4 v[208:211], v[132:133], off
	v_lshl_add_u64 v[132:133], v[160:161], 0, v[152:153]
	global_load_dwordx4 v[212:215], v[132:133], off offset:16
	global_load_dwordx4 v[216:219], v[132:133], off
	v_ashrrev_i32_e32 v183, 31, v182
	s_mov_b64 s[8:9], -1
	s_and_b64 vcc, exec, s[94:95]
	s_waitcnt vmcnt(0)
	v_pk_mul_f32 v[140:141], v[190:191], v[216:217]
	v_pk_mul_f32 v[132:133], v[134:135], v[216:217]
	v_pk_fma_f32 v[140:141], v[134:135], v[208:209], v[140:141]
	v_pk_mul_f32 v[134:135], v[128:129], v[218:219]
	v_pk_fma_f32 v[132:133], v[190:191], v[208:209], v[132:133] neg_lo:[0,0,1] neg_hi:[0,0,1]
	v_pk_fma_f32 v[134:135], v[142:143], v[210:211], v[134:135] neg_lo:[0,0,1] neg_hi:[0,0,1]
	v_pk_mul_f32 v[142:143], v[142:143], v[218:219]
	v_lshlrev_b64 v[190:191], 9, v[182:183]
	v_pk_fma_f32 v[142:143], v[128:129], v[210:211], v[142:143]
	v_pk_mul_f32 v[128:129], v[130:131], v[212:213]
	v_lshl_add_u64 v[190:191], v[174:175], 0, v[190:191]
	v_pk_fma_f32 v[128:129], v[136:137], v[204:205], v[128:129] neg_lo:[0,0,1] neg_hi:[0,0,1]
	v_pk_mul_f32 v[136:137], v[136:137], v[212:213]
	s_nop 0
	v_pk_fma_f32 v[136:137], v[130:131], v[204:205], v[136:137]
	v_pk_mul_f32 v[130:131], v[192:193], v[214:215]
	s_nop 0
	v_pk_fma_f32 v[130:131], v[138:139], v[206:207], v[130:131] neg_lo:[0,0,1] neg_hi:[0,0,1]
	v_pk_mul_f32 v[138:139], v[138:139], v[214:215]
	s_nop 0
	v_pk_fma_f32 v[138:139], v[192:193], v[206:207], v[138:139]
	s_cbranch_vccz .LBB0_353
	s_and_b64 vcc, exec, s[2:3]
	s_cbranch_vccz .LBB0_350
	v_readlane_b32 s8, v249, 10
	v_readlane_b32 s9, v249, 11
	v_cvt_pk_bf16_f32 v204, v132, v133
	v_cvt_pk_bf16_f32 v205, v134, v135
	v_cvt_pk_bf16_f32 v206, v128, v129
	v_cvt_pk_bf16_f32 v207, v130, v131
	s_nop 1
	v_lshl_add_u64 v[192:193], v[190:191], 1, s[8:9]
	global_store_dwordx4 v[192:193], v[204:207], off nt
	s_mov_b64 s[8:9], 0
	s_nop 0
	v_cvt_pk_bf16_f32 v204, v140, v141
	v_cvt_pk_bf16_f32 v205, v142, v143
	v_cvt_pk_bf16_f32 v206, v136, v137
	v_cvt_pk_bf16_f32 v207, v138, v139
	global_store_dwordx4 v[192:193], v[204:207], off offset:64 nt
.LBB0_350:
	s_andn2_b64 vcc, exec, s[8:9]
	s_cbranch_vccnz .LBB0_352
	v_readlane_b32 s8, v249, 6
	v_readlane_b32 s9, v249, 7
	v_readlane_b32 s60, v250, 0
	v_readlane_b32 s62, v250, 2
	v_lshl_add_u64 v[192:193], v[190:191], 1, s[8:9]
	s_lshl_b32 s8, s53, 2
	v_readlane_b32 s63, v250, 3
	s_add_u32 s8, s62, s8
	v_ashrrev_i32_e32 v189, 31, v188
	s_addc_u32 s9, s63, 0
	v_lshlrev_b64 v[188:189], 11, v[188:189]
	v_lshl_add_u64 v[188:189], s[8:9], 0, v[188:189]
	s_lshl_b32 s8, s18, 2
	s_mov_b32 s9, s19
	v_lshl_add_u64 v[188:189], v[188:189], 0, s[8:9]
	v_cvt_pk_bf16_f32 v204, v132, v133
	v_cvt_pk_bf16_f32 v205, v134, v135
	v_cvt_pk_bf16_f32 v206, v128, v129
	v_cvt_pk_bf16_f32 v207, v130, v131
	v_lshl_add_u64 v[188:189], v[154:155], 2, v[188:189]
	global_store_dwordx4 v[192:193], v[204:207], off nt
	v_readlane_b32 s61, v250, 1
	v_readlane_b32 s64, v250, 4
	v_cvt_pk_bf16_f32 v204, v140, v141
	v_cvt_pk_bf16_f32 v205, v142, v143
	v_cvt_pk_bf16_f32 v206, v136, v137
	v_cvt_pk_bf16_f32 v207, v138, v139
	global_store_dwordx4 v[192:193], v[204:207], off offset:64 nt
	v_readlane_b32 s65, v250, 5
	v_readlane_b32 s66, v250, 6
	v_readlane_b32 s67, v250, 7
	global_store_dwordx4 v[188:189], v[132:135], off nt
	global_store_dwordx4 v[188:189], v[128:131], off offset:16 nt
	global_store_dwordx4 v[188:189], v[140:143], off offset:128 nt
	global_store_dwordx4 v[188:189], v[136:139], off offset:144 nt

;     __device__ __forceinline__ void operator()(const f32x4 (&acc)[2][2][4][2], const Unit& u, int wr, int wc, int fr, int fq) const {
;     ...
;                     if (pn < 8) {
; #pragma unroll
;                         for (int e = 0; e < 8; ++e) { ol[e] *= 0.18033688011112042f; oh[e] *= 0.18033688011112042f; }
;                         store8_bf16(qb + o512, ol); store8_bf16(qb + o512 + 32, oh);
.LBB0_353:
	s_andn2_b64 vcc, exec, s[8:9]
	s_cbranch_vccnz .LBB0_355
	v_readlane_b32 s8, v249, 4
	v_mul_f32_e32 v131, 0x3e38aa3b, v131
	v_readlane_b32 s9, v249, 5
	v_mul_f32_e32 v152, 0x3e38aa3b, v132
	v_mul_f32_e32 v183, 0x3e38aa3b, v133
	v_mul_f32_e32 v134, 0x3e38aa3b, v134
	v_mul_f32_e32 v135, 0x3e38aa3b, v135
	v_mul_f32_e32 v188, 0x3e38aa3b, v128
	v_mul_f32_e32 v189, 0x3e38aa3b, v129
	v_mul_f32_e32 v192, 0x3e38aa3b, v130
	v_lshl_add_u64 v[132:133], v[190:191], 1, s[8:9]
	v_cvt_pk_bf16_f32 v128, v152, v183
	v_cvt_pk_bf16_f32 v129, v134, v135
	v_cvt_pk_bf16_f32 v130, v188, v189
	v_cvt_pk_bf16_f32 v131, v192, v131
	v_mul_f32_e32 v140, 0x3e38aa3b, v140
	v_mul_f32_e32 v141, 0x3e38aa3b, v141
	v_mul_f32_e32 v142, 0x3e38aa3b, v142
	v_mul_f32_e32 v143, 0x3e38aa3b, v143
	v_mul_f32_e32 v136, 0x3e38aa3b, v136
	v_mul_f32_e32 v137, 0x3e38aa3b, v137
	v_mul_f32_e32 v138, 0x3e38aa3b, v138
	v_mul_f32_e32 v139, 0x3e38aa3b, v139
	global_store_dwordx4 v[132:133], v[128:131], off nt
	s_nop 1
	v_cvt_pk_bf16_f32 v128, v140, v141
	v_cvt_pk_bf16_f32 v129, v142, v143
	v_cvt_pk_bf16_f32 v130, v136, v137
	v_cvt_pk_bf16_f32 v131, v138, v139
	global_store_dwordx4 v[132:133], v[128:131], off offset:64 nt

;     __device__ __forceinline__ void operator()(const f32x4 (&acc)[2][2][4][2], const Unit& u, int wr, int wc, int fr, int fq) const {
;     ...
;                 } else if (pn < 6) {
;                     const int ch = 128 * (pn - 2) + c8; float uu[8];
; #pragma unroll
;                     for (int e = 0; e < 8; ++e) uu[e] = lo[e] * hi[e];
;                     store8_bf16(ub + (size_t)r * 512 + ch, uu);
;                     if (!samp) { const int t = rl & (SEQ - 1); if (t >= SEQ - 2) store8_f32(out + OFF_CM_P + (size_t)((rl >> 13) * 2 + (t - (SEQ - 2))) * 512 + ch, uu); }
;                     else { const int tt = rl & 7; if (tt >= 6) store8_f32(out + OFF_CM_S + (size_t)((rl >> 3) * 2 + (tt - 6)) * 512 + ch, uu); }
.LBB0_356:
	s_andn2_b64 vcc, exec, s[8:9]
	s_cbranch_vccnz .LBB0_360
	v_ashrrev_i32_e32 v183, 31, v182
	v_lshlrev_b64 v[136:137], 10, v[182:183]
	v_lshl_add_u64 v[136:137], s[88:89], 0, v[136:137]
	v_cmp_lt_u32_e32 vcc, 5, v202
	v_pk_mul_f32 v[132:133], v[124:125], v[116:117]
	v_pk_mul_f32 v[134:135], v[126:127], v[118:119]
	v_pk_mul_f32 v[128:129], v[120:121], v[112:113]
	v_pk_mul_f32 v[130:131], v[122:123], v[114:115]
	v_lshl_add_u64 v[140:141], v[172:173], 1, v[136:137]
	s_and_b64 s[10:11], s[6:7], vcc
	v_cvt_pk_bf16_f32 v136, v132, v133
	v_cvt_pk_bf16_f32 v137, v134, v135
	v_cvt_pk_bf16_f32 v138, v128, v129
	v_cvt_pk_bf16_f32 v139, v130, v131
	global_store_dwordx4 v[140:141], v[136:139], off nt
	s_and_saveexec_b64 s[8:9], s[10:11]
	s_cbranch_execz .LBB0_359
	v_ashrrev_i32_e32 v136, 2, v179
	v_and_b32_e32 v136, -14, v136
	v_add3_u32 v136, v202, v136, -6
	v_ashrrev_i32_e32 v137, 31, v136
	v_readlane_b32 s10, v249, 18
	v_lshlrev_b64 v[136:137], 11, v[136:137]
	v_readlane_b32 s11, v249, 19
	s_nop 1
	v_lshl_add_u64 v[136:137], s[10:11], 0, v[136:137]
	v_lshl_add_u64 v[136:137], v[172:173], 2, v[136:137]
	global_store_dwordx4 v[136:137], v[132:135], off nt
	global_store_dwordx4 v[136:137], v[128:131], off offset:16 nt

; #define EPI_GET(dst, ai, bj, m, s) do { _Pragma("unroll") for (int e_ = 0; e_ < 4; ++e_) { (dst)[e_] = acc[ai][bj][m][0][e_] * (s); (dst)[4 + e_] = acc[ai][bj][m][1][e_] * (s); } } while (0)
;     __device__ __forceinline__ void operator()(const f32x4 (&acc)[2][2][4][2], const Unit& u, int wr, int wc, int fr, int fq) const {
;     ...
;             for (int m = 0; m < 4; ++m) {
;                 const int r = EPI_ROWS(ai, m); const float rs = rsa[m];
;                 float lo[8], hi[8]; EPI_GET(lo, ai, 0, m, rs); EPI_GET(hi, ai, 1, m, rs);
;                 const int rl = samp ? r - MP : r; const int pos = samp ? PAST + (rl & 7) : (rl & (SEQ - 1));
;                 if (pn < 2) {
;                     store8_bf16(cbb + (size_t)r * 512 + pn * 256 + c8, lo); store8_bf16(cbb + (size_t)r * 512 + pn * 256 + 128 + c8, hi);
;     ...
;                     } else if (wc == 1 && fq == 0) {
;                         store8_f32(iwf + (size_t)r * 8, lo);
;                     }
.LBB0_361:
	s_andn2_b64 vcc, exec, s[8:9]
	s_ashr_i32 s57, s56, 31
	s_cbranch_vccnz .LBB0_363
	v_ashrrev_i32_e32 v183, 31, v182
	v_lshlrev_b64 v[128:129], 10, v[182:183]
	v_lshl_add_u64 v[128:129], s[22:23], 0, v[128:129]
	v_lshl_add_u64 v[128:129], s[56:57], 1, v[128:129]
	v_lshl_add_u64 v[128:129], v[156:157], 1, v[128:129]
	v_cvt_pk_bf16_f32 v124, v124, v125
	v_cvt_pk_bf16_f32 v125, v126, v127
	v_cvt_pk_bf16_f32 v126, v120, v121
	v_cvt_pk_bf16_f32 v127, v122, v123
	global_store_dwordx4 v[128:129], v[124:127], off nt
	v_cvt_pk_bf16_f32 v116, v116, v117
	v_cvt_pk_bf16_f32 v117, v118, v119
	v_cvt_pk_bf16_f32 v118, v112, v113
	v_cvt_pk_bf16_f32 v119, v114, v115
	global_store_dwordx4 v[128:129], v[116:119], off offset:256 nt
.LBB0_363:
	v_cndmask_b32_e64 v112, 0, 1, s[12:13]
	v_cmp_ne_u32_e64 s[10:11], 1, v112
	v_cndmask_b32_e64 v112, 0, 1, s[34:35]
	v_pk_mul_f32 v[108:109], v[108:109], v[186:187] op_sel_hi:[1,0]
	v_pk_mul_f32 v[100:101], v[100:101], v[186:187] op_sel_hi:[1,0]
	v_pk_mul_f32 v[104:105], v[104:105], v[186:187] op_sel_hi:[1,0]
	v_pk_mul_f32 v[96:97], v[96:97], v[186:187] op_sel_hi:[1,0]
	v_pk_mul_f32 v[110:111], v[110:111], v[186:187] op_sel_hi:[1,0]
	v_pk_mul_f32 v[102:103], v[102:103], v[186:187] op_sel_hi:[1,0]
	v_pk_mul_f32 v[106:107], v[106:107], v[186:187] op_sel_hi:[1,0]
	v_pk_mul_f32 v[98:99], v[98:99], v[186:187] op_sel_hi:[1,0]
	v_or_b32_e32 v128, 16, v182
	s_mov_b64 s[26:27], -1
	s_andn2_b64 vcc, exec, s[12:13]
	v_cmp_ne_u32_e64 s[8:9], 1, v112
	s_cbranch_vccnz .LBB0_394
	v_add_u32_e32 v138, 0xffffc010, v182
	v_cndmask_b32_e64 v130, v128, v138, s[6:7]
	v_and_b32_e32 v139, 7, v130
	s_and_b64 vcc, exec, s[8:9]
	s_mov_b64 s[12:13], -1
	s_cbranch_vccnz .LBB0_389
	v_or_b32_e32 v112, 0x800, v139
	v_and_b32_e32 v113, 0x1fdf, v128
	v_cndmask_b32_e64 v132, v113, v112, s[6:7]
	s_andn2_b64 vcc, exec, s[20:21]
	s_cbranch_vccnz .LBB0_376
	s_andn2_b64 vcc, exec, s[16:17]
	s_cbranch_vccnz .LBB0_373
	v_readlane_b32 s12, v249, 14
	v_readlane_b32 s13, v249, 15
	s_andn2_b64 vcc, exec, s[12:13]
	s_cbranch_vccnz .LBB0_638
	s_mov_b64 s[12:13], exec
	v_readlane_b32 s26, v249, 16
	v_readlane_b32 s27, v249, 17
	s_and_b64 s[26:27], s[12:13], s[26:27]
	s_mov_b64 exec, s[26:27]
	s_cbranch_execz .LBB0_370
	v_ashrrev_i32_e32 v129, 31, v128
	v_readlane_b32 s26, v249, 12
	v_lshlrev_b64 v[112:113], 5, v[128:129]
	v_readlane_b32 s27, v249, 13
	s_nop 1
	v_lshl_add_u64 v[112:113], s[26:27], 0, v[112:113]
	global_store_dwordx4 v[112:113], v[108:111], off nt
	global_store_dwordx4 v[112:113], v[104:107], off offset:16 nt

;     __device__ __forceinline__ void operator()(const f32x4 (&acc)[2][2][4][2], const Unit& u, int wr, int wc, int fr, int fq) const {
;     ...
;                     if (wc == 0) {
;                         const int d0 = 8 * fq; float cs[8], sn[8]; load8_f32(cosT + (size_t)pos * 32 + d0, cs); load8_f32(sinT + (size_t)pos * 32 + d0, sn);
;                         float ol[8], oh[8];
; #pragma unroll
;                         for (int e = 0; e < 8; ++e) { ol[e] = lo[e] * cs[e] - hi[e] * sn[e]; oh[e] = hi[e] * cs[e] + lo[e] * sn[e]; }
;                         store8_bf16(kib + (size_t)r * 64 + d0, ol); store8_bf16(kib + (size_t)r * 64 + 32 + d0, oh);
;                         float* io = out + (samp ? OFF_IK_S : OFF_IK_P) + (size_t)rl * 64 + d0; store8_f32(io, ol); store8_f32(io + 32, oh);
.LBB0_371:
	v_lshlrev_b32_e32 v152, 7, v132
	v_lshl_add_u64 v[112:113], v[158:159], 0, v[152:153]
	v_lshl_add_u64 v[120:121], v[160:161], 0, v[152:153]
	global_load_dwordx4 v[124:127], v[112:113], off offset:16
	s_nop 0
	global_load_dwordx4 v[112:115], v[112:113], off
	s_nop 0
	global_load_dwordx4 v[116:119], v[120:121], off offset:16
	s_nop 0
	global_load_dwordx4 v[120:123], v[120:121], off
	v_mov_b32_e32 v134, v108
	v_mov_b32_e32 v135, v100
	v_mov_b32_e32 v140, v100
	v_mov_b32_e32 v141, v108
	v_ashrrev_i32_e32 v129, 31, v128
	v_readlane_b32 s60, v250, 0
	s_lshl_b32 s12, s69, 2
	v_readlane_b32 s62, v250, 2
	v_readlane_b32 s63, v250, 3
	s_add_u32 s12, s62, s12
	v_ashrrev_i32_e32 v131, 31, v130
	s_addc_u32 s13, s63, 0
	v_readlane_b32 s61, v250, 1
	v_readlane_b32 s64, v250, 4
	v_readlane_b32 s65, v250, 5
	v_readlane_b32 s66, v250, 6
	v_readlane_b32 s67, v250, 7
	s_waitcnt vmcnt(2)
	v_mov_b32_e32 v136, v112
	s_waitcnt vmcnt(0)
	v_mov_b32_e32 v137, v120
	v_pk_mul_f32 v[134:135], v[134:135], v[136:137]
	v_pk_mul_f32 v[136:137], v[140:141], v[136:137]
	v_mov_b32_e32 v140, v109
	v_mov_b32_e32 v141, v101
	v_mov_b32_e32 v120, v113
	v_pk_mul_f32 v[112:113], v[140:141], v[120:121]
	v_mov_b32_e32 v140, v134
	v_mov_b32_e32 v141, v112
	v_mov_b32_e32 v112, v135
	v_mov_b32_e32 v134, v101
	v_mov_b32_e32 v135, v109
	v_pk_mul_f32 v[120:121], v[134:135], v[120:121]
	v_mov_b32_e32 v134, v136
	v_mov_b32_e32 v135, v120
	v_mov_b32_e32 v120, v137
	v_pk_add_f32 v[112:113], v[140:141], v[112:113] neg_lo:[0,1] neg_hi:[0,1]
	v_pk_add_f32 v[120:121], v[134:135], v[120:121]
	v_mov_b32_e32 v134, v110
	v_mov_b32_e32 v135, v102
	v_mov_b32_e32 v136, v114
	v_mov_b32_e32 v137, v122
	v_mov_b32_e32 v140, v102
	v_mov_b32_e32 v141, v110
	v_pk_mul_f32 v[134:135], v[134:135], v[136:137]
	v_pk_mul_f32 v[136:137], v[140:141], v[136:137]
	v_mov_b32_e32 v140, v111
	v_mov_b32_e32 v141, v103
	v_mov_b32_e32 v122, v115
	v_pk_mul_f32 v[114:115], v[140:141], v[122:123]
	v_mov_b32_e32 v140, v134
	v_mov_b32_e32 v141, v114
	v_mov_b32_e32 v114, v135
	v_mov_b32_e32 v134, v103
	v_mov_b32_e32 v135, v111
	v_pk_mul_f32 v[122:123], v[134:135], v[122:123]
	v_mov_b32_e32 v134, v136
	v_mov_b32_e32 v135, v122
	v_mov_b32_e32 v122, v137
	v_pk_add_f32 v[114:115], v[140:141], v[114:115] neg_lo:[0,1] neg_hi:[0,1]
	v_pk_add_f32 v[122:123], v[134:135], v[122:123]
	v_mov_b32_e32 v134, v104
	v_mov_b32_e32 v135, v96
	v_mov_b32_e32 v136, v124
	v_mov_b32_e32 v137, v116
	v_mov_b32_e32 v140, v96
	v_mov_b32_e32 v141, v104
	v_pk_mul_f32 v[134:135], v[134:135], v[136:137]
	v_pk_mul_f32 v[136:137], v[140:141], v[136:137]
	v_mov_b32_e32 v140, v105
	v_mov_b32_e32 v141, v97
	v_mov_b32_e32 v116, v125
	v_pk_mul_f32 v[124:125], v[140:141], v[116:117]
	v_mov_b32_e32 v140, v134
	v_mov_b32_e32 v141, v124
	v_mov_b32_e32 v124, v135
	v_mov_b32_e32 v134, v97
	v_mov_b32_e32 v135, v105
	v_pk_mul_f32 v[116:117], v[134:135], v[116:117]
	v_mov_b32_e32 v134, v136
	v_mov_b32_e32 v135, v116
	v_mov_b32_e32 v116, v137
	v_pk_add_f32 v[124:125], v[140:141], v[124:125] neg_lo:[0,1] neg_hi:[0,1]
	v_pk_add_f32 v[116:117], v[134:135], v[116:117]
	v_mov_b32_e32 v134, v106
	v_mov_b32_e32 v135, v98
	v_mov_b32_e32 v136, v126
	v_mov_b32_e32 v137, v118
	v_mov_b32_e32 v140, v98
	v_mov_b32_e32 v141, v106
	v_pk_mul_f32 v[134:135], v[134:135], v[136:137]
	v_pk_mul_f32 v[136:137], v[140:141], v[136:137]
	v_mov_b32_e32 v140, v107
	v_mov_b32_e32 v141, v99
	v_mov_b32_e32 v118, v127
	v_pk_mul_f32 v[126:127], v[140:141], v[118:119]
	v_mov_b32_e32 v140, v134
	v_mov_b32_e32 v141, v126
	v_mov_b32_e32 v126, v135
	v_mov_b32_e32 v134, v99
	v_mov_b32_e32 v135, v107
	v_pk_mul_f32 v[118:119], v[134:135], v[118:119]
	v_mov_b32_e32 v134, v136
	v_mov_b32_e32 v135, v118
	v_mov_b32_e32 v118, v137
	v_pk_add_f32 v[118:119], v[134:135], v[118:119]
	v_lshlrev_b64 v[134:135], 7, v[128:129]
	v_pk_add_f32 v[126:127], v[140:141], v[126:127] neg_lo:[0,1] neg_hi:[0,1]
	v_lshl_add_u64 v[140:141], v[162:163], 0, v[134:135]
	v_cvt_pk_bf16_f32 v134, v112, v113
	v_cvt_pk_bf16_f32 v135, v114, v115
	v_cvt_pk_bf16_f32 v136, v124, v125
	v_cvt_pk_bf16_f32 v137, v126, v127
	global_store_dwordx4 v[140:141], v[134:137], off nt
	s_nop 1
	v_cvt_pk_bf16_f32 v134, v120, v121
	v_cvt_pk_bf16_f32 v135, v122, v123
	v_cvt_pk_bf16_f32 v136, v116, v117
	v_cvt_pk_bf16_f32 v137, v118, v119
	global_store_dwordx4 v[140:141], v[134:137], off offset:64 nt
	s_nop 1
	v_lshlrev_b64 v[134:135], 8, v[130:131]
	v_lshl_add_u64 v[134:135], s[12:13], 0, v[134:135]
	v_lshl_add_u64 v[134:135], v[154:155], 2, v[134:135]
	global_store_dwordx4 v[134:135], v[112:115], off nt
	global_store_dwordx4 v[134:135], v[124:127], off offset:16 nt
	global_store_dwordx4 v[134:135], v[120:123], off offset:128 nt
	global_store_dwordx4 v[134:135], v[116:119], off offset:144 nt

;     __device__ __forceinline__ void operator()(const f32x4 (&acc)[2][2][4][2], const Unit& u, int wr, int wc, int fr, int fq) const {
;     ...
;                 } else if (pn < 12) {
;                     const int c = 256 * (pn - 10) + c8;
;                     store8_bf16(vb + (size_t)r * 512 + c, lo); store8_bf16(vb + (size_t)r * 512 + c + 128, hi);
;                     float* vo = out + (samp ? OFF_V_S : OFF_V_P) + (size_t)rl * 512 + c; store8_f32(vo, lo); store8_f32(vo + 128, hi);
.LBB0_373:
	s_andn2_b64 vcc, exec, s[12:13]
	s_cbranch_vccnz .LBB0_375
	v_ashrrev_i32_e32 v129, 31, v128
	v_readlane_b32 s12, v249, 8
	v_lshlrev_b64 v[112:113], 10, v[128:129]
	v_readlane_b32 s13, v249, 9
	v_readlane_b32 s60, v250, 0
	v_readlane_b32 s62, v250, 2
	v_lshl_add_u64 v[112:113], s[12:13], 0, v[112:113]
	v_lshl_add_u64 v[116:117], v[176:177], 1, v[112:113]
	v_cvt_pk_bf16_f32 v112, v108, v109
	v_cvt_pk_bf16_f32 v113, v110, v111
	s_lshl_b32 s12, s55, 2
	v_cvt_pk_bf16_f32 v114, v104, v105
	v_cvt_pk_bf16_f32 v115, v106, v107
	global_store_dwordx4 v[116:117], v[112:115], off nt
	v_readlane_b32 s63, v250, 3
	s_add_u32 s12, s62, s12
	v_cvt_pk_bf16_f32 v112, v100, v101
	v_cvt_pk_bf16_f32 v113, v102, v103
	v_ashrrev_i32_e32 v131, 31, v130
	v_cvt_pk_bf16_f32 v114, v96, v97
	v_cvt_pk_bf16_f32 v115, v98, v99
	global_store_dwordx4 v[116:117], v[112:115], off offset:256 nt
	s_addc_u32 s13, s63, 0
	v_readlane_b32 s61, v250, 1
	v_lshlrev_b64 v[112:113], 11, v[130:131]
	v_lshl_add_u64 v[112:113], s[12:13], 0, v[112:113]
	v_lshl_add_u64 v[112:113], v[176:177], 2, v[112:113]
	v_readlane_b32 s64, v250, 4
	v_readlane_b32 s65, v250, 5
	v_readlane_b32 s66, v250, 6
	v_readlane_b32 s67, v250, 7
	global_store_dwordx4 v[112:113], v[108:111], off nt
	global_store_dwordx4 v[112:113], v[104:107], off offset:16 nt
	global_store_dwordx4 v[112:113], v[100:103], off offset:512 nt
	global_store_dwordx4 v[112:113], v[96:99], off offset:528 nt

;     __device__ __forceinline__ void operator()(const f32x4 (&acc)[2][2][4][2], const Unit& u, int wr, int wc, int fr, int fq) const {
;     ...
;                     float cs[8], sn[8]; load8_f32(cosT + (size_t)pos * 32 + d0, cs); load8_f32(sinT + (size_t)pos * 32 + d0, sn);
;                     float ol[8], oh[8];
; #pragma unroll
;                     for (int e = 0; e < 8; ++e) { ol[e] = lo[e] * cs[e] - hi[e] * sn[e]; oh[e] = hi[e] * cs[e] + lo[e] * sn[e]; }
;                     const size_t o512 = (size_t)r * 512 + head * 64 + d0;
;                     if (pn < 8) {
; #pragma unroll
;                         for (int e = 0; e < 8; ++e) { ol[e] *= 0.18033688011112042f; oh[e] *= 0.18033688011112042f; }
;                         store8_bf16(qb + o512, ol); store8_bf16(qb + o512 + 32, oh);
;                     } else if (pn < 10) {
;                         store8_bf16(kb + o512, ol); store8_bf16(kb + o512 + 32, oh);
;                         float* ko = out + (samp ? OFF_K_S : OFF_K_P) + (size_t)rl * 512 + head * 64 + d0; store8_f32(ko, ol); store8_f32(ko + 32, oh);
;                     } else {
;                         store8_bf16(qib + o512, ol); store8_bf16(qib + o512 + 32, oh);
;                     }
.LBB0_380:
	v_lshlrev_b32_e32 v152, 7, v132
	v_lshl_add_u64 v[132:133], v[160:161], 0, v[152:153]
	global_load_dwordx4 v[124:127], v[132:133], off
	global_load_dwordx4 v[140:143], v[132:133], off offset:16
	v_lshl_add_u64 v[132:133], v[158:159], 0, v[152:153]
	global_load_dwordx4 v[188:191], v[132:133], off
	global_load_dwordx4 v[202:205], v[132:133], off offset:16
	v_ashrrev_i32_e32 v129, 31, v128
	v_lshlrev_b64 v[132:133], 9, v[128:129]
	v_lshl_add_u64 v[132:133], v[132:133], 0, v[174:175]
	s_andn2_b64 vcc, exec, s[94:95]
	s_mov_b64 s[12:13], -1
	s_waitcnt vmcnt(3)
	v_pk_mul_f32 v[192:193], v[118:119], v[124:125]
	v_pk_mul_f32 v[206:207], v[120:121], v[124:125]
	v_pk_mul_f32 v[208:209], v[116:117], v[126:127]
	v_pk_mul_f32 v[210:211], v[122:123], v[126:127]
	s_waitcnt vmcnt(2)
	v_pk_mul_f32 v[212:213], v[112:113], v[140:141]
	v_pk_mul_f32 v[140:141], v[136:137], v[140:141]
	v_pk_mul_f32 v[214:215], v[114:115], v[142:143]
	v_pk_mul_f32 v[142:143], v[134:135], v[142:143]
	s_waitcnt vmcnt(1)
	v_pk_fma_f32 v[124:125], v[120:121], v[188:189], v[192:193] neg_lo:[0,0,1] neg_hi:[0,0,1]
	v_pk_fma_f32 v[120:121], v[118:119], v[188:189], v[206:207]
	v_pk_fma_f32 v[126:127], v[122:123], v[190:191], v[208:209] neg_lo:[0,0,1] neg_hi:[0,0,1]
	v_pk_fma_f32 v[122:123], v[116:117], v[190:191], v[210:211]
	s_waitcnt vmcnt(0)
	v_pk_fma_f32 v[116:117], v[136:137], v[202:203], v[212:213] neg_lo:[0,0,1] neg_hi:[0,0,1]
	v_pk_fma_f32 v[112:113], v[112:113], v[202:203], v[140:141]
	v_pk_fma_f32 v[118:119], v[134:135], v[204:205], v[214:215] neg_lo:[0,0,1] neg_hi:[0,0,1]
	v_pk_fma_f32 v[114:115], v[114:115], v[204:205], v[142:143]
	s_cbranch_vccnz .LBB0_386
	s_andn2_b64 vcc, exec, s[2:3]
	s_cbranch_vccnz .LBB0_383
	v_readlane_b32 s12, v249, 10
	v_readlane_b32 s13, v249, 11
	v_cvt_pk_bf16_f32 v134, v124, v125
	v_cvt_pk_bf16_f32 v135, v126, v127
	v_cvt_pk_bf16_f32 v136, v116, v117
	v_cvt_pk_bf16_f32 v137, v118, v119
	s_nop 1
	v_lshl_add_u64 v[140:141], v[132:133], 1, s[12:13]
	s_mov_b64 s[12:13], 0
	global_store_dwordx4 v[140:141], v[134:137], off nt
	s_nop 1
	v_cvt_pk_bf16_f32 v134, v120, v121
	v_cvt_pk_bf16_f32 v135, v122, v123
	v_cvt_pk_bf16_f32 v136, v112, v113
	v_cvt_pk_bf16_f32 v137, v114, v115
	global_store_dwordx4 v[140:141], v[134:137], off offset:64 nt
.LBB0_383:
	s_andn2_b64 vcc, exec, s[12:13]
	s_cbranch_vccnz .LBB0_385
	v_readlane_b32 s12, v249, 6
	v_readlane_b32 s13, v249, 7
	v_readlane_b32 s60, v250, 0
	v_readlane_b32 s62, v250, 2
	v_lshl_add_u64 v[140:141], v[132:133], 1, s[12:13]
	s_lshl_b32 s12, s53, 2
	v_readlane_b32 s63, v250, 3
	s_add_u32 s12, s62, s12
	v_ashrrev_i32_e32 v131, 31, v130
	s_addc_u32 s13, s63, 0
	v_lshlrev_b64 v[130:131], 11, v[130:131]
	v_lshl_add_u64 v[130:131], s[12:13], 0, v[130:131]
	s_lshl_b32 s12, s18, 2
	s_mov_b32 s13, s19
	v_lshl_add_u64 v[130:131], v[130:131], 0, s[12:13]
	v_cvt_pk_bf16_f32 v134, v124, v125
	v_cvt_pk_bf16_f32 v135, v126, v127
	v_cvt_pk_bf16_f32 v136, v116, v117
	v_cvt_pk_bf16_f32 v137, v118, v119
	v_lshl_add_u64 v[130:131], v[154:155], 2, v[130:131]
	global_store_dwordx4 v[140:141], v[134:137], off nt
	v_readlane_b32 s61, v250, 1
	v_readlane_b32 s64, v250, 4
	v_cvt_pk_bf16_f32 v134, v120, v121
	v_cvt_pk_bf16_f32 v135, v122, v123
	v_cvt_pk_bf16_f32 v136, v112, v113
	v_cvt_pk_bf16_f32 v137, v114, v115
	global_store_dwordx4 v[140:141], v[134:137], off offset:64 nt
	v_readlane_b32 s65, v250, 5
	v_readlane_b32 s66, v250, 6
	v_readlane_b32 s67, v250, 7
	global_store_dwordx4 v[130:131], v[124:127], off nt
	global_store_dwordx4 v[130:131], v[116:119], off offset:16 nt
	global_store_dwordx4 v[130:131], v[120:123], off offset:128 nt
	global_store_dwordx4 v[130:131], v[112:115], off offset:144 nt

;     __device__ __forceinline__ void operator()(const f32x4 (&acc)[2][2][4][2], const Unit& u, int wr, int wc, int fr, int fq) const {
;     ...
;                     if (pn < 8) {
; #pragma unroll
;                         for (int e = 0; e < 8; ++e) { ol[e] *= 0.18033688011112042f; oh[e] *= 0.18033688011112042f; }
;                         store8_bf16(qb + o512, ol); store8_bf16(qb + o512 + 32, oh);
.LBB0_386:
	s_andn2_b64 vcc, exec, s[12:13]
	s_cbranch_vccnz .LBB0_388
	v_readlane_b32 s12, v249, 4
	v_readlane_b32 s13, v249, 5
	v_mul_f32_e32 v124, 0x3e38aa3b, v124
	v_mul_f32_e32 v125, 0x3e38aa3b, v125
	v_mul_f32_e32 v126, 0x3e38aa3b, v126
	v_mul_f32_e32 v127, 0x3e38aa3b, v127
	v_mul_f32_e32 v129, 0x3e38aa3b, v116
	v_mul_f32_e32 v130, 0x3e38aa3b, v112
	v_mul_f32_e32 v131, 0x3e38aa3b, v117
	v_mul_f32_e32 v134, 0x3e38aa3b, v113
	v_mul_f32_e32 v118, 0x3e38aa3b, v118
	v_mul_f32_e32 v135, 0x3e38aa3b, v114
	v_mul_f32_e32 v119, 0x3e38aa3b, v119
	v_mul_f32_e32 v136, 0x3e38aa3b, v115
	v_lshl_add_u64 v[116:117], v[132:133], 1, s[12:13]
	v_cvt_pk_bf16_f32 v112, v124, v125
	v_cvt_pk_bf16_f32 v113, v126, v127
	v_cvt_pk_bf16_f32 v114, v129, v131
	v_cvt_pk_bf16_f32 v115, v118, v119
	v_mul_f32_e32 v120, 0x3e38aa3b, v120
	v_mul_f32_e32 v121, 0x3e38aa3b, v121
	v_mul_f32_e32 v122, 0x3e38aa3b, v122
	v_mul_f32_e32 v123, 0x3e38aa3b, v123
	global_store_dwordx4 v[116:117], v[112:115], off nt
	s_nop 1
	v_cvt_pk_bf16_f32 v112, v120, v121
	v_cvt_pk_bf16_f32 v113, v122, v123
	v_cvt_pk_bf16_f32 v114, v130, v134
	v_cvt_pk_bf16_f32 v115, v135, v136
	global_store_dwordx4 v[116:117], v[112:115], off offset:64 nt

;     __device__ __forceinline__ void operator()(const f32x4 (&acc)[2][2][4][2], const Unit& u, int wr, int wc, int fr, int fq) const {
;     ...
;                 } else if (pn < 6) {
;                     const int ch = 128 * (pn - 2) + c8; float uu[8];
; #pragma unroll
;                     for (int e = 0; e < 8; ++e) uu[e] = lo[e] * hi[e];
;                     store8_bf16(ub + (size_t)r * 512 + ch, uu);
;                     if (!samp) { const int t = rl & (SEQ - 1); if (t >= SEQ - 2) store8_f32(out + OFF_CM_P + (size_t)((rl >> 13) * 2 + (t - (SEQ - 2))) * 512 + ch, uu); }
;                     else { const int tt = rl & 7; if (tt >= 6) store8_f32(out + OFF_CM_S + (size_t)((rl >> 3) * 2 + (tt - 6)) * 512 + ch, uu); }
.LBB0_389:
	s_andn2_b64 vcc, exec, s[12:13]
	s_cbranch_vccnz .LBB0_393
	v_ashrrev_i32_e32 v129, 31, v128
	v_lshlrev_b64 v[120:121], 10, v[128:129]
	v_lshl_add_u64 v[120:121], s[88:89], 0, v[120:121]
	v_cmp_lt_u32_e32 vcc, 5, v139
	v_pk_mul_f32 v[116:117], v[108:109], v[100:101]
	v_pk_mul_f32 v[118:119], v[110:111], v[102:103]
	v_pk_mul_f32 v[112:113], v[104:105], v[96:97]
	v_pk_mul_f32 v[114:115], v[106:107], v[98:99]
	v_lshl_add_u64 v[124:125], v[172:173], 1, v[120:121]
	s_and_b64 s[26:27], s[6:7], vcc
	v_cvt_pk_bf16_f32 v120, v116, v117
	v_cvt_pk_bf16_f32 v121, v118, v119
	v_cvt_pk_bf16_f32 v122, v112, v113
	v_cvt_pk_bf16_f32 v123, v114, v115
	global_store_dwordx4 v[124:125], v[120:123], off nt
	s_and_saveexec_b64 s[12:13], s[26:27]
	s_cbranch_execz .LBB0_392
	v_ashrrev_i32_e32 v120, 2, v138
	v_and_b32_e32 v120, -10, v120
	v_add3_u32 v120, v139, v120, -6
	v_ashrrev_i32_e32 v121, 31, v120
	v_readlane_b32 s26, v249, 18
	v_lshlrev_b64 v[120:121], 11, v[120:121]
	v_readlane_b32 s27, v249, 19
	s_nop 1
	v_lshl_add_u64 v[120:121], s[26:27], 0, v[120:121]
	v_lshl_add_u64 v[120:121], v[172:173], 2, v[120:121]
	global_store_dwordx4 v[120:121], v[116:119], off nt
	global_store_dwordx4 v[120:121], v[112:115], off offset:16 nt

; #define EPI_GET(dst, ai, bj, m, s) do { _Pragma("unroll") for (int e_ = 0; e_ < 4; ++e_) { (dst)[e_] = acc[ai][bj][m][0][e_] * (s); (dst)[4 + e_] = acc[ai][bj][m][1][e_] * (s); } } while (0)
;     __device__ __forceinline__ void operator()(const f32x4 (&acc)[2][2][4][2], const Unit& u, int wr, int wc, int fr, int fq) const {
;     ...
;             for (int m = 0; m < 4; ++m) {
;                 const int r = EPI_ROWS(ai, m); const float rs = rsa[m];
;                 float lo[8], hi[8]; EPI_GET(lo, ai, 0, m, rs); EPI_GET(hi, ai, 1, m, rs);
;                 const int rl = samp ? r - MP : r; const int pos = samp ? PAST + (rl & 7) : (rl & (SEQ - 1));
;                 if (pn < 2) {
;                     store8_bf16(cbb + (size_t)r * 512 + pn * 256 + c8, lo); store8_bf16(cbb + (size_t)r * 512 + pn * 256 + 128 + c8, hi);
;     ...
;                     } else if (wc == 1 && fq == 0) {
;                         store8_f32(iwf + (size_t)r * 8, lo);
;                     }
.LBB0_394:
	s_andn2_b64 vcc, exec, s[26:27]
	s_cbranch_vccnz .LBB0_396
	v_ashrrev_i32_e32 v129, 31, v128
	v_lshlrev_b64 v[112:113], 10, v[128:129]
	v_lshl_add_u64 v[112:113], s[22:23], 0, v[112:113]
	v_lshl_add_u64 v[112:113], s[56:57], 1, v[112:113]
	v_lshl_add_u64 v[112:113], v[156:157], 1, v[112:113]
	v_cvt_pk_bf16_f32 v108, v108, v109
	v_cvt_pk_bf16_f32 v109, v110, v111
	v_cvt_pk_bf16_f32 v110, v104, v105
	v_cvt_pk_bf16_f32 v111, v106, v107
	global_store_dwordx4 v[112:113], v[108:111], off nt
	v_cvt_pk_bf16_f32 v100, v100, v101
	v_cvt_pk_bf16_f32 v101, v102, v103
	v_cvt_pk_bf16_f32 v102, v96, v97
	v_cvt_pk_bf16_f32 v103, v98, v99
	global_store_dwordx4 v[112:113], v[100:103], off offset:256 nt
.LBB0_396:
	v_pk_mul_f32 v[92:93], v[92:93], v[184:185] op_sel_hi:[1,0]
	v_pk_mul_f32 v[84:85], v[84:85], v[184:185] op_sel_hi:[1,0]
	v_pk_mul_f32 v[88:89], v[88:89], v[184:185] op_sel_hi:[1,0]
	v_pk_mul_f32 v[80:81], v[80:81], v[184:185] op_sel_hi:[1,0]
	v_pk_mul_f32 v[94:95], v[94:95], v[184:185] op_sel_hi:[1,0]
	v_pk_mul_f32 v[86:87], v[86:87], v[184:185] op_sel_hi:[1,0]
	v_pk_mul_f32 v[90:91], v[90:91], v[184:185] op_sel_hi:[1,0]
	v_pk_mul_f32 v[82:83], v[82:83], v[184:185] op_sel_hi:[1,0]
	v_or_b32_e32 v112, 32, v182
	s_and_b64 vcc, exec, s[10:11]
	s_mov_b64 s[12:13], -1
	s_cbranch_vccnz .LBB0_427
	v_add_u32_e32 v122, 0xffffc020, v182
	v_cndmask_b32_e64 v114, v112, v122, s[6:7]
	v_and_b32_e32 v123, 7, v114
	s_and_b64 vcc, exec, s[8:9]
	s_cbranch_vccnz .LBB0_422
	v_or_b32_e32 v96, 0x800, v123
	v_and_b32_e32 v97, 0x1fef, v112
	v_cndmask_b32_e64 v116, v97, v96, s[6:7]
	s_andn2_b64 vcc, exec, s[20:21]
	s_cbranch_vccnz .LBB0_409
	s_andn2_b64 vcc, exec, s[16:17]
	s_cbranch_vccnz .LBB0_406
	v_readlane_b32 s12, v249, 14
	v_readlane_b32 s13, v249, 15
	s_andn2_b64 vcc, exec, s[12:13]
	s_cbranch_vccnz .LBB0_639
	s_mov_b64 s[12:13], exec
	v_readlane_b32 s26, v249, 16
	v_readlane_b32 s27, v249, 17
	s_and_b64 s[26:27], s[12:13], s[26:27]
	s_mov_b64 exec, s[26:27]
	s_cbranch_execz .LBB0_403
	v_ashrrev_i32_e32 v113, 31, v112
	v_readlane_b32 s26, v249, 12
	v_lshlrev_b64 v[96:97], 5, v[112:113]
	v_readlane_b32 s27, v249, 13
	s_nop 1
	v_lshl_add_u64 v[96:97], s[26:27], 0, v[96:97]
	global_store_dwordx4 v[96:97], v[92:95], off nt
	global_store_dwordx4 v[96:97], v[88:91], off offset:16 nt

;     __device__ __forceinline__ void operator()(const f32x4 (&acc)[2][2][4][2], const Unit& u, int wr, int wc, int fr, int fq) const {
;     ...
;                     if (wc == 0) {
;                         const int d0 = 8 * fq; float cs[8], sn[8]; load8_f32(cosT + (size_t)pos * 32 + d0, cs); load8_f32(sinT + (size_t)pos * 32 + d0, sn);
;                         float ol[8], oh[8];
; #pragma unroll
;                         for (int e = 0; e < 8; ++e) { ol[e] = lo[e] * cs[e] - hi[e] * sn[e]; oh[e] = hi[e] * cs[e] + lo[e] * sn[e]; }
;                         store8_bf16(kib + (size_t)r * 64 + d0, ol); store8_bf16(kib + (size_t)r * 64 + 32 + d0, oh);
;                         float* io = out + (samp ? OFF_IK_S : OFF_IK_P) + (size_t)rl * 64 + d0; store8_f32(io, ol); store8_f32(io + 32, oh);
.LBB0_404:
	v_lshlrev_b32_e32 v152, 7, v116
	v_lshl_add_u64 v[96:97], v[158:159], 0, v[152:153]
	v_lshl_add_u64 v[104:105], v[160:161], 0, v[152:153]
	global_load_dwordx4 v[108:111], v[96:97], off offset:16
	s_nop 0
	global_load_dwordx4 v[96:99], v[96:97], off
	s_nop 0
	global_load_dwordx4 v[100:103], v[104:105], off offset:16
	s_nop 0
	global_load_dwordx4 v[104:107], v[104:105], off
	v_mov_b32_e32 v118, v92
	v_mov_b32_e32 v119, v84
	v_mov_b32_e32 v124, v84
	v_mov_b32_e32 v125, v92
	v_ashrrev_i32_e32 v113, 31, v112
	v_readlane_b32 s60, v250, 0
	s_lshl_b32 s12, s69, 2
	v_readlane_b32 s62, v250, 2
	v_readlane_b32 s63, v250, 3
	s_add_u32 s12, s62, s12
	v_ashrrev_i32_e32 v115, 31, v114
	s_addc_u32 s13, s63, 0
	v_readlane_b32 s61, v250, 1
	v_readlane_b32 s64, v250, 4
	v_readlane_b32 s65, v250, 5
	v_readlane_b32 s66, v250, 6
	v_readlane_b32 s67, v250, 7
	s_waitcnt vmcnt(2)
	v_mov_b32_e32 v120, v96
	s_waitcnt vmcnt(0)
	v_mov_b32_e32 v121, v104
	v_pk_mul_f32 v[118:119], v[118:119], v[120:121]
	v_pk_mul_f32 v[120:121], v[124:125], v[120:121]
	v_mov_b32_e32 v124, v93
	v_mov_b32_e32 v125, v85
	v_mov_b32_e32 v104, v97
	v_pk_mul_f32 v[96:97], v[124:125], v[104:105]
	v_mov_b32_e32 v124, v118
	v_mov_b32_e32 v125, v96
	v_mov_b32_e32 v96, v119
	v_mov_b32_e32 v118, v85
	v_mov_b32_e32 v119, v93
	v_pk_mul_f32 v[104:105], v[118:119], v[104:105]
	v_mov_b32_e32 v118, v120
	v_mov_b32_e32 v119, v104
	v_mov_b32_e32 v104, v121
	v_pk_add_f32 v[96:97], v[124:125], v[96:97] neg_lo:[0,1] neg_hi:[0,1]
	v_pk_add_f32 v[104:105], v[118:119], v[104:105]
	v_mov_b32_e32 v118, v94
	v_mov_b32_e32 v119, v86
	v_mov_b32_e32 v120, v98
	v_mov_b32_e32 v121, v106
	v_mov_b32_e32 v124, v86
	v_mov_b32_e32 v125, v94
	v_pk_mul_f32 v[118:119], v[118:119], v[120:121]
	v_pk_mul_f32 v[120:121], v[124:125], v[120:121]
	v_mov_b32_e32 v124, v95
	v_mov_b32_e32 v125, v87
	v_mov_b32_e32 v106, v99
	v_pk_mul_f32 v[98:99], v[124:125], v[106:107]
	v_mov_b32_e32 v124, v118
	v_mov_b32_e32 v125, v98
	v_mov_b32_e32 v98, v119
	v_mov_b32_e32 v118, v87
	v_mov_b32_e32 v119, v95
	v_pk_mul_f32 v[106:107], v[118:119], v[106:107]
	v_mov_b32_e32 v118, v120
	v_mov_b32_e32 v119, v106
	v_mov_b32_e32 v106, v121
	v_pk_add_f32 v[98:99], v[124:125], v[98:99] neg_lo:[0,1] neg_hi:[0,1]
	v_pk_add_f32 v[106:107], v[118:119], v[106:107]
	v_mov_b32_e32 v118, v88
	v_mov_b32_e32 v119, v80
	v_mov_b32_e32 v120, v108
	v_mov_b32_e32 v121, v100
	v_mov_b32_e32 v124, v80
	v_mov_b32_e32 v125, v88
	v_pk_mul_f32 v[118:119], v[118:119], v[120:121]
	v_pk_mul_f32 v[120:121], v[124:125], v[120:121]
	v_mov_b32_e32 v124, v89
	v_mov_b32_e32 v125, v81
	v_mov_b32_e32 v100, v109
	v_pk_mul_f32 v[108:109], v[124:125], v[100:101]
	v_mov_b32_e32 v124, v118
	v_mov_b32_e32 v125, v108
	v_mov_b32_e32 v108, v119
	v_mov_b32_e32 v118, v81
	v_mov_b32_e32 v119, v89
	v_pk_mul_f32 v[100:101], v[118:119], v[100:101]
	v_mov_b32_e32 v118, v120
	v_mov_b32_e32 v119, v100
	v_mov_b32_e32 v100, v121
	v_pk_add_f32 v[108:109], v[124:125], v[108:109] neg_lo:[0,1] neg_hi:[0,1]
	v_pk_add_f32 v[100:101], v[118:119], v[100:101]
	v_mov_b32_e32 v118, v90
	v_mov_b32_e32 v119, v82
	v_mov_b32_e32 v120, v110
	v_mov_b32_e32 v121, v102
	v_mov_b32_e32 v124, v82
	v_mov_b32_e32 v125, v90
	v_pk_mul_f32 v[118:119], v[118:119], v[120:121]
	v_pk_mul_f32 v[120:121], v[124:125], v[120:121]
	v_mov_b32_e32 v124, v91
	v_mov_b32_e32 v125, v83
	v_mov_b32_e32 v102, v111
	v_pk_mul_f32 v[110:111], v[124:125], v[102:103]
	v_mov_b32_e32 v124, v118
	v_mov_b32_e32 v125, v110
	v_mov_b32_e32 v110, v119
	v_mov_b32_e32 v118, v83
	v_mov_b32_e32 v119, v91
	v_pk_mul_f32 v[102:103], v[118:119], v[102:103]
	v_mov_b32_e32 v118, v120
	v_mov_b32_e32 v119, v102
	v_mov_b32_e32 v102, v121
	v_pk_add_f32 v[102:103], v[118:119], v[102:103]
	v_lshlrev_b64 v[118:119], 7, v[112:113]
	v_pk_add_f32 v[110:111], v[124:125], v[110:111] neg_lo:[0,1] neg_hi:[0,1]
	v_lshl_add_u64 v[124:125], v[162:163], 0, v[118:119]
	v_cvt_pk_bf16_f32 v118, v96, v97
	v_cvt_pk_bf16_f32 v119, v98, v99
	v_cvt_pk_bf16_f32 v120, v108, v109
	v_cvt_pk_bf16_f32 v121, v110, v111
	global_store_dwordx4 v[124:125], v[118:121], off nt
	s_nop 1
	v_cvt_pk_bf16_f32 v118, v104, v105
	v_cvt_pk_bf16_f32 v119, v106, v107
	v_cvt_pk_bf16_f32 v120, v100, v101
	v_cvt_pk_bf16_f32 v121, v102, v103
	global_store_dwordx4 v[124:125], v[118:121], off offset:64 nt
	s_nop 1
	v_lshlrev_b64 v[118:119], 8, v[114:115]
	v_lshl_add_u64 v[118:119], s[12:13], 0, v[118:119]
	v_lshl_add_u64 v[118:119], v[154:155], 2, v[118:119]
	global_store_dwordx4 v[118:119], v[96:99], off nt
	global_store_dwordx4 v[118:119], v[108:111], off offset:16 nt
	global_store_dwordx4 v[118:119], v[104:107], off offset:128 nt
	global_store_dwordx4 v[118:119], v[100:103], off offset:144 nt

;     __device__ __forceinline__ void operator()(const f32x4 (&acc)[2][2][4][2], const Unit& u, int wr, int wc, int fr, int fq) const {
;     ...
;                 } else if (pn < 12) {
;                     const int c = 256 * (pn - 10) + c8;
;                     store8_bf16(vb + (size_t)r * 512 + c, lo); store8_bf16(vb + (size_t)r * 512 + c + 128, hi);
;                     float* vo = out + (samp ? OFF_V_S : OFF_V_P) + (size_t)rl * 512 + c; store8_f32(vo, lo); store8_f32(vo + 128, hi);
.LBB0_406:
	s_andn2_b64 vcc, exec, s[12:13]
	s_cbranch_vccnz .LBB0_408
	v_ashrrev_i32_e32 v113, 31, v112
	v_readlane_b32 s12, v249, 8
	v_lshlrev_b64 v[96:97], 10, v[112:113]
	v_readlane_b32 s13, v249, 9
	v_readlane_b32 s60, v250, 0
	v_readlane_b32 s62, v250, 2
	v_lshl_add_u64 v[96:97], s[12:13], 0, v[96:97]
	v_lshl_add_u64 v[100:101], v[176:177], 1, v[96:97]
	v_cvt_pk_bf16_f32 v96, v92, v93
	v_cvt_pk_bf16_f32 v97, v94, v95
	s_lshl_b32 s12, s55, 2
	v_cvt_pk_bf16_f32 v98, v88, v89
	v_cvt_pk_bf16_f32 v99, v90, v91
	global_store_dwordx4 v[100:101], v[96:99], off nt
	v_readlane_b32 s63, v250, 3
	s_add_u32 s12, s62, s12
	v_cvt_pk_bf16_f32 v96, v84, v85
	v_cvt_pk_bf16_f32 v97, v86, v87
	v_ashrrev_i32_e32 v115, 31, v114
	v_cvt_pk_bf16_f32 v98, v80, v81
	v_cvt_pk_bf16_f32 v99, v82, v83
	global_store_dwordx4 v[100:101], v[96:99], off offset:256 nt
	s_addc_u32 s13, s63, 0
	v_readlane_b32 s61, v250, 1
	v_lshlrev_b64 v[96:97], 11, v[114:115]
	v_lshl_add_u64 v[96:97], s[12:13], 0, v[96:97]
	v_lshl_add_u64 v[96:97], v[176:177], 2, v[96:97]
	v_readlane_b32 s64, v250, 4
	v_readlane_b32 s65, v250, 5
	v_readlane_b32 s66, v250, 6
	v_readlane_b32 s67, v250, 7
	global_store_dwordx4 v[96:97], v[92:95], off nt
	global_store_dwordx4 v[96:97], v[88:91], off offset:16 nt
	global_store_dwordx4 v[96:97], v[84:87], off offset:512 nt
	global_store_dwordx4 v[96:97], v[80:83], off offset:528 nt

;     __device__ __forceinline__ void operator()(const f32x4 (&acc)[2][2][4][2], const Unit& u, int wr, int wc, int fr, int fq) const {
;     ...
;                     float cs[8], sn[8]; load8_f32(cosT + (size_t)pos * 32 + d0, cs); load8_f32(sinT + (size_t)pos * 32 + d0, sn);
;                     float ol[8], oh[8];
; #pragma unroll
;                     for (int e = 0; e < 8; ++e) { ol[e] = lo[e] * cs[e] - hi[e] * sn[e]; oh[e] = hi[e] * cs[e] + lo[e] * sn[e]; }
;                     const size_t o512 = (size_t)r * 512 + head * 64 + d0;
;                     if (pn < 8) {
; #pragma unroll
;                         for (int e = 0; e < 8; ++e) { ol[e] *= 0.18033688011112042f; oh[e] *= 0.18033688011112042f; }
;                         store8_bf16(qb + o512, ol); store8_bf16(qb + o512 + 32, oh);
;                     } else if (pn < 10) {
;                         store8_bf16(kb + o512, ol); store8_bf16(kb + o512 + 32, oh);
;                         float* ko = out + (samp ? OFF_K_S : OFF_K_P) + (size_t)rl * 512 + head * 64 + d0; store8_f32(ko, ol); store8_f32(ko + 32, oh);
;                     } else {
;                         store8_bf16(qib + o512, ol); store8_bf16(qib + o512 + 32, oh);
;                     }
.LBB0_413:
	v_lshlrev_b32_e32 v152, 7, v116
	v_lshl_add_u64 v[116:117], v[160:161], 0, v[152:153]
	global_load_dwordx4 v[108:111], v[116:117], off
	global_load_dwordx4 v[124:127], v[116:117], off offset:16
	v_lshl_add_u64 v[116:117], v[158:159], 0, v[152:153]
	global_load_dwordx4 v[128:131], v[116:117], off
	global_load_dwordx4 v[132:135], v[116:117], off offset:16
	v_ashrrev_i32_e32 v113, 31, v112
	v_lshlrev_b64 v[116:117], 9, v[112:113]
	v_lshl_add_u64 v[116:117], v[116:117], 0, v[174:175]
	s_andn2_b64 vcc, exec, s[94:95]
	s_mov_b64 s[12:13], -1
	s_waitcnt vmcnt(3)
	v_pk_mul_f32 v[136:137], v[102:103], v[108:109]
	v_pk_mul_f32 v[138:139], v[104:105], v[108:109]
	v_pk_mul_f32 v[140:141], v[100:101], v[110:111]
	v_pk_mul_f32 v[142:143], v[106:107], v[110:111]
	s_waitcnt vmcnt(2)
	v_pk_mul_f32 v[188:189], v[96:97], v[124:125]
	v_pk_mul_f32 v[124:125], v[120:121], v[124:125]
	v_pk_mul_f32 v[190:191], v[98:99], v[126:127]
	v_pk_mul_f32 v[126:127], v[118:119], v[126:127]
	s_waitcnt vmcnt(1)
	v_pk_fma_f32 v[108:109], v[104:105], v[128:129], v[136:137] neg_lo:[0,0,1] neg_hi:[0,0,1]
	v_pk_fma_f32 v[104:105], v[102:103], v[128:129], v[138:139]
	v_pk_fma_f32 v[110:111], v[106:107], v[130:131], v[140:141] neg_lo:[0,0,1] neg_hi:[0,0,1]
	v_pk_fma_f32 v[106:107], v[100:101], v[130:131], v[142:143]
	s_waitcnt vmcnt(0)
	v_pk_fma_f32 v[100:101], v[120:121], v[132:133], v[188:189] neg_lo:[0,0,1] neg_hi:[0,0,1]
	v_pk_fma_f32 v[96:97], v[96:97], v[132:133], v[124:125]
	v_pk_fma_f32 v[102:103], v[118:119], v[134:135], v[190:191] neg_lo:[0,0,1] neg_hi:[0,0,1]
	v_pk_fma_f32 v[98:99], v[98:99], v[134:135], v[126:127]
	s_cbranch_vccnz .LBB0_419
	s_andn2_b64 vcc, exec, s[2:3]
	s_cbranch_vccnz .LBB0_416
	v_readlane_b32 s12, v249, 10
	v_readlane_b32 s13, v249, 11
	v_cvt_pk_bf16_f32 v118, v108, v109
	v_cvt_pk_bf16_f32 v119, v110, v111
	v_cvt_pk_bf16_f32 v120, v100, v101
	v_cvt_pk_bf16_f32 v121, v102, v103
	s_nop 1
	v_lshl_add_u64 v[124:125], v[116:117], 1, s[12:13]
	s_mov_b64 s[12:13], 0
	global_store_dwordx4 v[124:125], v[118:121], off nt
	s_nop 1
	v_cvt_pk_bf16_f32 v118, v104, v105
	v_cvt_pk_bf16_f32 v119, v106, v107
	v_cvt_pk_bf16_f32 v120, v96, v97
	v_cvt_pk_bf16_f32 v121, v98, v99
	global_store_dwordx4 v[124:125], v[118:121], off offset:64 nt
.LBB0_416:
	s_andn2_b64 vcc, exec, s[12:13]
	s_cbranch_vccnz .LBB0_418
	v_readlane_b32 s12, v249, 6
	v_readlane_b32 s13, v249, 7
	v_readlane_b32 s60, v250, 0
	v_readlane_b32 s62, v250, 2
	v_lshl_add_u64 v[124:125], v[116:117], 1, s[12:13]
	s_lshl_b32 s12, s53, 2
	v_readlane_b32 s63, v250, 3
	s_add_u32 s12, s62, s12
	v_ashrrev_i32_e32 v115, 31, v114
	s_addc_u32 s13, s63, 0
	v_lshlrev_b64 v[114:115], 11, v[114:115]
	v_lshl_add_u64 v[114:115], s[12:13], 0, v[114:115]
	s_lshl_b32 s12, s18, 2
	s_mov_b32 s13, s19
	v_lshl_add_u64 v[114:115], v[114:115], 0, s[12:13]
	v_cvt_pk_bf16_f32 v118, v108, v109
	v_cvt_pk_bf16_f32 v119, v110, v111
	v_cvt_pk_bf16_f32 v120, v100, v101
	v_cvt_pk_bf16_f32 v121, v102, v103
	v_lshl_add_u64 v[114:115], v[154:155], 2, v[114:115]
	global_store_dwordx4 v[124:125], v[118:121], off nt
	v_readlane_b32 s61, v250, 1
	v_readlane_b32 s64, v250, 4
	v_cvt_pk_bf16_f32 v118, v104, v105
	v_cvt_pk_bf16_f32 v119, v106, v107
	v_cvt_pk_bf16_f32 v120, v96, v97
	v_cvt_pk_bf16_f32 v121, v98, v99
	global_store_dwordx4 v[124:125], v[118:121], off offset:64 nt
	v_readlane_b32 s65, v250, 5
	v_readlane_b32 s66, v250, 6
	v_readlane_b32 s67, v250, 7
	global_store_dwordx4 v[114:115], v[108:111], off nt
	global_store_dwordx4 v[114:115], v[100:103], off offset:16 nt
	global_store_dwordx4 v[114:115], v[104:107], off offset:128 nt
	global_store_dwordx4 v[114:115], v[96:99], off offset:144 nt

;     __device__ __forceinline__ void operator()(const f32x4 (&acc)[2][2][4][2], const Unit& u, int wr, int wc, int fr, int fq) const {
;     ...
;                     if (pn < 8) {
; #pragma unroll
;                         for (int e = 0; e < 8; ++e) { ol[e] *= 0.18033688011112042f; oh[e] *= 0.18033688011112042f; }
;                         store8_bf16(qb + o512, ol); store8_bf16(qb + o512 + 32, oh);
.LBB0_419:
	s_andn2_b64 vcc, exec, s[12:13]
	s_cbranch_vccnz .LBB0_421
	v_readlane_b32 s12, v249, 4
	v_readlane_b32 s13, v249, 5
	v_mul_f32_e32 v108, 0x3e38aa3b, v108
	v_mul_f32_e32 v109, 0x3e38aa3b, v109
	v_mul_f32_e32 v110, 0x3e38aa3b, v110
	v_mul_f32_e32 v111, 0x3e38aa3b, v111
	v_mul_f32_e32 v113, 0x3e38aa3b, v100
	v_mul_f32_e32 v114, 0x3e38aa3b, v96
	v_mul_f32_e32 v115, 0x3e38aa3b, v101
	v_mul_f32_e32 v118, 0x3e38aa3b, v97
	v_mul_f32_e32 v102, 0x3e38aa3b, v102
	v_mul_f32_e32 v119, 0x3e38aa3b, v98
	v_mul_f32_e32 v103, 0x3e38aa3b, v103
	v_mul_f32_e32 v120, 0x3e38aa3b, v99
	v_lshl_add_u64 v[100:101], v[116:117], 1, s[12:13]
	v_cvt_pk_bf16_f32 v96, v108, v109
	v_cvt_pk_bf16_f32 v97, v110, v111
	v_cvt_pk_bf16_f32 v98, v113, v115
	v_cvt_pk_bf16_f32 v99, v102, v103
	v_mul_f32_e32 v104, 0x3e38aa3b, v104
	v_mul_f32_e32 v105, 0x3e38aa3b, v105
	v_mul_f32_e32 v106, 0x3e38aa3b, v106
	v_mul_f32_e32 v107, 0x3e38aa3b, v107
	global_store_dwordx4 v[100:101], v[96:99], off nt
	s_nop 1
	v_cvt_pk_bf16_f32 v96, v104, v105
	v_cvt_pk_bf16_f32 v97, v106, v107
	v_cvt_pk_bf16_f32 v98, v114, v118
	v_cvt_pk_bf16_f32 v99, v119, v120
	global_store_dwordx4 v[100:101], v[96:99], off offset:64 nt

;     __device__ __forceinline__ void operator()(const f32x4 (&acc)[2][2][4][2], const Unit& u, int wr, int wc, int fr, int fq) const {
;     ...
;                 } else if (pn < 6) {
;                     const int ch = 128 * (pn - 2) + c8; float uu[8];
; #pragma unroll
;                     for (int e = 0; e < 8; ++e) uu[e] = lo[e] * hi[e];
;                     store8_bf16(ub + (size_t)r * 512 + ch, uu);
;                     if (!samp) { const int t = rl & (SEQ - 1); if (t >= SEQ - 2) store8_f32(out + OFF_CM_P + (size_t)((rl >> 13) * 2 + (t - (SEQ - 2))) * 512 + ch, uu); }
;                     else { const int tt = rl & 7; if (tt >= 6) store8_f32(out + OFF_CM_S + (size_t)((rl >> 3) * 2 + (tt - 6)) * 512 + ch, uu); }
.LBB0_422:
	s_andn2_b64 vcc, exec, s[12:13]
	s_cbranch_vccnz .LBB0_426
	v_ashrrev_i32_e32 v113, 31, v112
	v_lshlrev_b64 v[104:105], 10, v[112:113]
	v_lshl_add_u64 v[104:105], s[88:89], 0, v[104:105]
	v_cmp_lt_u32_e32 vcc, 5, v123
	v_pk_mul_f32 v[100:101], v[92:93], v[84:85]
	v_pk_mul_f32 v[102:103], v[94:95], v[86:87]
	v_pk_mul_f32 v[96:97], v[88:89], v[80:81]
	v_pk_mul_f32 v[98:99], v[90:91], v[82:83]
	v_lshl_add_u64 v[108:109], v[172:173], 1, v[104:105]
	s_and_b64 s[26:27], s[6:7], vcc
	v_cvt_pk_bf16_f32 v104, v100, v101
	v_cvt_pk_bf16_f32 v105, v102, v103
	v_cvt_pk_bf16_f32 v106, v96, v97
	v_cvt_pk_bf16_f32 v107, v98, v99
	global_store_dwordx4 v[108:109], v[104:107], off nt
	s_and_saveexec_b64 s[12:13], s[26:27]
	s_cbranch_execz .LBB0_425
	v_ashrrev_i32_e32 v104, 2, v122
	v_and_b32_e32 v104, -6, v104
	v_add3_u32 v104, v123, v104, -6
	v_ashrrev_i32_e32 v105, 31, v104
	v_readlane_b32 s26, v249, 18
	v_lshlrev_b64 v[104:105], 11, v[104:105]
	v_readlane_b32 s27, v249, 19
	s_nop 1
	v_lshl_add_u64 v[104:105], s[26:27], 0, v[104:105]
	v_lshl_add_u64 v[104:105], v[172:173], 2, v[104:105]
	global_store_dwordx4 v[104:105], v[100:103], off nt
	global_store_dwordx4 v[104:105], v[96:99], off offset:16 nt

; #define EPI_GET(dst, ai, bj, m, s) do { _Pragma("unroll") for (int e_ = 0; e_ < 4; ++e_) { (dst)[e_] = acc[ai][bj][m][0][e_] * (s); (dst)[4 + e_] = acc[ai][bj][m][1][e_] * (s); } } while (0)
;     __device__ __forceinline__ void operator()(const f32x4 (&acc)[2][2][4][2], const Unit& u, int wr, int wc, int fr, int fq) const {
;     ...
;             for (int m = 0; m < 4; ++m) {
;                 const int r = EPI_ROWS(ai, m); const float rs = rsa[m];
;                 float lo[8], hi[8]; EPI_GET(lo, ai, 0, m, rs); EPI_GET(hi, ai, 1, m, rs);
;                 const int rl = samp ? r - MP : r; const int pos = samp ? PAST + (rl & 7) : (rl & (SEQ - 1));
;                 if (pn < 2) {
;                     store8_bf16(cbb + (size_t)r * 512 + pn * 256 + c8, lo); store8_bf16(cbb + (size_t)r * 512 + pn * 256 + 128 + c8, hi);
;     ...
;                     } else if (wc == 1 && fq == 0) {
;                         store8_f32(iwf + (size_t)r * 8, lo);
;                     }
.LBB0_427:
	s_andn2_b64 vcc, exec, s[12:13]
	s_cbranch_vccnz .LBB0_429
	v_ashrrev_i32_e32 v113, 31, v112
	v_lshlrev_b64 v[96:97], 10, v[112:113]
	v_lshl_add_u64 v[96:97], s[22:23], 0, v[96:97]
	v_lshl_add_u64 v[96:97], s[56:57], 1, v[96:97]
	v_lshl_add_u64 v[96:97], v[156:157], 1, v[96:97]
	v_cvt_pk_bf16_f32 v92, v92, v93
	v_cvt_pk_bf16_f32 v93, v94, v95
	v_cvt_pk_bf16_f32 v94, v88, v89
	v_cvt_pk_bf16_f32 v95, v90, v91
	global_store_dwordx4 v[96:97], v[92:95], off nt
	v_cvt_pk_bf16_f32 v84, v84, v85
	v_cvt_pk_bf16_f32 v85, v86, v87
	v_cvt_pk_bf16_f32 v86, v80, v81
	v_cvt_pk_bf16_f32 v87, v82, v83
	global_store_dwordx4 v[96:97], v[84:87], off offset:256 nt
.LBB0_429:
	v_pk_mul_f32 v[76:77], v[76:77], v[180:181] op_sel_hi:[1,0]
	v_pk_mul_f32 v[68:69], v[68:69], v[180:181] op_sel_hi:[1,0]
	v_pk_mul_f32 v[72:73], v[72:73], v[180:181] op_sel_hi:[1,0]
	v_pk_mul_f32 v[64:65], v[64:65], v[180:181] op_sel_hi:[1,0]
	v_pk_mul_f32 v[78:79], v[78:79], v[180:181] op_sel_hi:[1,0]
	v_pk_mul_f32 v[70:71], v[70:71], v[180:181] op_sel_hi:[1,0]
	v_pk_mul_f32 v[74:75], v[74:75], v[180:181] op_sel_hi:[1,0]
	v_pk_mul_f32 v[66:67], v[66:67], v[180:181] op_sel_hi:[1,0]
	v_or_b32_e32 v96, 48, v182
	s_and_b64 vcc, exec, s[10:11]
	s_mov_b64 s[12:13], -1
	s_cbranch_vccnz .LBB0_468
	v_add_u32_e32 v104, 0xffffc030, v182
	v_cndmask_b32_e64 v98, v96, v104, s[6:7]
	v_and_b32_e32 v105, 7, v98
	v_and_b32_e32 v106, 0x1fff, v98
	s_and_b64 vcc, exec, s[8:9]
	s_cbranch_vccnz .LBB0_455
	v_or_b32_e32 v80, 0x800, v105
	v_cndmask_b32_e64 v107, v106, v80, s[6:7]
	s_andn2_b64 vcc, exec, s[20:21]
	s_cbranch_vccnz .LBB0_442
	s_andn2_b64 vcc, exec, s[16:17]
	s_cbranch_vccnz .LBB0_439
	v_readlane_b32 s12, v249, 14
	v_readlane_b32 s13, v249, 15
	s_andn2_b64 vcc, exec, s[12:13]
	s_cbranch_vccnz .LBB0_640
	s_mov_b64 s[12:13], exec
	v_readlane_b32 s26, v249, 16
	v_readlane_b32 s27, v249, 17
	s_and_b64 s[26:27], s[12:13], s[26:27]
	s_mov_b64 exec, s[26:27]
	s_cbranch_execz .LBB0_436
	v_ashrrev_i32_e32 v97, 31, v96
	v_readlane_b32 s26, v249, 12
	v_lshlrev_b64 v[80:81], 5, v[96:97]
	v_readlane_b32 s27, v249, 13
	s_nop 1
	v_lshl_add_u64 v[80:81], s[26:27], 0, v[80:81]
	global_store_dwordx4 v[80:81], v[76:79], off nt
	global_store_dwordx4 v[80:81], v[72:75], off offset:16 nt

;     __device__ __forceinline__ void operator()(const f32x4 (&acc)[2][2][4][2], const Unit& u, int wr, int wc, int fr, int fq) const {
;     ...
;                     if (wc == 0) {
;                         const int d0 = 8 * fq; float cs[8], sn[8]; load8_f32(cosT + (size_t)pos * 32 + d0, cs); load8_f32(sinT + (size_t)pos * 32 + d0, sn);
;                         float ol[8], oh[8];
; #pragma unroll
;                         for (int e = 0; e < 8; ++e) { ol[e] = lo[e] * cs[e] - hi[e] * sn[e]; oh[e] = hi[e] * cs[e] + lo[e] * sn[e]; }
;                         store8_bf16(kib + (size_t)r * 64 + d0, ol); store8_bf16(kib + (size_t)r * 64 + 32 + d0, oh);
;                         float* io = out + (samp ? OFF_IK_S : OFF_IK_P) + (size_t)rl * 64 + d0; store8_f32(io, ol); store8_f32(io + 32, oh);
.LBB0_437:
	v_lshlrev_b32_e32 v152, 7, v107
	v_lshl_add_u64 v[80:81], v[158:159], 0, v[152:153]
	v_lshl_add_u64 v[88:89], v[160:161], 0, v[152:153]
	global_load_dwordx4 v[92:95], v[80:81], off offset:16
	s_nop 0
	global_load_dwordx4 v[80:83], v[80:81], off
	s_nop 0
	global_load_dwordx4 v[84:87], v[88:89], off offset:16
	s_nop 0
	global_load_dwordx4 v[88:91], v[88:89], off
	v_mov_b32_e32 v100, v76
	v_mov_b32_e32 v101, v68
	v_mov_b32_e32 v108, v68
	v_mov_b32_e32 v109, v76
	v_ashrrev_i32_e32 v97, 31, v96
	v_readlane_b32 s60, v250, 0
	s_lshl_b32 s12, s69, 2
	v_readlane_b32 s62, v250, 2
	v_readlane_b32 s63, v250, 3
	s_add_u32 s12, s62, s12
	v_ashrrev_i32_e32 v99, 31, v98
	s_addc_u32 s13, s63, 0
	v_readlane_b32 s61, v250, 1
	v_readlane_b32 s64, v250, 4
	v_readlane_b32 s65, v250, 5
	v_readlane_b32 s66, v250, 6
	v_readlane_b32 s67, v250, 7
	s_waitcnt vmcnt(2)
	v_mov_b32_e32 v102, v80
	s_waitcnt vmcnt(0)
	v_mov_b32_e32 v103, v88
	v_pk_mul_f32 v[100:101], v[100:101], v[102:103]
	v_pk_mul_f32 v[102:103], v[108:109], v[102:103]
	v_mov_b32_e32 v108, v77
	v_mov_b32_e32 v109, v69
	v_mov_b32_e32 v88, v81
	v_pk_mul_f32 v[80:81], v[108:109], v[88:89]
	v_mov_b32_e32 v108, v100
	v_mov_b32_e32 v109, v80
	v_mov_b32_e32 v80, v101
	v_mov_b32_e32 v100, v69
	v_mov_b32_e32 v101, v77
	v_pk_mul_f32 v[88:89], v[100:101], v[88:89]
	v_mov_b32_e32 v100, v102
	v_mov_b32_e32 v101, v88
	v_mov_b32_e32 v88, v103
	v_pk_add_f32 v[80:81], v[108:109], v[80:81] neg_lo:[0,1] neg_hi:[0,1]
	v_pk_add_f32 v[88:89], v[100:101], v[88:89]
	v_mov_b32_e32 v100, v78
	v_mov_b32_e32 v101, v70
	v_mov_b32_e32 v102, v82
	v_mov_b32_e32 v103, v90
	v_mov_b32_e32 v108, v70
	v_mov_b32_e32 v109, v78
	v_pk_mul_f32 v[100:101], v[100:101], v[102:103]
	v_pk_mul_f32 v[102:103], v[108:109], v[102:103]
	v_mov_b32_e32 v108, v79
	v_mov_b32_e32 v109, v71
	v_mov_b32_e32 v90, v83
	v_pk_mul_f32 v[82:83], v[108:109], v[90:91]
	v_mov_b32_e32 v108, v100
	v_mov_b32_e32 v109, v82
	v_mov_b32_e32 v82, v101
	v_mov_b32_e32 v100, v71
	v_mov_b32_e32 v101, v79
	v_pk_mul_f32 v[90:91], v[100:101], v[90:91]
	v_mov_b32_e32 v100, v102
	v_mov_b32_e32 v101, v90
	v_mov_b32_e32 v90, v103
	v_pk_add_f32 v[82:83], v[108:109], v[82:83] neg_lo:[0,1] neg_hi:[0,1]
	v_pk_add_f32 v[90:91], v[100:101], v[90:91]
	v_mov_b32_e32 v100, v72
	v_mov_b32_e32 v101, v64
	v_mov_b32_e32 v102, v92
	v_mov_b32_e32 v103, v84
	v_mov_b32_e32 v108, v64
	v_mov_b32_e32 v109, v72
	v_pk_mul_f32 v[100:101], v[100:101], v[102:103]
	v_pk_mul_f32 v[102:103], v[108:109], v[102:103]
	v_mov_b32_e32 v108, v73
	v_mov_b32_e32 v109, v65
	v_mov_b32_e32 v84, v93
	v_pk_mul_f32 v[92:93], v[108:109], v[84:85]
	v_mov_b32_e32 v108, v100
	v_mov_b32_e32 v109, v92
	v_mov_b32_e32 v92, v101
	v_mov_b32_e32 v100, v65
	v_mov_b32_e32 v101, v73
	v_pk_mul_f32 v[84:85], v[100:101], v[84:85]
	v_mov_b32_e32 v100, v102
	v_mov_b32_e32 v101, v84
	v_mov_b32_e32 v84, v103
	v_pk_add_f32 v[92:93], v[108:109], v[92:93] neg_lo:[0,1] neg_hi:[0,1]
	v_pk_add_f32 v[84:85], v[100:101], v[84:85]
	v_mov_b32_e32 v100, v74
	v_mov_b32_e32 v101, v66
	v_mov_b32_e32 v102, v94
	v_mov_b32_e32 v103, v86
	v_mov_b32_e32 v108, v66
	v_mov_b32_e32 v109, v74
	v_pk_mul_f32 v[100:101], v[100:101], v[102:103]
	v_pk_mul_f32 v[102:103], v[108:109], v[102:103]
	v_mov_b32_e32 v108, v75
	v_mov_b32_e32 v109, v67
	v_mov_b32_e32 v86, v95
	v_pk_mul_f32 v[94:95], v[108:109], v[86:87]
	v_mov_b32_e32 v108, v100
	v_mov_b32_e32 v109, v94
	v_mov_b32_e32 v94, v101
	v_mov_b32_e32 v100, v67
	v_mov_b32_e32 v101, v75
	v_pk_mul_f32 v[86:87], v[100:101], v[86:87]
	v_mov_b32_e32 v100, v102
	v_mov_b32_e32 v101, v86
	v_mov_b32_e32 v86, v103
	v_pk_add_f32 v[86:87], v[100:101], v[86:87]
	v_lshlrev_b64 v[100:101], 7, v[96:97]
	v_pk_add_f32 v[94:95], v[108:109], v[94:95] neg_lo:[0,1] neg_hi:[0,1]
	v_lshl_add_u64 v[108:109], v[162:163], 0, v[100:101]
	v_cvt_pk_bf16_f32 v100, v80, v81
	v_cvt_pk_bf16_f32 v101, v82, v83
	v_cvt_pk_bf16_f32 v102, v92, v93
	v_cvt_pk_bf16_f32 v103, v94, v95
	global_store_dwordx4 v[108:109], v[100:103], off nt
	s_nop 1
	v_cvt_pk_bf16_f32 v100, v88, v89
	v_cvt_pk_bf16_f32 v101, v90, v91
	v_cvt_pk_bf16_f32 v102, v84, v85
	v_cvt_pk_bf16_f32 v103, v86, v87
	global_store_dwordx4 v[108:109], v[100:103], off offset:64 nt
	s_nop 1
	v_lshlrev_b64 v[100:101], 8, v[98:99]
	v_lshl_add_u64 v[100:101], s[12:13], 0, v[100:101]
	v_lshl_add_u64 v[100:101], v[154:155], 2, v[100:101]
	global_store_dwordx4 v[100:101], v[80:83], off nt
	global_store_dwordx4 v[100:101], v[92:95], off offset:16 nt
	global_store_dwordx4 v[100:101], v[88:91], off offset:128 nt
	global_store_dwordx4 v[100:101], v[84:87], off offset:144 nt

;     __device__ __forceinline__ void operator()(const f32x4 (&acc)[2][2][4][2], const Unit& u, int wr, int wc, int fr, int fq) const {
;     ...
;                 } else if (pn < 12) {
;                     const int c = 256 * (pn - 10) + c8;
;                     store8_bf16(vb + (size_t)r * 512 + c, lo); store8_bf16(vb + (size_t)r * 512 + c + 128, hi);
;                     float* vo = out + (samp ? OFF_V_S : OFF_V_P) + (size_t)rl * 512 + c; store8_f32(vo, lo); store8_f32(vo + 128, hi);
.LBB0_439:
	s_andn2_b64 vcc, exec, s[12:13]
	s_cbranch_vccnz .LBB0_441
	v_ashrrev_i32_e32 v97, 31, v96
	v_readlane_b32 s12, v249, 8
	v_lshlrev_b64 v[80:81], 10, v[96:97]
	v_readlane_b32 s13, v249, 9
	v_readlane_b32 s60, v250, 0
	v_readlane_b32 s62, v250, 2
	v_lshl_add_u64 v[80:81], s[12:13], 0, v[80:81]
	v_lshl_add_u64 v[84:85], v[176:177], 1, v[80:81]
	v_cvt_pk_bf16_f32 v80, v76, v77
	v_cvt_pk_bf16_f32 v81, v78, v79
	s_lshl_b32 s12, s55, 2
	v_cvt_pk_bf16_f32 v82, v72, v73
	v_cvt_pk_bf16_f32 v83, v74, v75
	global_store_dwordx4 v[84:85], v[80:83], off nt
	v_readlane_b32 s63, v250, 3
	s_add_u32 s12, s62, s12
	v_cvt_pk_bf16_f32 v80, v68, v69
	v_cvt_pk_bf16_f32 v81, v70, v71
	v_ashrrev_i32_e32 v99, 31, v98
	v_cvt_pk_bf16_f32 v82, v64, v65
	v_cvt_pk_bf16_f32 v83, v66, v67
	global_store_dwordx4 v[84:85], v[80:83], off offset:256 nt
	s_addc_u32 s13, s63, 0
	v_readlane_b32 s61, v250, 1
	v_lshlrev_b64 v[80:81], 11, v[98:99]
	v_lshl_add_u64 v[80:81], s[12:13], 0, v[80:81]
	v_lshl_add_u64 v[80:81], v[176:177], 2, v[80:81]
	v_readlane_b32 s64, v250, 4
	v_readlane_b32 s65, v250, 5
	v_readlane_b32 s66, v250, 6
	v_readlane_b32 s67, v250, 7
	global_store_dwordx4 v[80:81], v[76:79], off nt
	global_store_dwordx4 v[80:81], v[72:75], off offset:16 nt
	global_store_dwordx4 v[80:81], v[68:71], off offset:512 nt
	global_store_dwordx4 v[80:81], v[64:67], off offset:528 nt

;     __device__ __forceinline__ void operator()(const f32x4 (&acc)[2][2][4][2], const Unit& u, int wr, int wc, int fr, int fq) const {
;     ...
;                     float cs[8], sn[8]; load8_f32(cosT + (size_t)pos * 32 + d0, cs); load8_f32(sinT + (size_t)pos * 32 + d0, sn);
;                     float ol[8], oh[8];
; #pragma unroll
;                     for (int e = 0; e < 8; ++e) { ol[e] = lo[e] * cs[e] - hi[e] * sn[e]; oh[e] = hi[e] * cs[e] + lo[e] * sn[e]; }
;                     const size_t o512 = (size_t)r * 512 + head * 64 + d0;
;                     if (pn < 8) {
; #pragma unroll
;                         for (int e = 0; e < 8; ++e) { ol[e] *= 0.18033688011112042f; oh[e] *= 0.18033688011112042f; }
;                         store8_bf16(qb + o512, ol); store8_bf16(qb + o512 + 32, oh);
;                     } else if (pn < 10) {
;                         store8_bf16(kb + o512, ol); store8_bf16(kb + o512 + 32, oh);
;                         float* ko = out + (samp ? OFF_K_S : OFF_K_P) + (size_t)rl * 512 + head * 64 + d0; store8_f32(ko, ol); store8_f32(ko + 32, oh);
;                     } else {
;                         store8_bf16(qib + o512, ol); store8_bf16(qib + o512 + 32, oh);
;                     }
.LBB0_446:
	v_lshlrev_b32_e32 v152, 7, v107
	v_lshl_add_u64 v[84:85], v[158:159], 0, v[152:153]
	global_load_dwordx4 v[108:111], v[84:85], off offset:16
	global_load_dwordx4 v[112:115], v[84:85], off
	v_lshl_add_u64 v[84:85], v[160:161], 0, v[152:153]
	global_load_dwordx4 v[116:119], v[84:85], off offset:16
	global_load_dwordx4 v[120:123], v[84:85], off
	v_ashrrev_i32_e32 v97, 31, v96
	s_mov_b64 s[12:13], -1
	s_andn2_b64 vcc, exec, s[94:95]
	s_waitcnt vmcnt(0)
	v_pk_mul_f32 v[92:93], v[100:101], v[120:121]
	v_pk_mul_f32 v[84:85], v[86:87], v[120:121]
	v_pk_fma_f32 v[92:93], v[86:87], v[112:113], v[92:93]
	v_pk_mul_f32 v[86:87], v[80:81], v[122:123]
	v_pk_fma_f32 v[84:85], v[100:101], v[112:113], v[84:85] neg_lo:[0,0,1] neg_hi:[0,0,1]
	v_pk_fma_f32 v[86:87], v[94:95], v[114:115], v[86:87] neg_lo:[0,0,1] neg_hi:[0,0,1]
	v_pk_mul_f32 v[94:95], v[94:95], v[122:123]
	v_lshlrev_b64 v[100:101], 9, v[96:97]
	v_pk_fma_f32 v[94:95], v[80:81], v[114:115], v[94:95]
	v_pk_mul_f32 v[80:81], v[82:83], v[116:117]
	v_lshl_add_u64 v[100:101], v[100:101], 0, v[174:175]
	v_pk_fma_f32 v[80:81], v[88:89], v[108:109], v[80:81] neg_lo:[0,0,1] neg_hi:[0,0,1]
	v_pk_mul_f32 v[88:89], v[88:89], v[116:117]
	s_nop 0
	v_pk_fma_f32 v[88:89], v[82:83], v[108:109], v[88:89]
	v_pk_mul_f32 v[82:83], v[102:103], v[118:119]
	s_nop 0
	v_pk_fma_f32 v[82:83], v[90:91], v[110:111], v[82:83] neg_lo:[0,0,1] neg_hi:[0,0,1]
	v_pk_mul_f32 v[90:91], v[90:91], v[118:119]
	s_nop 0
	v_pk_fma_f32 v[90:91], v[102:103], v[110:111], v[90:91]
	s_cbranch_vccnz .LBB0_452
	s_andn2_b64 vcc, exec, s[2:3]
	s_cbranch_vccnz .LBB0_449
	v_readlane_b32 s12, v249, 10
	v_readlane_b32 s13, v249, 11
	v_cvt_pk_bf16_f32 v108, v84, v85
	v_cvt_pk_bf16_f32 v109, v86, v87
	v_cvt_pk_bf16_f32 v110, v80, v81
	v_cvt_pk_bf16_f32 v111, v82, v83
	s_nop 1
	v_lshl_add_u64 v[102:103], v[100:101], 1, s[12:13]
	s_mov_b64 s[12:13], 0
	global_store_dwordx4 v[102:103], v[108:111], off nt
	s_nop 1
	v_cvt_pk_bf16_f32 v108, v92, v93
	v_cvt_pk_bf16_f32 v109, v94, v95
	v_cvt_pk_bf16_f32 v110, v88, v89
	v_cvt_pk_bf16_f32 v111, v90, v91
	global_store_dwordx4 v[102:103], v[108:111], off offset:64 nt
.LBB0_449:
	s_andn2_b64 vcc, exec, s[12:13]
	s_cbranch_vccnz .LBB0_451
	v_readlane_b32 s12, v249, 6
	v_readlane_b32 s13, v249, 7
	v_readlane_b32 s60, v250, 0
	v_readlane_b32 s62, v250, 2
	v_lshl_add_u64 v[102:103], v[100:101], 1, s[12:13]
	s_lshl_b32 s12, s53, 2
	v_readlane_b32 s63, v250, 3
	s_add_u32 s12, s62, s12
	v_ashrrev_i32_e32 v99, 31, v98
	s_addc_u32 s13, s63, 0
	v_lshlrev_b64 v[98:99], 11, v[98:99]
	v_lshl_add_u64 v[98:99], s[12:13], 0, v[98:99]
	s_lshl_b32 s12, s18, 2
	s_mov_b32 s13, s19
	v_lshl_add_u64 v[98:99], v[98:99], 0, s[12:13]
	v_cvt_pk_bf16_f32 v108, v84, v85
	v_cvt_pk_bf16_f32 v109, v86, v87
	v_cvt_pk_bf16_f32 v110, v80, v81
	v_cvt_pk_bf16_f32 v111, v82, v83
	v_lshl_add_u64 v[98:99], v[154:155], 2, v[98:99]
	global_store_dwordx4 v[102:103], v[108:111], off nt
	v_readlane_b32 s61, v250, 1
	v_readlane_b32 s64, v250, 4
	v_cvt_pk_bf16_f32 v108, v92, v93
	v_cvt_pk_bf16_f32 v109, v94, v95
	v_cvt_pk_bf16_f32 v110, v88, v89
	v_cvt_pk_bf16_f32 v111, v90, v91
	global_store_dwordx4 v[102:103], v[108:111], off offset:64 nt
	v_readlane_b32 s65, v250, 5
	v_readlane_b32 s66, v250, 6
	v_readlane_b32 s67, v250, 7
	global_store_dwordx4 v[98:99], v[84:87], off nt
	global_store_dwordx4 v[98:99], v[80:83], off offset:16 nt
	global_store_dwordx4 v[98:99], v[92:95], off offset:128 nt
	global_store_dwordx4 v[98:99], v[88:91], off offset:144 nt

;     __device__ __forceinline__ void operator()(const f32x4 (&acc)[2][2][4][2], const Unit& u, int wr, int wc, int fr, int fq) const {
;     ...
;                     if (pn < 8) {
; #pragma unroll
;                         for (int e = 0; e < 8; ++e) { ol[e] *= 0.18033688011112042f; oh[e] *= 0.18033688011112042f; }
;                         store8_bf16(qb + o512, ol); store8_bf16(qb + o512 + 32, oh);
.LBB0_452:
	s_andn2_b64 vcc, exec, s[12:13]
	s_cbranch_vccnz .LBB0_454
	v_readlane_b32 s12, v249, 4
	v_mul_f32_e32 v83, 0x3e38aa3b, v83
	v_readlane_b32 s13, v249, 5
	v_mul_f32_e32 v97, 0x3e38aa3b, v84
	v_mul_f32_e32 v98, 0x3e38aa3b, v85
	v_mul_f32_e32 v86, 0x3e38aa3b, v86
	v_mul_f32_e32 v87, 0x3e38aa3b, v87
	v_mul_f32_e32 v99, 0x3e38aa3b, v80
	v_mul_f32_e32 v102, 0x3e38aa3b, v81
	v_mul_f32_e32 v103, 0x3e38aa3b, v82
	v_lshl_add_u64 v[84:85], v[100:101], 1, s[12:13]
	v_cvt_pk_bf16_f32 v80, v97, v98
	v_cvt_pk_bf16_f32 v81, v86, v87
	v_cvt_pk_bf16_f32 v82, v99, v102
	v_cvt_pk_bf16_f32 v83, v103, v83
	v_mul_f32_e32 v92, 0x3e38aa3b, v92
	v_mul_f32_e32 v93, 0x3e38aa3b, v93
	v_mul_f32_e32 v94, 0x3e38aa3b, v94
	v_mul_f32_e32 v95, 0x3e38aa3b, v95
	v_mul_f32_e32 v88, 0x3e38aa3b, v88
	v_mul_f32_e32 v89, 0x3e38aa3b, v89
	v_mul_f32_e32 v90, 0x3e38aa3b, v90
	v_mul_f32_e32 v91, 0x3e38aa3b, v91
	global_store_dwordx4 v[84:85], v[80:83], off nt
	s_nop 1
	v_cvt_pk_bf16_f32 v80, v92, v93
	v_cvt_pk_bf16_f32 v81, v94, v95
	v_cvt_pk_bf16_f32 v82, v88, v89
	v_cvt_pk_bf16_f32 v83, v90, v91
	global_store_dwordx4 v[84:85], v[80:83], off offset:64 nt

;     __device__ __forceinline__ void operator()(const f32x4 (&acc)[2][2][4][2], const Unit& u, int wr, int wc, int fr, int fq) const {
;     ...
;                 } else if (pn < 6) {
;                     const int ch = 128 * (pn - 2) + c8; float uu[8];
; #pragma unroll
;                     for (int e = 0; e < 8; ++e) uu[e] = lo[e] * hi[e];
;                     store8_bf16(ub + (size_t)r * 512 + ch, uu);
;                     if (!samp) { const int t = rl & (SEQ - 1); if (t >= SEQ - 2) store8_f32(out + OFF_CM_P + (size_t)((rl >> 13) * 2 + (t - (SEQ - 2))) * 512 + ch, uu); }
;                     else { const int tt = rl & 7; if (tt >= 6) store8_f32(out + OFF_CM_S + (size_t)((rl >> 3) * 2 + (tt - 6)) * 512 + ch, uu); }
.LBB0_455:
	s_andn2_b64 vcc, exec, s[12:13]
	s_cbranch_vccnz .LBB0_467
	v_ashrrev_i32_e32 v97, 31, v96
	v_lshlrev_b64 v[88:89], 10, v[96:97]
	v_lshl_add_u64 v[88:89], s[88:89], 0, v[88:89]
	v_pk_mul_f32 v[84:85], v[76:77], v[68:69]
	v_pk_mul_f32 v[86:87], v[78:79], v[70:71]
	v_pk_mul_f32 v[80:81], v[72:73], v[64:65]
	v_pk_mul_f32 v[82:83], v[74:75], v[66:67]
	v_lshl_add_u64 v[92:93], v[172:173], 1, v[88:89]
	s_andn2_b64 vcc, exec, s[84:85]
	v_cvt_pk_bf16_f32 v88, v84, v85
	v_cvt_pk_bf16_f32 v89, v86, v87
	v_cvt_pk_bf16_f32 v90, v80, v81
	v_cvt_pk_bf16_f32 v91, v82, v83
	global_store_dwordx4 v[92:93], v[88:91], off nt
	s_cbranch_vccnz .LBB0_460
	s_movk_i32 s12, 0x1ffd
	v_cmp_lt_u32_e32 vcc, s12, v106
	s_mov_b64 s[26:27], 0
	s_mov_b64 s[12:13], 0
	s_and_saveexec_b64 s[28:29], vcc
	s_ashr_i32 s12, s58, 12
	s_and_b32 s12, s12, -2
	s_addk_i32 s12, 0xe002
	v_add_u32_e32 v88, s12, v106
	s_mov_b64 s[12:13], exec
	s_or_b64 exec, exec, s[28:29]
	s_mov_b64 s[28:29], 0x8800000
	s_and_b64 vcc, exec, s[26:27]
	s_cbranch_vccnz .LBB0_461
	s_branch .LBB0_464

;     __device__ __forceinline__ void operator()(const f32x4 (&acc)[2][2][4][2], const Unit& u, int wr, int wc, int fr, int fq) const {
;     ...
;                 } else if (pn < 6) {
;                     const int ch = 128 * (pn - 2) + c8; float uu[8];
; #pragma unroll
;                     for (int e = 0; e < 8; ++e) uu[e] = lo[e] * hi[e];
;                     store8_bf16(ub + (size_t)r * 512 + ch, uu);
;                     if (!samp) { const int t = rl & (SEQ - 1); if (t >= SEQ - 2) store8_f32(out + OFF_CM_P + (size_t)((rl >> 13) * 2 + (t - (SEQ - 2))) * 512 + ch, uu); }
;                     else { const int tt = rl & 7; if (tt >= 6) store8_f32(out + OFF_CM_S + (size_t)((rl >> 3) * 2 + (tt - 6)) * 512 + ch, uu); }
.LBB0_464:
	s_and_saveexec_b64 s[26:27], s[12:13]
	s_cbranch_execz .LBB0_466
	v_readlane_b32 s60, v250, 0
	v_readlane_b32 s62, v250, 2
	v_readlane_b32 s63, v250, 3
	s_add_u32 s12, s62, s28
	v_ashrrev_i32_e32 v89, 31, v88
	s_addc_u32 s13, s63, s29
	v_lshlrev_b64 v[88:89], 11, v[88:89]
	v_lshl_add_u64 v[88:89], s[12:13], 0, v[88:89]
	v_lshl_add_u64 v[88:89], v[172:173], 2, v[88:89]
	v_readlane_b32 s61, v250, 1
	v_readlane_b32 s64, v250, 4
	v_readlane_b32 s65, v250, 5
	v_readlane_b32 s66, v250, 6
	v_readlane_b32 s67, v250, 7
	global_store_dwordx4 v[88:89], v[84:87], off nt
	global_store_dwordx4 v[88:89], v[80:83], off offset:16 nt

; #define EPI_GET(dst, ai, bj, m, s) do { _Pragma("unroll") for (int e_ = 0; e_ < 4; ++e_) { (dst)[e_] = acc[ai][bj][m][0][e_] * (s); (dst)[4 + e_] = acc[ai][bj][m][1][e_] * (s); } } while (0)
;     __device__ __forceinline__ void operator()(const f32x4 (&acc)[2][2][4][2], const Unit& u, int wr, int wc, int fr, int fq) const {
;     ...
;         for (int ai = 0; ai < 2; ++ai) {
;             float rsa[4];
; #pragma unroll
;             for (int m = 0; m < 4; ++m) rsa[m] = rstd[EPI_ROWS(ai, m)];
; #pragma unroll
;             for (int m = 0; m < 4; ++m) {
;                 const int r = EPI_ROWS(ai, m); const float rs = rsa[m];
;                 float lo[8], hi[8]; EPI_GET(lo, ai, 0, m, rs); EPI_GET(hi, ai, 1, m, rs);
;                 const int rl = samp ? r - MP : r; const int pos = samp ? PAST + (rl & 7) : (rl & (SEQ - 1));
;                 if (pn < 2) {
;                     store8_bf16(cbb + (size_t)r * 512 + pn * 256 + c8, lo); store8_bf16(cbb + (size_t)r * 512 + pn * 256 + 128 + c8, hi);
;                 } else if (pn < 6) {
;                     const int ch = 128 * (pn - 2) + c8; float uu[8];
; #pragma unroll
;                     for (int e = 0; e < 8; ++e) uu[e] = lo[e] * hi[e];
;                     store8_bf16(ub + (size_t)r * 512 + ch, uu);
;                     if (!samp) { const int t = rl & (SEQ - 1); if (t >= SEQ - 2) store8_f32(out + OFF_CM_P + (size_t)((rl >> 13) * 2 + (t - (SEQ - 2))) * 512 + ch, uu); }
;                     else { const int tt = rl & 7; if (tt >= 6) store8_f32(out + OFF_CM_S + (size_t)((rl >> 3) * 2 + (tt - 6)) * 512 + ch, uu); }
;                 } else if (pn < 10 || pn == 12 || pn == 13) {
;     ...
;                     } else if (wc == 1 && fq == 0) {
;                         store8_f32(iwf + (size_t)r * 8, lo);
.LBB0_468:
	s_andn2_b64 vcc, exec, s[12:13]
	s_cbranch_vccnz .LBB0_470
	v_ashrrev_i32_e32 v97, 31, v96
	v_lshlrev_b64 v[80:81], 10, v[96:97]
	v_lshl_add_u64 v[80:81], s[22:23], 0, v[80:81]
	v_lshl_add_u64 v[80:81], s[56:57], 1, v[80:81]
	v_lshl_add_u64 v[80:81], v[156:157], 1, v[80:81]
	v_cvt_pk_bf16_f32 v76, v76, v77
	v_cvt_pk_bf16_f32 v77, v78, v79
	v_cvt_pk_bf16_f32 v78, v72, v73
	v_cvt_pk_bf16_f32 v79, v74, v75
	global_store_dwordx4 v[80:81], v[76:79], off nt
	v_cvt_pk_bf16_f32 v68, v68, v69
	v_cvt_pk_bf16_f32 v69, v70, v71
	v_cvt_pk_bf16_f32 v70, v64, v65
	v_cvt_pk_bf16_f32 v71, v66, v67
	global_store_dwordx4 v[80:81], v[68:71], off offset:256 nt
.LBB0_470:
	v_add_u32_e32 v64, 0x80, v178
	v_ashrrev_i32_e32 v65, 31, v64
	v_lshl_add_u64 v[64:65], v[64:65], 2, s[86:87]
	global_load_dword v66, v[64:65], off
	global_load_dword v86, v[64:65], off offset:64
	global_load_dword v84, v[64:65], off offset:128
	global_load_dword v80, v[64:65], off offset:192
	s_addk_i32 s58, 0x80
	v_or_b32_e32 v82, s58, v181
	s_mov_b64 s[12:13], -1
	s_and_b64 vcc, exec, s[10:11]
	s_waitcnt vmcnt(3)
	v_pk_mul_f32 v[60:61], v[60:61], v[66:67] op_sel_hi:[1,0]
	v_pk_mul_f32 v[52:53], v[52:53], v[66:67] op_sel_hi:[1,0]
	v_pk_mul_f32 v[56:57], v[56:57], v[66:67] op_sel_hi:[1,0]
	v_pk_mul_f32 v[48:49], v[48:49], v[66:67] op_sel_hi:[1,0]
	v_pk_mul_f32 v[62:63], v[62:63], v[66:67] op_sel_hi:[1,0]
	v_pk_mul_f32 v[54:55], v[54:55], v[66:67] op_sel_hi:[1,0]
	v_pk_mul_f32 v[58:59], v[58:59], v[66:67] op_sel_hi:[1,0]
	v_pk_mul_f32 v[50:51], v[50:51], v[66:67] op_sel_hi:[1,0]
	s_cbranch_vccnz .LBB0_509
	v_add_u32_e32 v81, 0xffffc000, v82
	v_cndmask_b32_e64 v88, v82, v81, s[6:7]
	v_and_b32_e32 v85, 7, v88
	v_and_b32_e32 v87, 0x1fff, v88
	s_and_b64 vcc, exec, s[8:9]
	s_cbranch_vccnz .LBB0_496
	v_or_b32_e32 v64, 0x800, v85
	v_cndmask_b32_e64 v90, v87, v64, s[6:7]
	s_andn2_b64 vcc, exec, s[20:21]
	s_cbranch_vccnz .LBB0_483
	s_andn2_b64 vcc, exec, s[16:17]
	s_cbranch_vccnz .LBB0_480
	v_readlane_b32 s12, v249, 14
	v_readlane_b32 s13, v249, 15
	s_andn2_b64 vcc, exec, s[12:13]
	s_cbranch_vccnz .LBB0_641
	s_mov_b64 s[12:13], exec
	v_readlane_b32 s26, v249, 16
	v_readlane_b32 s27, v249, 17
	s_and_b64 s[26:27], s[12:13], s[26:27]
	s_mov_b64 exec, s[26:27]
	s_cbranch_execz .LBB0_477
	v_ashrrev_i32_e32 v83, 31, v82
	v_readlane_b32 s26, v249, 12
	v_lshlrev_b64 v[64:65], 5, v[82:83]
	v_readlane_b32 s27, v249, 13
	s_nop 1
	v_lshl_add_u64 v[64:65], s[26:27], 0, v[64:65]
	global_store_dwordx4 v[64:65], v[60:63], off nt
	global_store_dwordx4 v[64:65], v[56:59], off offset:16 nt

;     __device__ __forceinline__ void operator()(const f32x4 (&acc)[2][2][4][2], const Unit& u, int wr, int wc, int fr, int fq) const {
;     ...
;                     if (wc == 0) {
;                         const int d0 = 8 * fq; float cs[8], sn[8]; load8_f32(cosT + (size_t)pos * 32 + d0, cs); load8_f32(sinT + (size_t)pos * 32 + d0, sn);
;                         float ol[8], oh[8];
; #pragma unroll
;                         for (int e = 0; e < 8; ++e) { ol[e] = lo[e] * cs[e] - hi[e] * sn[e]; oh[e] = hi[e] * cs[e] + lo[e] * sn[e]; }
;                         store8_bf16(kib + (size_t)r * 64 + d0, ol); store8_bf16(kib + (size_t)r * 64 + 32 + d0, oh);
;                         float* io = out + (samp ? OFF_IK_S : OFF_IK_P) + (size_t)rl * 64 + d0; store8_f32(io, ol); store8_f32(io + 32, oh);
.LBB0_478:
	v_lshlrev_b32_e32 v152, 7, v90
	v_lshl_add_u64 v[64:65], v[158:159], 0, v[152:153]
	v_lshl_add_u64 v[72:73], v[160:161], 0, v[152:153]
	global_load_dwordx4 v[76:79], v[64:65], off offset:16
	s_nop 0
	global_load_dwordx4 v[64:67], v[64:65], off
	s_nop 0
	global_load_dwordx4 v[68:71], v[72:73], off offset:16
	s_nop 0
	global_load_dwordx4 v[72:75], v[72:73], off
	v_mov_b32_e32 v92, v60
	v_mov_b32_e32 v93, v52
	v_mov_b32_e32 v96, v52
	v_mov_b32_e32 v97, v60
	v_ashrrev_i32_e32 v83, 31, v82
	v_readlane_b32 s60, v250, 0
	s_lshl_b32 s12, s69, 2
	v_readlane_b32 s62, v250, 2
	v_readlane_b32 s63, v250, 3
	s_add_u32 s12, s62, s12
	v_ashrrev_i32_e32 v89, 31, v88
	s_addc_u32 s13, s63, 0
	v_readlane_b32 s61, v250, 1
	v_readlane_b32 s64, v250, 4
	v_readlane_b32 s65, v250, 5
	v_readlane_b32 s66, v250, 6
	v_readlane_b32 s67, v250, 7
	s_waitcnt vmcnt(2)
	v_mov_b32_e32 v94, v64
	s_waitcnt vmcnt(0)
	v_mov_b32_e32 v95, v72
	v_pk_mul_f32 v[92:93], v[92:93], v[94:95]
	v_pk_mul_f32 v[94:95], v[96:97], v[94:95]
	v_mov_b32_e32 v96, v61
	v_mov_b32_e32 v97, v53
	v_mov_b32_e32 v72, v65
	v_pk_mul_f32 v[64:65], v[96:97], v[72:73]
	v_mov_b32_e32 v96, v92
	v_mov_b32_e32 v97, v64
	v_mov_b32_e32 v64, v93
	v_mov_b32_e32 v92, v53
	v_mov_b32_e32 v93, v61
	v_pk_mul_f32 v[72:73], v[92:93], v[72:73]
	v_mov_b32_e32 v92, v94
	v_mov_b32_e32 v93, v72
	v_mov_b32_e32 v72, v95
	v_pk_add_f32 v[64:65], v[96:97], v[64:65] neg_lo:[0,1] neg_hi:[0,1]
	v_pk_add_f32 v[72:73], v[92:93], v[72:73]
	v_mov_b32_e32 v92, v62
	v_mov_b32_e32 v93, v54
	v_mov_b32_e32 v94, v66
	v_mov_b32_e32 v95, v74
	v_mov_b32_e32 v96, v54
	v_mov_b32_e32 v97, v62
	v_pk_mul_f32 v[92:93], v[92:93], v[94:95]
	v_pk_mul_f32 v[94:95], v[96:97], v[94:95]
	v_mov_b32_e32 v96, v63
	v_mov_b32_e32 v97, v55
	v_mov_b32_e32 v74, v67
	v_pk_mul_f32 v[66:67], v[96:97], v[74:75]
	v_mov_b32_e32 v96, v92
	v_mov_b32_e32 v97, v66
	v_mov_b32_e32 v66, v93
	v_mov_b32_e32 v92, v55
	v_mov_b32_e32 v93, v63
	v_pk_mul_f32 v[74:75], v[92:93], v[74:75]
	v_mov_b32_e32 v92, v94
	v_mov_b32_e32 v93, v74
	v_mov_b32_e32 v74, v95
	v_pk_add_f32 v[66:67], v[96:97], v[66:67] neg_lo:[0,1] neg_hi:[0,1]
	v_pk_add_f32 v[74:75], v[92:93], v[74:75]
	v_mov_b32_e32 v92, v56
	v_mov_b32_e32 v93, v48
	v_mov_b32_e32 v94, v76
	v_mov_b32_e32 v95, v68
	v_mov_b32_e32 v96, v48
	v_mov_b32_e32 v97, v56
	v_pk_mul_f32 v[92:93], v[92:93], v[94:95]
	v_pk_mul_f32 v[94:95], v[96:97], v[94:95]
	v_mov_b32_e32 v96, v57
	v_mov_b32_e32 v97, v49
	v_mov_b32_e32 v68, v77
	v_pk_mul_f32 v[76:77], v[96:97], v[68:69]
	v_mov_b32_e32 v96, v92
	v_mov_b32_e32 v97, v76
	v_mov_b32_e32 v76, v93
	v_mov_b32_e32 v92, v49
	v_mov_b32_e32 v93, v57
	v_pk_mul_f32 v[68:69], v[92:93], v[68:69]
	v_mov_b32_e32 v92, v94
	v_mov_b32_e32 v93, v68
	v_mov_b32_e32 v68, v95
	v_pk_add_f32 v[76:77], v[96:97], v[76:77] neg_lo:[0,1] neg_hi:[0,1]
	v_pk_add_f32 v[68:69], v[92:93], v[68:69]
	v_mov_b32_e32 v92, v58
	v_mov_b32_e32 v93, v50
	v_mov_b32_e32 v94, v78
	v_mov_b32_e32 v95, v70
	v_mov_b32_e32 v96, v50
	v_mov_b32_e32 v97, v58
	v_pk_mul_f32 v[92:93], v[92:93], v[94:95]
	v_pk_mul_f32 v[94:95], v[96:97], v[94:95]
	v_mov_b32_e32 v96, v59
	v_mov_b32_e32 v97, v51
	v_mov_b32_e32 v70, v79
	v_pk_mul_f32 v[78:79], v[96:97], v[70:71]
	v_mov_b32_e32 v96, v92
	v_mov_b32_e32 v97, v78
	v_mov_b32_e32 v78, v93
	v_mov_b32_e32 v92, v51
	v_mov_b32_e32 v93, v59
	v_pk_mul_f32 v[70:71], v[92:93], v[70:71]
	v_mov_b32_e32 v92, v94
	v_mov_b32_e32 v93, v70
	v_mov_b32_e32 v70, v95
	v_pk_add_f32 v[70:71], v[92:93], v[70:71]
	v_lshlrev_b64 v[92:93], 7, v[82:83]
	v_pk_add_f32 v[78:79], v[96:97], v[78:79] neg_lo:[0,1] neg_hi:[0,1]
	v_lshl_add_u64 v[96:97], v[162:163], 0, v[92:93]
	v_cvt_pk_bf16_f32 v92, v64, v65
	v_cvt_pk_bf16_f32 v93, v66, v67
	v_cvt_pk_bf16_f32 v94, v76, v77
	v_cvt_pk_bf16_f32 v95, v78, v79
	global_store_dwordx4 v[96:97], v[92:95], off nt
	s_nop 1
	v_cvt_pk_bf16_f32 v92, v72, v73
	v_cvt_pk_bf16_f32 v93, v74, v75
	v_cvt_pk_bf16_f32 v94, v68, v69
	v_cvt_pk_bf16_f32 v95, v70, v71
	global_store_dwordx4 v[96:97], v[92:95], off offset:64 nt
	s_nop 1
	v_lshlrev_b64 v[92:93], 8, v[88:89]
	v_lshl_add_u64 v[92:93], s[12:13], 0, v[92:93]
	v_lshl_add_u64 v[92:93], v[154:155], 2, v[92:93]
	global_store_dwordx4 v[92:93], v[64:67], off nt
	global_store_dwordx4 v[92:93], v[76:79], off offset:16 nt
	global_store_dwordx4 v[92:93], v[72:75], off offset:128 nt
	global_store_dwordx4 v[92:93], v[68:71], off offset:144 nt

;     __device__ __forceinline__ void operator()(const f32x4 (&acc)[2][2][4][2], const Unit& u, int wr, int wc, int fr, int fq) const {
;     ...
;                 } else if (pn < 12) {
;                     const int c = 256 * (pn - 10) + c8;
;                     store8_bf16(vb + (size_t)r * 512 + c, lo); store8_bf16(vb + (size_t)r * 512 + c + 128, hi);
;                     float* vo = out + (samp ? OFF_V_S : OFF_V_P) + (size_t)rl * 512 + c; store8_f32(vo, lo); store8_f32(vo + 128, hi);
.LBB0_480:
	s_andn2_b64 vcc, exec, s[12:13]
	s_cbranch_vccnz .LBB0_482
	v_ashrrev_i32_e32 v83, 31, v82
	v_readlane_b32 s12, v249, 8
	v_lshlrev_b64 v[64:65], 10, v[82:83]
	v_readlane_b32 s13, v249, 9
	v_readlane_b32 s60, v250, 0
	v_readlane_b32 s62, v250, 2
	v_lshl_add_u64 v[64:65], s[12:13], 0, v[64:65]
	v_lshl_add_u64 v[68:69], v[176:177], 1, v[64:65]
	v_cvt_pk_bf16_f32 v64, v60, v61
	v_cvt_pk_bf16_f32 v65, v62, v63
	s_lshl_b32 s12, s55, 2
	v_cvt_pk_bf16_f32 v66, v56, v57
	v_cvt_pk_bf16_f32 v67, v58, v59
	global_store_dwordx4 v[68:69], v[64:67], off nt
	v_readlane_b32 s63, v250, 3
	s_add_u32 s12, s62, s12
	v_cvt_pk_bf16_f32 v64, v52, v53
	v_cvt_pk_bf16_f32 v65, v54, v55
	v_ashrrev_i32_e32 v89, 31, v88
	v_cvt_pk_bf16_f32 v66, v48, v49
	v_cvt_pk_bf16_f32 v67, v50, v51
	global_store_dwordx4 v[68:69], v[64:67], off offset:256 nt
	s_addc_u32 s13, s63, 0
	v_readlane_b32 s61, v250, 1
	v_lshlrev_b64 v[64:65], 11, v[88:89]
	v_lshl_add_u64 v[64:65], s[12:13], 0, v[64:65]
	v_lshl_add_u64 v[64:65], v[176:177], 2, v[64:65]
	v_readlane_b32 s64, v250, 4
	v_readlane_b32 s65, v250, 5
	v_readlane_b32 s66, v250, 6
	v_readlane_b32 s67, v250, 7
	global_store_dwordx4 v[64:65], v[60:63], off nt
	global_store_dwordx4 v[64:65], v[56:59], off offset:16 nt
	global_store_dwordx4 v[64:65], v[52:55], off offset:512 nt
	global_store_dwordx4 v[64:65], v[48:51], off offset:528 nt

;     __device__ __forceinline__ void operator()(const f32x4 (&acc)[2][2][4][2], const Unit& u, int wr, int wc, int fr, int fq) const {
;     ...
;                     float cs[8], sn[8]; load8_f32(cosT + (size_t)pos * 32 + d0, cs); load8_f32(sinT + (size_t)pos * 32 + d0, sn);
;                     float ol[8], oh[8];
; #pragma unroll
;                     for (int e = 0; e < 8; ++e) { ol[e] = lo[e] * cs[e] - hi[e] * sn[e]; oh[e] = hi[e] * cs[e] + lo[e] * sn[e]; }
;                     const size_t o512 = (size_t)r * 512 + head * 64 + d0;
;                     if (pn < 8) {
; #pragma unroll
;                         for (int e = 0; e < 8; ++e) { ol[e] *= 0.18033688011112042f; oh[e] *= 0.18033688011112042f; }
;                         store8_bf16(qb + o512, ol); store8_bf16(qb + o512 + 32, oh);
;                     } else if (pn < 10) {
;                         store8_bf16(kb + o512, ol); store8_bf16(kb + o512 + 32, oh);
;                         float* ko = out + (samp ? OFF_K_S : OFF_K_P) + (size_t)rl * 512 + head * 64 + d0; store8_f32(ko, ol); store8_f32(ko + 32, oh);
;                     } else {
;                         store8_bf16(qib + o512, ol); store8_bf16(qib + o512 + 32, oh);
;                     }
.LBB0_487:
	v_lshlrev_b32_e32 v152, 7, v90
	v_lshl_add_u64 v[90:91], v[160:161], 0, v[152:153]
	global_load_dwordx4 v[76:79], v[90:91], off
	global_load_dwordx4 v[96:99], v[90:91], off offset:16
	v_lshl_add_u64 v[90:91], v[158:159], 0, v[152:153]
	global_load_dwordx4 v[100:103], v[90:91], off
	global_load_dwordx4 v[104:107], v[90:91], off offset:16
	v_ashrrev_i32_e32 v83, 31, v82
	v_lshlrev_b64 v[90:91], 9, v[82:83]
	v_lshl_add_u64 v[90:91], v[174:175], 0, v[90:91]
	s_andn2_b64 vcc, exec, s[94:95]
	s_mov_b64 s[12:13], -1
	s_waitcnt vmcnt(3)
	v_pk_mul_f32 v[108:109], v[70:71], v[76:77]
	v_pk_mul_f32 v[110:111], v[72:73], v[76:77]
	v_pk_mul_f32 v[112:113], v[68:69], v[78:79]
	v_pk_mul_f32 v[114:115], v[74:75], v[78:79]
	s_waitcnt vmcnt(2)
	v_pk_mul_f32 v[116:117], v[64:65], v[96:97]
	v_pk_mul_f32 v[96:97], v[94:95], v[96:97]
	v_pk_mul_f32 v[118:119], v[66:67], v[98:99]
	v_pk_mul_f32 v[98:99], v[92:93], v[98:99]
	s_waitcnt vmcnt(1)
	v_pk_fma_f32 v[76:77], v[72:73], v[100:101], v[108:109] neg_lo:[0,0,1] neg_hi:[0,0,1]
	v_pk_fma_f32 v[72:73], v[70:71], v[100:101], v[110:111]
	v_pk_fma_f32 v[78:79], v[74:75], v[102:103], v[112:113] neg_lo:[0,0,1] neg_hi:[0,0,1]
	v_pk_fma_f32 v[74:75], v[68:69], v[102:103], v[114:115]
	s_waitcnt vmcnt(0)
	v_pk_fma_f32 v[68:69], v[94:95], v[104:105], v[116:117] neg_lo:[0,0,1] neg_hi:[0,0,1]
	v_pk_fma_f32 v[64:65], v[64:65], v[104:105], v[96:97]
	v_pk_fma_f32 v[70:71], v[92:93], v[106:107], v[118:119] neg_lo:[0,0,1] neg_hi:[0,0,1]
	v_pk_fma_f32 v[66:67], v[66:67], v[106:107], v[98:99]
	s_cbranch_vccnz .LBB0_493
	s_andn2_b64 vcc, exec, s[2:3]
	s_cbranch_vccnz .LBB0_490
	v_readlane_b32 s12, v249, 10
	v_readlane_b32 s13, v249, 11
	v_cvt_pk_bf16_f32 v92, v76, v77
	v_cvt_pk_bf16_f32 v93, v78, v79
	v_cvt_pk_bf16_f32 v94, v68, v69
	v_cvt_pk_bf16_f32 v95, v70, v71
	s_nop 1
	v_lshl_add_u64 v[96:97], v[90:91], 1, s[12:13]
	s_mov_b64 s[12:13], 0
	global_store_dwordx4 v[96:97], v[92:95], off nt
	s_nop 1
	v_cvt_pk_bf16_f32 v92, v72, v73
	v_cvt_pk_bf16_f32 v93, v74, v75
	v_cvt_pk_bf16_f32 v94, v64, v65
	v_cvt_pk_bf16_f32 v95, v66, v67
	global_store_dwordx4 v[96:97], v[92:95], off offset:64 nt
.LBB0_490:
	s_andn2_b64 vcc, exec, s[12:13]
	s_cbranch_vccnz .LBB0_492
	v_readlane_b32 s12, v249, 6
	v_readlane_b32 s13, v249, 7
	v_readlane_b32 s60, v250, 0
	v_readlane_b32 s62, v250, 2
	v_lshl_add_u64 v[96:97], v[90:91], 1, s[12:13]
	s_lshl_b32 s12, s53, 2
	v_readlane_b32 s63, v250, 3
	s_add_u32 s12, s62, s12
	v_ashrrev_i32_e32 v89, 31, v88
	s_addc_u32 s13, s63, 0
	v_lshlrev_b64 v[88:89], 11, v[88:89]
	v_lshl_add_u64 v[88:89], s[12:13], 0, v[88:89]
	s_lshl_b32 s12, s18, 2
	s_mov_b32 s13, s19
	v_lshl_add_u64 v[88:89], v[88:89], 0, s[12:13]
	v_cvt_pk_bf16_f32 v92, v76, v77
	v_cvt_pk_bf16_f32 v93, v78, v79
	v_cvt_pk_bf16_f32 v94, v68, v69
	v_cvt_pk_bf16_f32 v95, v70, v71
	v_lshl_add_u64 v[88:89], v[154:155], 2, v[88:89]
	global_store_dwordx4 v[96:97], v[92:95], off nt
	v_readlane_b32 s61, v250, 1
	v_readlane_b32 s64, v250, 4
	v_cvt_pk_bf16_f32 v92, v72, v73
	v_cvt_pk_bf16_f32 v93, v74, v75
	v_cvt_pk_bf16_f32 v94, v64, v65
	v_cvt_pk_bf16_f32 v95, v66, v67
	global_store_dwordx4 v[96:97], v[92:95], off offset:64 nt
	v_readlane_b32 s65, v250, 5
	v_readlane_b32 s66, v250, 6
	v_readlane_b32 s67, v250, 7
	global_store_dwordx4 v[88:89], v[76:79], off nt
	global_store_dwordx4 v[88:89], v[68:71], off offset:16 nt
	global_store_dwordx4 v[88:89], v[72:75], off offset:128 nt
	global_store_dwordx4 v[88:89], v[64:67], off offset:144 nt

;     __device__ __forceinline__ void operator()(const f32x4 (&acc)[2][2][4][2], const Unit& u, int wr, int wc, int fr, int fq) const {
;     ...
;                     if (pn < 8) {
; #pragma unroll
;                         for (int e = 0; e < 8; ++e) { ol[e] *= 0.18033688011112042f; oh[e] *= 0.18033688011112042f; }
;                         store8_bf16(qb + o512, ol); store8_bf16(qb + o512 + 32, oh);
.LBB0_493:
	s_andn2_b64 vcc, exec, s[12:13]
	s_cbranch_vccnz .LBB0_495
	v_readlane_b32 s12, v249, 4
	v_readlane_b32 s13, v249, 5
	v_mul_f32_e32 v76, 0x3e38aa3b, v76
	v_mul_f32_e32 v77, 0x3e38aa3b, v77
	v_mul_f32_e32 v78, 0x3e38aa3b, v78
	v_mul_f32_e32 v79, 0x3e38aa3b, v79
	v_mul_f32_e32 v83, 0x3e38aa3b, v68
	v_mul_f32_e32 v88, 0x3e38aa3b, v64
	v_mul_f32_e32 v89, 0x3e38aa3b, v69
	v_mul_f32_e32 v92, 0x3e38aa3b, v65
	v_mul_f32_e32 v70, 0x3e38aa3b, v70
	v_mul_f32_e32 v93, 0x3e38aa3b, v66
	v_mul_f32_e32 v71, 0x3e38aa3b, v71
	v_mul_f32_e32 v94, 0x3e38aa3b, v67
	v_lshl_add_u64 v[68:69], v[90:91], 1, s[12:13]
	v_cvt_pk_bf16_f32 v64, v76, v77
	v_cvt_pk_bf16_f32 v65, v78, v79
	v_cvt_pk_bf16_f32 v66, v83, v89
	v_cvt_pk_bf16_f32 v67, v70, v71
	v_mul_f32_e32 v72, 0x3e38aa3b, v72
	v_mul_f32_e32 v73, 0x3e38aa3b, v73
	v_mul_f32_e32 v74, 0x3e38aa3b, v74
	v_mul_f32_e32 v75, 0x3e38aa3b, v75
	global_store_dwordx4 v[68:69], v[64:67], off nt
	s_nop 1
	v_cvt_pk_bf16_f32 v64, v72, v73
	v_cvt_pk_bf16_f32 v65, v74, v75
	v_cvt_pk_bf16_f32 v66, v88, v92
	v_cvt_pk_bf16_f32 v67, v93, v94
	global_store_dwordx4 v[68:69], v[64:67], off offset:64 nt

;     __device__ __forceinline__ void operator()(const f32x4 (&acc)[2][2][4][2], const Unit& u, int wr, int wc, int fr, int fq) const {
;     ...
;                     const int ch = 128 * (pn - 2) + c8; float uu[8];
; #pragma unroll
;                     for (int e = 0; e < 8; ++e) uu[e] = lo[e] * hi[e];
;                     store8_bf16(ub + (size_t)r * 512 + ch, uu);
;                     if (!samp) { const int t = rl & (SEQ - 1); if (t >= SEQ - 2) store8_f32(out + OFF_CM_P + (size_t)((rl >> 13) * 2 + (t - (SEQ - 2))) * 512 + ch, uu); }
;                     else { const int tt = rl & 7; if (tt >= 6) store8_f32(out + OFF_CM_S + (size_t)((rl >> 3) * 2 + (tt - 6)) * 512 + ch, uu); }
.LBB0_496:
	s_andn2_b64 vcc, exec, s[12:13]
	s_cbranch_vccnz .LBB0_508
	v_ashrrev_i32_e32 v83, 31, v82
	v_lshlrev_b64 v[72:73], 10, v[82:83]
	v_lshl_add_u64 v[72:73], s[88:89], 0, v[72:73]
	v_pk_mul_f32 v[68:69], v[60:61], v[52:53]
	v_pk_mul_f32 v[70:71], v[62:63], v[54:55]
	v_pk_mul_f32 v[64:65], v[56:57], v[48:49]
	v_pk_mul_f32 v[66:67], v[58:59], v[50:51]
	v_lshl_add_u64 v[76:77], v[172:173], 1, v[72:73]
	s_andn2_b64 vcc, exec, s[84:85]
	v_cvt_pk_bf16_f32 v72, v68, v69
	v_cvt_pk_bf16_f32 v73, v70, v71
	v_cvt_pk_bf16_f32 v74, v64, v65
	v_cvt_pk_bf16_f32 v75, v66, v67
	global_store_dwordx4 v[76:77], v[72:75], off nt
	s_cbranch_vccnz .LBB0_501
	s_movk_i32 s12, 0x1ffd
	v_cmp_lt_u32_e32 vcc, s12, v87
	s_mov_b64 s[26:27], 0
	s_mov_b64 s[12:13], 0
	s_and_saveexec_b64 s[28:29], vcc
	s_ashr_i32 s12, s58, 12
	s_and_b32 s12, s12, -2
	s_addk_i32 s12, 0xe002
	v_add_u32_e32 v72, s12, v87
	s_mov_b64 s[12:13], exec
	s_or_b64 exec, exec, s[28:29]
	s_mov_b64 s[28:29], 0x8800000
	s_and_b64 vcc, exec, s[26:27]
	s_cbranch_vccnz .LBB0_502
	s_branch .LBB0_505

;     __device__ __forceinline__ void operator()(const f32x4 (&acc)[2][2][4][2], const Unit& u, int wr, int wc, int fr, int fq) const {
;     ...
;                     if (!samp) { const int t = rl & (SEQ - 1); if (t >= SEQ - 2) store8_f32(out + OFF_CM_P + (size_t)((rl >> 13) * 2 + (t - (SEQ - 2))) * 512 + ch, uu); }
;                     else { const int tt = rl & 7; if (tt >= 6) store8_f32(out + OFF_CM_S + (size_t)((rl >> 3) * 2 + (tt - 6)) * 512 + ch, uu); }
.LBB0_505:
	s_and_saveexec_b64 s[26:27], s[12:13]
	s_cbranch_execz .LBB0_507
	v_readlane_b32 s60, v250, 0
	v_readlane_b32 s62, v250, 2
	v_readlane_b32 s63, v250, 3
	s_add_u32 s12, s62, s28
	v_ashrrev_i32_e32 v73, 31, v72
	s_addc_u32 s13, s63, s29
	v_lshlrev_b64 v[72:73], 11, v[72:73]
	v_lshl_add_u64 v[72:73], s[12:13], 0, v[72:73]
	v_lshl_add_u64 v[72:73], v[172:173], 2, v[72:73]
	v_readlane_b32 s61, v250, 1
	v_readlane_b32 s64, v250, 4
	v_readlane_b32 s65, v250, 5
	v_readlane_b32 s66, v250, 6
	v_readlane_b32 s67, v250, 7
	global_store_dwordx4 v[72:73], v[68:71], off nt
	global_store_dwordx4 v[72:73], v[64:67], off offset:16 nt

; #define EPI_GET(dst, ai, bj, m, s) do { _Pragma("unroll") for (int e_ = 0; e_ < 4; ++e_) { (dst)[e_] = acc[ai][bj][m][0][e_] * (s); (dst)[4 + e_] = acc[ai][bj][m][1][e_] * (s); } } while (0)
;     __device__ __forceinline__ void operator()(const f32x4 (&acc)[2][2][4][2], const Unit& u, int wr, int wc, int fr, int fq) const {
;     ...
;             for (int m = 0; m < 4; ++m) {
;                 const int r = EPI_ROWS(ai, m); const float rs = rsa[m];
;                 float lo[8], hi[8]; EPI_GET(lo, ai, 0, m, rs); EPI_GET(hi, ai, 1, m, rs);
;                 const int rl = samp ? r - MP : r; const int pos = samp ? PAST + (rl & 7) : (rl & (SEQ - 1));
;                 if (pn < 2) {
;                     store8_bf16(cbb + (size_t)r * 512 + pn * 256 + c8, lo); store8_bf16(cbb + (size_t)r * 512 + pn * 256 + 128 + c8, hi);
;                 } else if (pn < 6) {
;                     const int ch = 128 * (pn - 2) + c8; float uu[8];
; #pragma unroll
;                     for (int e = 0; e < 8; ++e) uu[e] = lo[e] * hi[e];
;                     store8_bf16(ub + (size_t)r * 512 + ch, uu);
;                     if (!samp) { const int t = rl & (SEQ - 1); if (t >= SEQ - 2) store8_f32(out + OFF_CM_P + (size_t)((rl >> 13) * 2 + (t - (SEQ - 2))) * 512 + ch, uu); }
;                     else { const int tt = rl & 7; if (tt >= 6) store8_f32(out + OFF_CM_S + (size_t)((rl >> 3) * 2 + (tt - 6)) * 512 + ch, uu); }
;                 } else if (pn < 10 || pn == 12 || pn == 13) {
;     ...
;                     } else if (wc == 1 && fq == 0) {
;                         store8_f32(iwf + (size_t)r * 8, lo);
.LBB0_509:
	s_andn2_b64 vcc, exec, s[12:13]
	s_cbranch_vccnz .LBB0_511
	v_ashrrev_i32_e32 v83, 31, v82
	v_lshlrev_b64 v[64:65], 10, v[82:83]
	v_lshl_add_u64 v[64:65], s[22:23], 0, v[64:65]
	v_lshl_add_u64 v[64:65], s[56:57], 1, v[64:65]
	v_lshl_add_u64 v[64:65], v[156:157], 1, v[64:65]
	v_cvt_pk_bf16_f32 v60, v60, v61
	v_cvt_pk_bf16_f32 v61, v62, v63
	v_cvt_pk_bf16_f32 v62, v56, v57
	v_cvt_pk_bf16_f32 v63, v58, v59
	global_store_dwordx4 v[64:65], v[60:63], off nt
	v_cvt_pk_bf16_f32 v52, v52, v53
	v_cvt_pk_bf16_f32 v53, v54, v55
	v_cvt_pk_bf16_f32 v54, v48, v49
	v_cvt_pk_bf16_f32 v55, v50, v51
	global_store_dwordx4 v[64:65], v[52:55], off offset:256 nt
.LBB0_511:
	s_waitcnt vmcnt(2)
	v_pk_mul_f32 v[44:45], v[44:45], v[86:87] op_sel_hi:[1,0]
	v_pk_mul_f32 v[36:37], v[36:37], v[86:87] op_sel_hi:[1,0]
	v_pk_mul_f32 v[40:41], v[40:41], v[86:87] op_sel_hi:[1,0]
	v_pk_mul_f32 v[32:33], v[32:33], v[86:87] op_sel_hi:[1,0]
	v_pk_mul_f32 v[46:47], v[46:47], v[86:87] op_sel_hi:[1,0]
	v_pk_mul_f32 v[38:39], v[38:39], v[86:87] op_sel_hi:[1,0]
	v_pk_mul_f32 v[42:43], v[42:43], v[86:87] op_sel_hi:[1,0]
	v_pk_mul_f32 v[34:35], v[34:35], v[86:87] op_sel_hi:[1,0]
	v_or_b32_e32 v64, 16, v82
	s_and_b64 vcc, exec, s[10:11]
	s_mov_b64 s[12:13], -1
	s_cbranch_vccnz .LBB0_550
	v_add_u32_e32 v74, 0xffffc010, v82
	v_cndmask_b32_e64 v66, v64, v74, s[6:7]
	v_and_b32_e32 v75, 7, v66
	v_and_b32_e32 v76, 0x1fff, v66
	s_and_b64 vcc, exec, s[8:9]
	s_cbranch_vccnz .LBB0_537
	v_or_b32_e32 v48, 0x800, v75
	v_cndmask_b32_e64 v68, v76, v48, s[6:7]
	s_andn2_b64 vcc, exec, s[20:21]
	s_cbranch_vccnz .LBB0_524
	s_andn2_b64 vcc, exec, s[16:17]
	s_cbranch_vccnz .LBB0_521
	v_readlane_b32 s12, v249, 14
	v_readlane_b32 s13, v249, 15
	s_andn2_b64 vcc, exec, s[12:13]
	s_cbranch_vccnz .LBB0_642
	s_mov_b64 s[12:13], exec
	v_readlane_b32 s26, v249, 16
	v_readlane_b32 s27, v249, 17
	s_and_b64 s[26:27], s[12:13], s[26:27]
	s_mov_b64 exec, s[26:27]
	s_cbranch_execz .LBB0_518
	v_ashrrev_i32_e32 v65, 31, v64
	v_readlane_b32 s26, v249, 12
	v_lshlrev_b64 v[48:49], 5, v[64:65]
	v_readlane_b32 s27, v249, 13
	s_nop 1
	v_lshl_add_u64 v[48:49], s[26:27], 0, v[48:49]
	global_store_dwordx4 v[48:49], v[44:47], off nt
	global_store_dwordx4 v[48:49], v[40:43], off offset:16 nt

;     __device__ __forceinline__ void operator()(const f32x4 (&acc)[2][2][4][2], const Unit& u, int wr, int wc, int fr, int fq) const {
;     ...
;                     if (wc == 0) {
;                         const int d0 = 8 * fq; float cs[8], sn[8]; load8_f32(cosT + (size_t)pos * 32 + d0, cs); load8_f32(sinT + (size_t)pos * 32 + d0, sn);
;                         float ol[8], oh[8];
; #pragma unroll
;                         for (int e = 0; e < 8; ++e) { ol[e] = lo[e] * cs[e] - hi[e] * sn[e]; oh[e] = hi[e] * cs[e] + lo[e] * sn[e]; }
;                         store8_bf16(kib + (size_t)r * 64 + d0, ol); store8_bf16(kib + (size_t)r * 64 + 32 + d0, oh);
;                         float* io = out + (samp ? OFF_IK_S : OFF_IK_P) + (size_t)rl * 64 + d0; store8_f32(io, ol); store8_f32(io + 32, oh);
.LBB0_519:
	v_lshlrev_b32_e32 v152, 7, v68
	v_lshl_add_u64 v[48:49], v[158:159], 0, v[152:153]
	v_lshl_add_u64 v[56:57], v[160:161], 0, v[152:153]
	global_load_dwordx4 v[60:63], v[48:49], off offset:16
	s_nop 0
	global_load_dwordx4 v[48:51], v[48:49], off
	s_nop 0
	global_load_dwordx4 v[52:55], v[56:57], off offset:16
	s_nop 0
	global_load_dwordx4 v[56:59], v[56:57], off
	v_mov_b32_e32 v70, v44
	v_mov_b32_e32 v71, v36
	v_mov_b32_e32 v78, v36
	v_mov_b32_e32 v79, v44
	v_ashrrev_i32_e32 v65, 31, v64
	v_readlane_b32 s60, v250, 0
	s_lshl_b32 s12, s69, 2
	v_readlane_b32 s62, v250, 2
	v_readlane_b32 s63, v250, 3
	s_add_u32 s12, s62, s12
	v_ashrrev_i32_e32 v67, 31, v66
	s_addc_u32 s13, s63, 0
	v_readlane_b32 s61, v250, 1
	v_readlane_b32 s64, v250, 4
	v_readlane_b32 s65, v250, 5
	v_readlane_b32 s66, v250, 6
	v_readlane_b32 s67, v250, 7
	s_waitcnt vmcnt(2)
	v_mov_b32_e32 v72, v48
	s_waitcnt vmcnt(0)
	v_mov_b32_e32 v73, v56
	v_pk_mul_f32 v[70:71], v[70:71], v[72:73]
	v_pk_mul_f32 v[72:73], v[78:79], v[72:73]
	v_mov_b32_e32 v78, v45
	v_mov_b32_e32 v79, v37
	v_mov_b32_e32 v56, v49
	v_pk_mul_f32 v[48:49], v[78:79], v[56:57]
	v_mov_b32_e32 v78, v70
	v_mov_b32_e32 v79, v48
	v_mov_b32_e32 v48, v71
	v_mov_b32_e32 v70, v37
	v_mov_b32_e32 v71, v45
	v_pk_mul_f32 v[56:57], v[70:71], v[56:57]
	v_mov_b32_e32 v70, v72
	v_mov_b32_e32 v71, v56
	v_mov_b32_e32 v56, v73
	v_pk_add_f32 v[48:49], v[78:79], v[48:49] neg_lo:[0,1] neg_hi:[0,1]
	v_pk_add_f32 v[56:57], v[70:71], v[56:57]
	v_mov_b32_e32 v70, v46
	v_mov_b32_e32 v71, v38
	v_mov_b32_e32 v72, v50
	v_mov_b32_e32 v73, v58
	v_mov_b32_e32 v78, v38
	v_mov_b32_e32 v79, v46
	v_pk_mul_f32 v[70:71], v[70:71], v[72:73]
	v_pk_mul_f32 v[72:73], v[78:79], v[72:73]
	v_mov_b32_e32 v78, v47
	v_mov_b32_e32 v79, v39
	v_mov_b32_e32 v58, v51
	v_pk_mul_f32 v[50:51], v[78:79], v[58:59]
	v_mov_b32_e32 v78, v70
	v_mov_b32_e32 v79, v50
	v_mov_b32_e32 v50, v71
	v_mov_b32_e32 v70, v39
	v_mov_b32_e32 v71, v47
	v_pk_mul_f32 v[58:59], v[70:71], v[58:59]
	v_mov_b32_e32 v70, v72
	v_mov_b32_e32 v71, v58
	v_mov_b32_e32 v58, v73
	v_pk_add_f32 v[50:51], v[78:79], v[50:51] neg_lo:[0,1] neg_hi:[0,1]
	v_pk_add_f32 v[58:59], v[70:71], v[58:59]
	v_mov_b32_e32 v70, v40
	v_mov_b32_e32 v71, v32
	v_mov_b32_e32 v72, v60
	v_mov_b32_e32 v73, v52
	v_mov_b32_e32 v78, v32
	v_mov_b32_e32 v79, v40
	v_pk_mul_f32 v[70:71], v[70:71], v[72:73]
	v_pk_mul_f32 v[72:73], v[78:79], v[72:73]
	v_mov_b32_e32 v78, v41
	v_mov_b32_e32 v79, v33
	v_mov_b32_e32 v52, v61
	v_pk_mul_f32 v[60:61], v[78:79], v[52:53]
	v_mov_b32_e32 v78, v70
	v_mov_b32_e32 v79, v60
	v_mov_b32_e32 v60, v71
	v_mov_b32_e32 v70, v33
	v_mov_b32_e32 v71, v41
	v_pk_mul_f32 v[52:53], v[70:71], v[52:53]
	v_mov_b32_e32 v70, v72
	v_mov_b32_e32 v71, v52
	v_mov_b32_e32 v52, v73
	v_pk_add_f32 v[60:61], v[78:79], v[60:61] neg_lo:[0,1] neg_hi:[0,1]
	v_pk_add_f32 v[52:53], v[70:71], v[52:53]
	v_mov_b32_e32 v70, v42
	v_mov_b32_e32 v71, v34
	v_mov_b32_e32 v72, v62
	v_mov_b32_e32 v73, v54
	v_mov_b32_e32 v78, v34
	v_mov_b32_e32 v79, v42
	v_pk_mul_f32 v[70:71], v[70:71], v[72:73]
	v_pk_mul_f32 v[72:73], v[78:79], v[72:73]
	v_mov_b32_e32 v78, v43
	v_mov_b32_e32 v79, v35
	v_mov_b32_e32 v54, v63
	v_pk_mul_f32 v[62:63], v[78:79], v[54:55]
	v_mov_b32_e32 v78, v70
	v_mov_b32_e32 v79, v62
	v_mov_b32_e32 v62, v71
	v_mov_b32_e32 v70, v35
	v_mov_b32_e32 v71, v43
	v_pk_mul_f32 v[54:55], v[70:71], v[54:55]
	v_mov_b32_e32 v70, v72
	v_mov_b32_e32 v71, v54
	v_mov_b32_e32 v54, v73
	v_pk_add_f32 v[54:55], v[70:71], v[54:55]
	v_lshlrev_b64 v[70:71], 7, v[64:65]
	v_pk_add_f32 v[62:63], v[78:79], v[62:63] neg_lo:[0,1] neg_hi:[0,1]
	v_lshl_add_u64 v[78:79], v[162:163], 0, v[70:71]
	v_cvt_pk_bf16_f32 v70, v48, v49
	v_cvt_pk_bf16_f32 v71, v50, v51
	v_cvt_pk_bf16_f32 v72, v60, v61
	v_cvt_pk_bf16_f32 v73, v62, v63
	global_store_dwordx4 v[78:79], v[70:73], off nt
	s_nop 1
	v_cvt_pk_bf16_f32 v70, v56, v57
	v_cvt_pk_bf16_f32 v71, v58, v59
	v_cvt_pk_bf16_f32 v72, v52, v53
	v_cvt_pk_bf16_f32 v73, v54, v55
	global_store_dwordx4 v[78:79], v[70:73], off offset:64 nt
	s_nop 1
	v_lshlrev_b64 v[70:71], 8, v[66:67]
	v_lshl_add_u64 v[70:71], s[12:13], 0, v[70:71]
	v_lshl_add_u64 v[70:71], v[154:155], 2, v[70:71]
	global_store_dwordx4 v[70:71], v[48:51], off nt
	global_store_dwordx4 v[70:71], v[60:63], off offset:16 nt
	global_store_dwordx4 v[70:71], v[56:59], off offset:128 nt
	global_store_dwordx4 v[70:71], v[52:55], off offset:144 nt

;     __device__ __forceinline__ void operator()(const f32x4 (&acc)[2][2][4][2], const Unit& u, int wr, int wc, int fr, int fq) const {
;     ...
;                 } else if (pn < 12) {
;                     const int c = 256 * (pn - 10) + c8;
;                     store8_bf16(vb + (size_t)r * 512 + c, lo); store8_bf16(vb + (size_t)r * 512 + c + 128, hi);
;                     float* vo = out + (samp ? OFF_V_S : OFF_V_P) + (size_t)rl * 512 + c; store8_f32(vo, lo); store8_f32(vo + 128, hi);
.LBB0_521:
	s_andn2_b64 vcc, exec, s[12:13]
	s_cbranch_vccnz .LBB0_523
	v_ashrrev_i32_e32 v65, 31, v64
	v_readlane_b32 s12, v249, 8
	v_lshlrev_b64 v[48:49], 10, v[64:65]
	v_readlane_b32 s13, v249, 9
	v_readlane_b32 s60, v250, 0
	v_readlane_b32 s62, v250, 2
	v_lshl_add_u64 v[48:49], s[12:13], 0, v[48:49]
	v_lshl_add_u64 v[52:53], v[176:177], 1, v[48:49]
	v_cvt_pk_bf16_f32 v48, v44, v45
	v_cvt_pk_bf16_f32 v49, v46, v47
	s_lshl_b32 s12, s55, 2
	v_cvt_pk_bf16_f32 v50, v40, v41
	v_cvt_pk_bf16_f32 v51, v42, v43
	global_store_dwordx4 v[52:53], v[48:51], off nt
	v_readlane_b32 s63, v250, 3
	s_add_u32 s12, s62, s12
	v_cvt_pk_bf16_f32 v48, v36, v37
	v_cvt_pk_bf16_f32 v49, v38, v39
	v_ashrrev_i32_e32 v67, 31, v66
	v_cvt_pk_bf16_f32 v50, v32, v33
	v_cvt_pk_bf16_f32 v51, v34, v35
	global_store_dwordx4 v[52:53], v[48:51], off offset:256 nt
	s_addc_u32 s13, s63, 0
	v_readlane_b32 s61, v250, 1
	v_lshlrev_b64 v[48:49], 11, v[66:67]
	v_lshl_add_u64 v[48:49], s[12:13], 0, v[48:49]
	v_lshl_add_u64 v[48:49], v[176:177], 2, v[48:49]
	v_readlane_b32 s64, v250, 4
	v_readlane_b32 s65, v250, 5
	v_readlane_b32 s66, v250, 6
	v_readlane_b32 s67, v250, 7
	global_store_dwordx4 v[48:49], v[44:47], off nt
	global_store_dwordx4 v[48:49], v[40:43], off offset:16 nt
	global_store_dwordx4 v[48:49], v[36:39], off offset:512 nt
	global_store_dwordx4 v[48:49], v[32:35], off offset:528 nt

;     __device__ __forceinline__ void operator()(const f32x4 (&acc)[2][2][4][2], const Unit& u, int wr, int wc, int fr, int fq) const {
;     ...
;                     float cs[8], sn[8]; load8_f32(cosT + (size_t)pos * 32 + d0, cs); load8_f32(sinT + (size_t)pos * 32 + d0, sn);
;                     float ol[8], oh[8];
; #pragma unroll
;                     for (int e = 0; e < 8; ++e) { ol[e] = lo[e] * cs[e] - hi[e] * sn[e]; oh[e] = hi[e] * cs[e] + lo[e] * sn[e]; }
;                     const size_t o512 = (size_t)r * 512 + head * 64 + d0;
;                     if (pn < 8) {
; #pragma unroll
;                         for (int e = 0; e < 8; ++e) { ol[e] *= 0.18033688011112042f; oh[e] *= 0.18033688011112042f; }
;                         store8_bf16(qb + o512, ol); store8_bf16(qb + o512 + 32, oh);
;                     } else if (pn < 10) {
;                         store8_bf16(kb + o512, ol); store8_bf16(kb + o512 + 32, oh);
;                         float* ko = out + (samp ? OFF_K_S : OFF_K_P) + (size_t)rl * 512 + head * 64 + d0; store8_f32(ko, ol); store8_f32(ko + 32, oh);
;                     } else {
;                         store8_bf16(qib + o512, ol); store8_bf16(qib + o512 + 32, oh);
;                     }
.LBB0_528:
	v_lshlrev_b32_e32 v152, 7, v68
	v_lshl_add_u64 v[68:69], v[160:161], 0, v[152:153]
	global_load_dwordx4 v[60:63], v[68:69], off
	global_load_dwordx4 v[86:89], v[68:69], off offset:16
	v_lshl_add_u64 v[68:69], v[158:159], 0, v[152:153]
	global_load_dwordx4 v[90:93], v[68:69], off
	global_load_dwordx4 v[94:97], v[68:69], off offset:16
	v_ashrrev_i32_e32 v65, 31, v64
	v_lshlrev_b64 v[68:69], 9, v[64:65]
	v_lshl_add_u64 v[68:69], v[68:69], 0, v[174:175]
	s_andn2_b64 vcc, exec, s[94:95]
	s_mov_b64 s[12:13], -1
	s_waitcnt vmcnt(3)
	v_pk_mul_f32 v[78:79], v[54:55], v[60:61]
	v_pk_mul_f32 v[98:99], v[56:57], v[60:61]
	v_pk_mul_f32 v[100:101], v[52:53], v[62:63]
	v_pk_mul_f32 v[102:103], v[58:59], v[62:63]
	s_waitcnt vmcnt(2)
	v_pk_mul_f32 v[104:105], v[48:49], v[86:87]
	v_pk_mul_f32 v[86:87], v[72:73], v[86:87]
	v_pk_mul_f32 v[106:107], v[50:51], v[88:89]
	v_pk_mul_f32 v[88:89], v[70:71], v[88:89]
	s_waitcnt vmcnt(1)
	v_pk_fma_f32 v[60:61], v[56:57], v[90:91], v[78:79] neg_lo:[0,0,1] neg_hi:[0,0,1]
	v_pk_fma_f32 v[56:57], v[54:55], v[90:91], v[98:99]
	v_pk_fma_f32 v[62:63], v[58:59], v[92:93], v[100:101] neg_lo:[0,0,1] neg_hi:[0,0,1]
	v_pk_fma_f32 v[58:59], v[52:53], v[92:93], v[102:103]
	s_waitcnt vmcnt(0)
	v_pk_fma_f32 v[52:53], v[72:73], v[94:95], v[104:105] neg_lo:[0,0,1] neg_hi:[0,0,1]
	v_pk_fma_f32 v[48:49], v[48:49], v[94:95], v[86:87]
	v_pk_fma_f32 v[54:55], v[70:71], v[96:97], v[106:107] neg_lo:[0,0,1] neg_hi:[0,0,1]
	v_pk_fma_f32 v[50:51], v[50:51], v[96:97], v[88:89]
	s_cbranch_vccnz .LBB0_534
	s_andn2_b64 vcc, exec, s[2:3]
	s_cbranch_vccnz .LBB0_531
	v_readlane_b32 s12, v249, 10
	v_readlane_b32 s13, v249, 11
	v_cvt_pk_bf16_f32 v70, v60, v61
	v_cvt_pk_bf16_f32 v71, v62, v63
	v_cvt_pk_bf16_f32 v72, v52, v53
	v_cvt_pk_bf16_f32 v73, v54, v55
	s_nop 1
	v_lshl_add_u64 v[78:79], v[68:69], 1, s[12:13]
	s_mov_b64 s[12:13], 0
	global_store_dwordx4 v[78:79], v[70:73], off nt
	s_nop 1
	v_cvt_pk_bf16_f32 v70, v56, v57
	v_cvt_pk_bf16_f32 v71, v58, v59
	v_cvt_pk_bf16_f32 v72, v48, v49
	v_cvt_pk_bf16_f32 v73, v50, v51
	global_store_dwordx4 v[78:79], v[70:73], off offset:64 nt
.LBB0_531:
	s_andn2_b64 vcc, exec, s[12:13]
	s_cbranch_vccnz .LBB0_533
	v_readlane_b32 s12, v249, 6
	v_readlane_b32 s13, v249, 7
	v_readlane_b32 s60, v250, 0
	v_readlane_b32 s62, v250, 2
	v_lshl_add_u64 v[78:79], v[68:69], 1, s[12:13]
	s_lshl_b32 s12, s53, 2
	v_readlane_b32 s63, v250, 3
	s_add_u32 s12, s62, s12
	v_ashrrev_i32_e32 v67, 31, v66
	s_addc_u32 s13, s63, 0
	v_lshlrev_b64 v[66:67], 11, v[66:67]
	v_lshl_add_u64 v[66:67], s[12:13], 0, v[66:67]
	s_lshl_b32 s12, s18, 2
	s_mov_b32 s13, s19
	v_lshl_add_u64 v[66:67], v[66:67], 0, s[12:13]
	v_cvt_pk_bf16_f32 v70, v60, v61
	v_cvt_pk_bf16_f32 v71, v62, v63
	v_cvt_pk_bf16_f32 v72, v52, v53
	v_cvt_pk_bf16_f32 v73, v54, v55
	v_lshl_add_u64 v[66:67], v[154:155], 2, v[66:67]
	global_store_dwordx4 v[78:79], v[70:73], off nt
	v_readlane_b32 s61, v250, 1
	v_readlane_b32 s64, v250, 4
	v_cvt_pk_bf16_f32 v70, v56, v57
	v_cvt_pk_bf16_f32 v71, v58, v59
	v_cvt_pk_bf16_f32 v72, v48, v49
	v_cvt_pk_bf16_f32 v73, v50, v51
	global_store_dwordx4 v[78:79], v[70:73], off offset:64 nt
	v_readlane_b32 s65, v250, 5
	v_readlane_b32 s66, v250, 6
	v_readlane_b32 s67, v250, 7
	global_store_dwordx4 v[66:67], v[60:63], off nt
	global_store_dwordx4 v[66:67], v[52:55], off offset:16 nt
	global_store_dwordx4 v[66:67], v[56:59], off offset:128 nt
	global_store_dwordx4 v[66:67], v[48:51], off offset:144 nt

;     __device__ __forceinline__ void operator()(const f32x4 (&acc)[2][2][4][2], const Unit& u, int wr, int wc, int fr, int fq) const {
;     ...
;                     if (pn < 8) {
; #pragma unroll
;                         for (int e = 0; e < 8; ++e) { ol[e] *= 0.18033688011112042f; oh[e] *= 0.18033688011112042f; }
;                         store8_bf16(qb + o512, ol); store8_bf16(qb + o512 + 32, oh);
.LBB0_534:
	s_andn2_b64 vcc, exec, s[12:13]
	s_cbranch_vccnz .LBB0_536
	v_readlane_b32 s12, v249, 4
	v_readlane_b32 s13, v249, 5
	v_mul_f32_e32 v60, 0x3e38aa3b, v60
	v_mul_f32_e32 v61, 0x3e38aa3b, v61
	v_mul_f32_e32 v62, 0x3e38aa3b, v62
	v_mul_f32_e32 v63, 0x3e38aa3b, v63
	v_mul_f32_e32 v65, 0x3e38aa3b, v52
	v_mul_f32_e32 v66, 0x3e38aa3b, v48
	v_mul_f32_e32 v67, 0x3e38aa3b, v53
	v_mul_f32_e32 v70, 0x3e38aa3b, v49
	v_mul_f32_e32 v54, 0x3e38aa3b, v54
	v_mul_f32_e32 v71, 0x3e38aa3b, v50
	v_mul_f32_e32 v55, 0x3e38aa3b, v55
	v_mul_f32_e32 v72, 0x3e38aa3b, v51
	v_lshl_add_u64 v[52:53], v[68:69], 1, s[12:13]
	v_cvt_pk_bf16_f32 v48, v60, v61
	v_cvt_pk_bf16_f32 v49, v62, v63
	v_cvt_pk_bf16_f32 v50, v65, v67
	v_cvt_pk_bf16_f32 v51, v54, v55
	v_mul_f32_e32 v56, 0x3e38aa3b, v56
	v_mul_f32_e32 v57, 0x3e38aa3b, v57
	v_mul_f32_e32 v58, 0x3e38aa3b, v58
	v_mul_f32_e32 v59, 0x3e38aa3b, v59
	global_store_dwordx4 v[52:53], v[48:51], off nt
	s_nop 1
	v_cvt_pk_bf16_f32 v48, v56, v57
	v_cvt_pk_bf16_f32 v49, v58, v59
	v_cvt_pk_bf16_f32 v50, v66, v70
	v_cvt_pk_bf16_f32 v51, v71, v72
	global_store_dwordx4 v[52:53], v[48:51], off offset:64 nt

;     __device__ __forceinline__ void operator()(const f32x4 (&acc)[2][2][4][2], const Unit& u, int wr, int wc, int fr, int fq) const {
;     ...
;                     const int ch = 128 * (pn - 2) + c8; float uu[8];
; #pragma unroll
;                     for (int e = 0; e < 8; ++e) uu[e] = lo[e] * hi[e];
;                     store8_bf16(ub + (size_t)r * 512 + ch, uu);
;                     if (!samp) { const int t = rl & (SEQ - 1); if (t >= SEQ - 2) store8_f32(out + OFF_CM_P + (size_t)((rl >> 13) * 2 + (t - (SEQ - 2))) * 512 + ch, uu); }
;                     else { const int tt = rl & 7; if (tt >= 6) store8_f32(out + OFF_CM_S + (size_t)((rl >> 3) * 2 + (tt - 6)) * 512 + ch, uu); }
.LBB0_537:
	s_andn2_b64 vcc, exec, s[12:13]
	s_cbranch_vccnz .LBB0_549
	v_ashrrev_i32_e32 v65, 31, v64
	v_lshlrev_b64 v[56:57], 10, v[64:65]
	v_lshl_add_u64 v[56:57], s[88:89], 0, v[56:57]
	v_pk_mul_f32 v[52:53], v[44:45], v[36:37]
	v_pk_mul_f32 v[54:55], v[46:47], v[38:39]
	v_pk_mul_f32 v[48:49], v[40:41], v[32:33]
	v_pk_mul_f32 v[50:51], v[42:43], v[34:35]
	v_lshl_add_u64 v[60:61], v[172:173], 1, v[56:57]
	s_andn2_b64 vcc, exec, s[84:85]
	v_cvt_pk_bf16_f32 v56, v52, v53
	v_cvt_pk_bf16_f32 v57, v54, v55
	v_cvt_pk_bf16_f32 v58, v48, v49
	v_cvt_pk_bf16_f32 v59, v50, v51
	global_store_dwordx4 v[60:61], v[56:59], off nt
	s_cbranch_vccnz .LBB0_542
	s_movk_i32 s12, 0x1ffd
	v_cmp_lt_u32_e32 vcc, s12, v76
	s_mov_b64 s[26:27], 0
	s_mov_b64 s[12:13], 0
	s_and_saveexec_b64 s[28:29], vcc
	s_ashr_i32 s12, s58, 12
	s_and_b32 s12, s12, -2
	s_addk_i32 s12, 0xe002
	v_add_u32_e32 v56, s12, v76
	s_mov_b64 s[12:13], exec
	s_or_b64 exec, exec, s[28:29]
	s_mov_b64 s[28:29], 0x8800000
	s_and_b64 vcc, exec, s[26:27]
	s_cbranch_vccnz .LBB0_543
	s_branch .LBB0_546

;     __device__ __forceinline__ void operator()(const f32x4 (&acc)[2][2][4][2], const Unit& u, int wr, int wc, int fr, int fq) const {
;     ...
;                     if (!samp) { const int t = rl & (SEQ - 1); if (t >= SEQ - 2) store8_f32(out + OFF_CM_P + (size_t)((rl >> 13) * 2 + (t - (SEQ - 2))) * 512 + ch, uu); }
;                     else { const int tt = rl & 7; if (tt >= 6) store8_f32(out + OFF_CM_S + (size_t)((rl >> 3) * 2 + (tt - 6)) * 512 + ch, uu); }
.LBB0_546:
	s_and_saveexec_b64 s[26:27], s[12:13]
	s_cbranch_execz .LBB0_548
	v_readlane_b32 s60, v250, 0
	v_readlane_b32 s62, v250, 2
	v_readlane_b32 s63, v250, 3
	s_add_u32 s12, s62, s28
	v_ashrrev_i32_e32 v57, 31, v56
	s_addc_u32 s13, s63, s29
	v_lshlrev_b64 v[56:57], 11, v[56:57]
	v_lshl_add_u64 v[56:57], s[12:13], 0, v[56:57]
	v_lshl_add_u64 v[56:57], v[172:173], 2, v[56:57]
	v_readlane_b32 s61, v250, 1
	v_readlane_b32 s64, v250, 4
	v_readlane_b32 s65, v250, 5
	v_readlane_b32 s66, v250, 6
	v_readlane_b32 s67, v250, 7
	global_store_dwordx4 v[56:57], v[52:55], off nt
	global_store_dwordx4 v[56:57], v[48:51], off offset:16 nt

; #define EPI_GET(dst, ai, bj, m, s) do { _Pragma("unroll") for (int e_ = 0; e_ < 4; ++e_) { (dst)[e_] = acc[ai][bj][m][0][e_] * (s); (dst)[4 + e_] = acc[ai][bj][m][1][e_] * (s); } } while (0)
;     __device__ __forceinline__ void operator()(const f32x4 (&acc)[2][2][4][2], const Unit& u, int wr, int wc, int fr, int fq) const {
;     ...
;             for (int m = 0; m < 4; ++m) {
;                 const int r = EPI_ROWS(ai, m); const float rs = rsa[m];
;                 float lo[8], hi[8]; EPI_GET(lo, ai, 0, m, rs); EPI_GET(hi, ai, 1, m, rs);
;                 const int rl = samp ? r - MP : r; const int pos = samp ? PAST + (rl & 7) : (rl & (SEQ - 1));
;                 if (pn < 2) {
;                     store8_bf16(cbb + (size_t)r * 512 + pn * 256 + c8, lo); store8_bf16(cbb + (size_t)r * 512 + pn * 256 + 128 + c8, hi);
;                 } else if (pn < 6) {
;                     const int ch = 128 * (pn - 2) + c8; float uu[8];
; #pragma unroll
;                     for (int e = 0; e < 8; ++e) uu[e] = lo[e] * hi[e];
;                     store8_bf16(ub + (size_t)r * 512 + ch, uu);
;                     if (!samp) { const int t = rl & (SEQ - 1); if (t >= SEQ - 2) store8_f32(out + OFF_CM_P + (size_t)((rl >> 13) * 2 + (t - (SEQ - 2))) * 512 + ch, uu); }
;                     else { const int tt = rl & 7; if (tt >= 6) store8_f32(out + OFF_CM_S + (size_t)((rl >> 3) * 2 + (tt - 6)) * 512 + ch, uu); }
;                 } else if (pn < 10 || pn == 12 || pn == 13) {
;     ...
;                     } else if (wc == 1 && fq == 0) {
;                         store8_f32(iwf + (size_t)r * 8, lo);
.LBB0_550:
	s_andn2_b64 vcc, exec, s[12:13]
	s_cbranch_vccnz .LBB0_552
	v_ashrrev_i32_e32 v65, 31, v64
	v_lshlrev_b64 v[48:49], 10, v[64:65]
	v_lshl_add_u64 v[48:49], s[22:23], 0, v[48:49]
	v_lshl_add_u64 v[48:49], s[56:57], 1, v[48:49]
	v_lshl_add_u64 v[48:49], v[156:157], 1, v[48:49]
	v_cvt_pk_bf16_f32 v44, v44, v45
	v_cvt_pk_bf16_f32 v45, v46, v47
	v_cvt_pk_bf16_f32 v46, v40, v41
	v_cvt_pk_bf16_f32 v47, v42, v43
	global_store_dwordx4 v[48:49], v[44:47], off nt
	v_cvt_pk_bf16_f32 v36, v36, v37
	v_cvt_pk_bf16_f32 v37, v38, v39
	v_cvt_pk_bf16_f32 v38, v32, v33
	v_cvt_pk_bf16_f32 v39, v34, v35
	global_store_dwordx4 v[48:49], v[36:39], off offset:256 nt
.LBB0_552:
	s_waitcnt vmcnt(1)
	v_pk_mul_f32 v[28:29], v[28:29], v[84:85] op_sel_hi:[1,0]
	v_pk_mul_f32 v[20:21], v[20:21], v[84:85] op_sel_hi:[1,0]
	v_pk_mul_f32 v[24:25], v[24:25], v[84:85] op_sel_hi:[1,0]
	v_pk_mul_f32 v[16:17], v[16:17], v[84:85] op_sel_hi:[1,0]
	v_pk_mul_f32 v[30:31], v[30:31], v[84:85] op_sel_hi:[1,0]
	v_pk_mul_f32 v[22:23], v[22:23], v[84:85] op_sel_hi:[1,0]
	v_pk_mul_f32 v[26:27], v[26:27], v[84:85] op_sel_hi:[1,0]
	v_pk_mul_f32 v[18:19], v[18:19], v[84:85] op_sel_hi:[1,0]
	v_or_b32_e32 v48, 32, v82
	s_and_b64 vcc, exec, s[10:11]
	s_mov_b64 s[12:13], -1
	s_cbranch_vccnz .LBB0_591
	v_add_u32_e32 v58, 0xffffc020, v82
	v_cndmask_b32_e64 v50, v48, v58, s[6:7]
	v_and_b32_e32 v59, 7, v50
	v_and_b32_e32 v60, 0x1fff, v50
	s_and_b64 vcc, exec, s[8:9]
	s_cbranch_vccnz .LBB0_578
	v_or_b32_e32 v32, 0x800, v59
	v_cndmask_b32_e64 v52, v60, v32, s[6:7]
	s_andn2_b64 vcc, exec, s[20:21]
	s_cbranch_vccnz .LBB0_565
	s_andn2_b64 vcc, exec, s[16:17]
	s_cbranch_vccnz .LBB0_562
	v_readlane_b32 s12, v249, 14
	v_readlane_b32 s13, v249, 15
	s_andn2_b64 vcc, exec, s[12:13]
	s_cbranch_vccnz .LBB0_643
	s_mov_b64 s[12:13], exec
	v_readlane_b32 s26, v249, 16
	v_readlane_b32 s27, v249, 17
	s_and_b64 s[26:27], s[12:13], s[26:27]
	s_mov_b64 exec, s[26:27]
	s_cbranch_execz .LBB0_559
	v_ashrrev_i32_e32 v49, 31, v48
	v_readlane_b32 s26, v249, 12
	v_lshlrev_b64 v[32:33], 5, v[48:49]
	v_readlane_b32 s27, v249, 13
	s_nop 1
	v_lshl_add_u64 v[32:33], s[26:27], 0, v[32:33]
	global_store_dwordx4 v[32:33], v[28:31], off nt
	global_store_dwordx4 v[32:33], v[24:27], off offset:16 nt

;     __device__ __forceinline__ void operator()(const f32x4 (&acc)[2][2][4][2], const Unit& u, int wr, int wc, int fr, int fq) const {
;     ...
;                     if (wc == 0) {
;                         const int d0 = 8 * fq; float cs[8], sn[8]; load8_f32(cosT + (size_t)pos * 32 + d0, cs); load8_f32(sinT + (size_t)pos * 32 + d0, sn);
;                         float ol[8], oh[8];
; #pragma unroll
;                         for (int e = 0; e < 8; ++e) { ol[e] = lo[e] * cs[e] - hi[e] * sn[e]; oh[e] = hi[e] * cs[e] + lo[e] * sn[e]; }
;                         store8_bf16(kib + (size_t)r * 64 + d0, ol); store8_bf16(kib + (size_t)r * 64 + 32 + d0, oh);
;                         float* io = out + (samp ? OFF_IK_S : OFF_IK_P) + (size_t)rl * 64 + d0; store8_f32(io, ol); store8_f32(io + 32, oh);
.LBB0_560:
	v_lshlrev_b32_e32 v152, 7, v52
	v_lshl_add_u64 v[32:33], v[158:159], 0, v[152:153]
	v_lshl_add_u64 v[40:41], v[160:161], 0, v[152:153]
	global_load_dwordx4 v[44:47], v[32:33], off offset:16
	s_nop 0
	global_load_dwordx4 v[32:35], v[32:33], off
	s_nop 0
	global_load_dwordx4 v[36:39], v[40:41], off offset:16
	s_nop 0
	global_load_dwordx4 v[40:43], v[40:41], off
	v_mov_b32_e32 v54, v28
	v_mov_b32_e32 v55, v20
	v_mov_b32_e32 v62, v20
	v_mov_b32_e32 v63, v28
	v_ashrrev_i32_e32 v49, 31, v48
	v_readlane_b32 s60, v250, 0
	s_lshl_b32 s12, s69, 2
	v_readlane_b32 s62, v250, 2
	v_readlane_b32 s63, v250, 3
	s_add_u32 s12, s62, s12
	v_ashrrev_i32_e32 v51, 31, v50
	s_addc_u32 s13, s63, 0
	v_readlane_b32 s61, v250, 1
	v_readlane_b32 s64, v250, 4
	v_readlane_b32 s65, v250, 5
	v_readlane_b32 s66, v250, 6
	v_readlane_b32 s67, v250, 7
	s_waitcnt vmcnt(2)
	v_mov_b32_e32 v56, v32
	s_waitcnt vmcnt(0)
	v_mov_b32_e32 v57, v40
	v_pk_mul_f32 v[54:55], v[54:55], v[56:57]
	v_pk_mul_f32 v[56:57], v[62:63], v[56:57]
	v_mov_b32_e32 v62, v29
	v_mov_b32_e32 v63, v21
	v_mov_b32_e32 v40, v33
	v_pk_mul_f32 v[32:33], v[62:63], v[40:41]
	v_mov_b32_e32 v62, v54
	v_mov_b32_e32 v63, v32
	v_mov_b32_e32 v32, v55
	v_mov_b32_e32 v54, v21
	v_mov_b32_e32 v55, v29
	v_pk_mul_f32 v[40:41], v[54:55], v[40:41]
	v_mov_b32_e32 v54, v56
	v_mov_b32_e32 v55, v40
	v_mov_b32_e32 v40, v57
	v_pk_add_f32 v[32:33], v[62:63], v[32:33] neg_lo:[0,1] neg_hi:[0,1]
	v_pk_add_f32 v[40:41], v[54:55], v[40:41]
	v_mov_b32_e32 v54, v30
	v_mov_b32_e32 v55, v22
	v_mov_b32_e32 v56, v34
	v_mov_b32_e32 v57, v42
	v_mov_b32_e32 v62, v22
	v_mov_b32_e32 v63, v30
	v_pk_mul_f32 v[54:55], v[54:55], v[56:57]
	v_pk_mul_f32 v[56:57], v[62:63], v[56:57]
	v_mov_b32_e32 v62, v31
	v_mov_b32_e32 v63, v23
	v_mov_b32_e32 v42, v35
	v_pk_mul_f32 v[34:35], v[62:63], v[42:43]
	v_mov_b32_e32 v62, v54
	v_mov_b32_e32 v63, v34
	v_mov_b32_e32 v34, v55
	v_mov_b32_e32 v54, v23
	v_mov_b32_e32 v55, v31
	v_pk_mul_f32 v[42:43], v[54:55], v[42:43]
	v_mov_b32_e32 v54, v56
	v_mov_b32_e32 v55, v42
	v_mov_b32_e32 v42, v57
	v_pk_add_f32 v[34:35], v[62:63], v[34:35] neg_lo:[0,1] neg_hi:[0,1]
	v_pk_add_f32 v[42:43], v[54:55], v[42:43]
	v_mov_b32_e32 v54, v24
	v_mov_b32_e32 v55, v16
	v_mov_b32_e32 v56, v44
	v_mov_b32_e32 v57, v36
	v_mov_b32_e32 v62, v16
	v_mov_b32_e32 v63, v24
	v_pk_mul_f32 v[54:55], v[54:55], v[56:57]
	v_pk_mul_f32 v[56:57], v[62:63], v[56:57]
	v_mov_b32_e32 v62, v25
	v_mov_b32_e32 v63, v17
	v_mov_b32_e32 v36, v45
	v_pk_mul_f32 v[44:45], v[62:63], v[36:37]
	v_mov_b32_e32 v62, v54
	v_mov_b32_e32 v63, v44
	v_mov_b32_e32 v44, v55
	v_mov_b32_e32 v54, v17
	v_mov_b32_e32 v55, v25
	v_pk_mul_f32 v[36:37], v[54:55], v[36:37]
	v_mov_b32_e32 v54, v56
	v_mov_b32_e32 v55, v36
	v_mov_b32_e32 v36, v57
	v_pk_add_f32 v[44:45], v[62:63], v[44:45] neg_lo:[0,1] neg_hi:[0,1]
	v_pk_add_f32 v[36:37], v[54:55], v[36:37]
	v_mov_b32_e32 v54, v26
	v_mov_b32_e32 v55, v18
	v_mov_b32_e32 v56, v46
	v_mov_b32_e32 v57, v38
	v_mov_b32_e32 v62, v18
	v_mov_b32_e32 v63, v26
	v_pk_mul_f32 v[54:55], v[54:55], v[56:57]
	v_pk_mul_f32 v[56:57], v[62:63], v[56:57]
	v_mov_b32_e32 v62, v27
	v_mov_b32_e32 v63, v19
	v_mov_b32_e32 v38, v47
	v_pk_mul_f32 v[46:47], v[62:63], v[38:39]
	v_mov_b32_e32 v62, v54
	v_mov_b32_e32 v63, v46
	v_mov_b32_e32 v46, v55
	v_mov_b32_e32 v54, v19
	v_mov_b32_e32 v55, v27
	v_pk_mul_f32 v[38:39], v[54:55], v[38:39]
	v_mov_b32_e32 v54, v56
	v_mov_b32_e32 v55, v38
	v_mov_b32_e32 v38, v57
	v_pk_add_f32 v[38:39], v[54:55], v[38:39]
	v_lshlrev_b64 v[54:55], 7, v[48:49]
	v_pk_add_f32 v[46:47], v[62:63], v[46:47] neg_lo:[0,1] neg_hi:[0,1]
	v_lshl_add_u64 v[62:63], v[162:163], 0, v[54:55]
	v_cvt_pk_bf16_f32 v54, v32, v33
	v_cvt_pk_bf16_f32 v55, v34, v35
	v_cvt_pk_bf16_f32 v56, v44, v45
	v_cvt_pk_bf16_f32 v57, v46, v47
	global_store_dwordx4 v[62:63], v[54:57], off nt
	s_nop 1
	v_cvt_pk_bf16_f32 v54, v40, v41
	v_cvt_pk_bf16_f32 v55, v42, v43
	v_cvt_pk_bf16_f32 v56, v36, v37
	v_cvt_pk_bf16_f32 v57, v38, v39
	global_store_dwordx4 v[62:63], v[54:57], off offset:64 nt
	s_nop 1
	v_lshlrev_b64 v[54:55], 8, v[50:51]
	v_lshl_add_u64 v[54:55], s[12:13], 0, v[54:55]
	v_lshl_add_u64 v[54:55], v[154:155], 2, v[54:55]
	global_store_dwordx4 v[54:55], v[32:35], off nt
	global_store_dwordx4 v[54:55], v[44:47], off offset:16 nt
	global_store_dwordx4 v[54:55], v[40:43], off offset:128 nt
	global_store_dwordx4 v[54:55], v[36:39], off offset:144 nt

;     __device__ __forceinline__ void operator()(const f32x4 (&acc)[2][2][4][2], const Unit& u, int wr, int wc, int fr, int fq) const {
;     ...
;                 } else if (pn < 12) {
;                     const int c = 256 * (pn - 10) + c8;
;                     store8_bf16(vb + (size_t)r * 512 + c, lo); store8_bf16(vb + (size_t)r * 512 + c + 128, hi);
;                     float* vo = out + (samp ? OFF_V_S : OFF_V_P) + (size_t)rl * 512 + c; store8_f32(vo, lo); store8_f32(vo + 128, hi);
.LBB0_562:
	s_andn2_b64 vcc, exec, s[12:13]
	s_cbranch_vccnz .LBB0_564
	v_ashrrev_i32_e32 v49, 31, v48
	v_readlane_b32 s12, v249, 8
	v_lshlrev_b64 v[32:33], 10, v[48:49]
	v_readlane_b32 s13, v249, 9
	v_readlane_b32 s60, v250, 0
	v_readlane_b32 s62, v250, 2
	v_lshl_add_u64 v[32:33], s[12:13], 0, v[32:33]
	v_lshl_add_u64 v[36:37], v[176:177], 1, v[32:33]
	v_cvt_pk_bf16_f32 v32, v28, v29
	v_cvt_pk_bf16_f32 v33, v30, v31
	s_lshl_b32 s12, s55, 2
	v_cvt_pk_bf16_f32 v34, v24, v25
	v_cvt_pk_bf16_f32 v35, v26, v27
	global_store_dwordx4 v[36:37], v[32:35], off nt
	v_readlane_b32 s63, v250, 3
	s_add_u32 s12, s62, s12
	v_cvt_pk_bf16_f32 v32, v20, v21
	v_cvt_pk_bf16_f32 v33, v22, v23
	v_ashrrev_i32_e32 v51, 31, v50
	v_cvt_pk_bf16_f32 v34, v16, v17
	v_cvt_pk_bf16_f32 v35, v18, v19
	global_store_dwordx4 v[36:37], v[32:35], off offset:256 nt
	s_addc_u32 s13, s63, 0
	v_readlane_b32 s61, v250, 1
	v_lshlrev_b64 v[32:33], 11, v[50:51]
	v_lshl_add_u64 v[32:33], s[12:13], 0, v[32:33]
	v_lshl_add_u64 v[32:33], v[176:177], 2, v[32:33]
	v_readlane_b32 s64, v250, 4
	v_readlane_b32 s65, v250, 5
	v_readlane_b32 s66, v250, 6
	v_readlane_b32 s67, v250, 7
	global_store_dwordx4 v[32:33], v[28:31], off nt
	global_store_dwordx4 v[32:33], v[24:27], off offset:16 nt
	global_store_dwordx4 v[32:33], v[20:23], off offset:512 nt
	global_store_dwordx4 v[32:33], v[16:19], off offset:528 nt

;     __device__ __forceinline__ void operator()(const f32x4 (&acc)[2][2][4][2], const Unit& u, int wr, int wc, int fr, int fq) const {
;     ...
;                     float cs[8], sn[8]; load8_f32(cosT + (size_t)pos * 32 + d0, cs); load8_f32(sinT + (size_t)pos * 32 + d0, sn);
;                     float ol[8], oh[8];
; #pragma unroll
;                     for (int e = 0; e < 8; ++e) { ol[e] = lo[e] * cs[e] - hi[e] * sn[e]; oh[e] = hi[e] * cs[e] + lo[e] * sn[e]; }
;                     const size_t o512 = (size_t)r * 512 + head * 64 + d0;
;                     if (pn < 8) {
; #pragma unroll
;                         for (int e = 0; e < 8; ++e) { ol[e] *= 0.18033688011112042f; oh[e] *= 0.18033688011112042f; }
;                         store8_bf16(qb + o512, ol); store8_bf16(qb + o512 + 32, oh);
;                     } else if (pn < 10) {
;                         store8_bf16(kb + o512, ol); store8_bf16(kb + o512 + 32, oh);
;                         float* ko = out + (samp ? OFF_K_S : OFF_K_P) + (size_t)rl * 512 + head * 64 + d0; store8_f32(ko, ol); store8_f32(ko + 32, oh);
;                     } else {
;                         store8_bf16(qib + o512, ol); store8_bf16(qib + o512 + 32, oh);
;                     }
.LBB0_569:
	v_lshlrev_b32_e32 v152, 7, v52
	v_lshl_add_u64 v[52:53], v[160:161], 0, v[152:153]
	global_load_dwordx4 v[44:47], v[52:53], off
	global_load_dwordx4 v[62:65], v[52:53], off offset:16
	v_lshl_add_u64 v[52:53], v[158:159], 0, v[152:153]
	global_load_dwordx4 v[66:69], v[52:53], off
	global_load_dwordx4 v[70:73], v[52:53], off offset:16
	v_ashrrev_i32_e32 v49, 31, v48
	v_lshlrev_b64 v[52:53], 9, v[48:49]
	v_lshl_add_u64 v[52:53], v[52:53], 0, v[174:175]
	s_andn2_b64 vcc, exec, s[94:95]
	s_mov_b64 s[12:13], -1
	s_waitcnt vmcnt(3)
	v_pk_mul_f32 v[74:75], v[38:39], v[44:45]
	v_pk_mul_f32 v[76:77], v[40:41], v[44:45]
	v_pk_mul_f32 v[78:79], v[36:37], v[46:47]
	v_pk_mul_f32 v[84:85], v[42:43], v[46:47]
	s_waitcnt vmcnt(2)
	v_pk_mul_f32 v[86:87], v[32:33], v[62:63]
	v_pk_mul_f32 v[62:63], v[56:57], v[62:63]
	v_pk_mul_f32 v[88:89], v[34:35], v[64:65]
	v_pk_mul_f32 v[64:65], v[54:55], v[64:65]
	s_waitcnt vmcnt(1)
	v_pk_fma_f32 v[44:45], v[40:41], v[66:67], v[74:75] neg_lo:[0,0,1] neg_hi:[0,0,1]
	v_pk_fma_f32 v[40:41], v[38:39], v[66:67], v[76:77]
	v_pk_fma_f32 v[46:47], v[42:43], v[68:69], v[78:79] neg_lo:[0,0,1] neg_hi:[0,0,1]
	v_pk_fma_f32 v[42:43], v[36:37], v[68:69], v[84:85]
	s_waitcnt vmcnt(0)
	v_pk_fma_f32 v[36:37], v[56:57], v[70:71], v[86:87] neg_lo:[0,0,1] neg_hi:[0,0,1]
	v_pk_fma_f32 v[32:33], v[32:33], v[70:71], v[62:63]
	v_pk_fma_f32 v[38:39], v[54:55], v[72:73], v[88:89] neg_lo:[0,0,1] neg_hi:[0,0,1]
	v_pk_fma_f32 v[34:35], v[34:35], v[72:73], v[64:65]
	s_cbranch_vccnz .LBB0_575
	s_andn2_b64 vcc, exec, s[2:3]
	s_cbranch_vccnz .LBB0_572
	v_readlane_b32 s12, v249, 10
	v_readlane_b32 s13, v249, 11
	v_cvt_pk_bf16_f32 v54, v44, v45
	v_cvt_pk_bf16_f32 v55, v46, v47
	v_cvt_pk_bf16_f32 v56, v36, v37
	v_cvt_pk_bf16_f32 v57, v38, v39
	s_nop 1
	v_lshl_add_u64 v[62:63], v[52:53], 1, s[12:13]
	s_mov_b64 s[12:13], 0
	global_store_dwordx4 v[62:63], v[54:57], off nt
	s_nop 1
	v_cvt_pk_bf16_f32 v54, v40, v41
	v_cvt_pk_bf16_f32 v55, v42, v43
	v_cvt_pk_bf16_f32 v56, v32, v33
	v_cvt_pk_bf16_f32 v57, v34, v35
	global_store_dwordx4 v[62:63], v[54:57], off offset:64 nt
.LBB0_572:
	s_andn2_b64 vcc, exec, s[12:13]
	s_cbranch_vccnz .LBB0_574
	v_readlane_b32 s12, v249, 6
	v_readlane_b32 s13, v249, 7
	v_readlane_b32 s60, v250, 0
	v_readlane_b32 s62, v250, 2
	v_lshl_add_u64 v[62:63], v[52:53], 1, s[12:13]
	s_lshl_b32 s12, s53, 2
	v_readlane_b32 s63, v250, 3
	s_add_u32 s12, s62, s12
	v_ashrrev_i32_e32 v51, 31, v50
	s_addc_u32 s13, s63, 0
	v_lshlrev_b64 v[50:51], 11, v[50:51]
	v_lshl_add_u64 v[50:51], s[12:13], 0, v[50:51]
	s_lshl_b32 s12, s18, 2
	s_mov_b32 s13, s19
	v_lshl_add_u64 v[50:51], v[50:51], 0, s[12:13]
	v_cvt_pk_bf16_f32 v54, v44, v45
	v_cvt_pk_bf16_f32 v55, v46, v47
	v_cvt_pk_bf16_f32 v56, v36, v37
	v_cvt_pk_bf16_f32 v57, v38, v39
	v_lshl_add_u64 v[50:51], v[154:155], 2, v[50:51]
	global_store_dwordx4 v[62:63], v[54:57], off nt
	v_readlane_b32 s61, v250, 1
	v_readlane_b32 s64, v250, 4
	v_cvt_pk_bf16_f32 v54, v40, v41
	v_cvt_pk_bf16_f32 v55, v42, v43
	v_cvt_pk_bf16_f32 v56, v32, v33
	v_cvt_pk_bf16_f32 v57, v34, v35
	global_store_dwordx4 v[62:63], v[54:57], off offset:64 nt
	v_readlane_b32 s65, v250, 5
	v_readlane_b32 s66, v250, 6
	v_readlane_b32 s67, v250, 7
	global_store_dwordx4 v[50:51], v[44:47], off nt
	global_store_dwordx4 v[50:51], v[36:39], off offset:16 nt
	global_store_dwordx4 v[50:51], v[40:43], off offset:128 nt
	global_store_dwordx4 v[50:51], v[32:35], off offset:144 nt

;     __device__ __forceinline__ void operator()(const f32x4 (&acc)[2][2][4][2], const Unit& u, int wr, int wc, int fr, int fq) const {
;     ...
;                     if (pn < 8) {
; #pragma unroll
;                         for (int e = 0; e < 8; ++e) { ol[e] *= 0.18033688011112042f; oh[e] *= 0.18033688011112042f; }
;                         store8_bf16(qb + o512, ol); store8_bf16(qb + o512 + 32, oh);
.LBB0_575:
	s_andn2_b64 vcc, exec, s[12:13]
	s_cbranch_vccnz .LBB0_577
	v_readlane_b32 s12, v249, 4
	v_readlane_b32 s13, v249, 5
	v_mul_f32_e32 v44, 0x3e38aa3b, v44
	v_mul_f32_e32 v45, 0x3e38aa3b, v45
	v_mul_f32_e32 v46, 0x3e38aa3b, v46
	v_mul_f32_e32 v47, 0x3e38aa3b, v47
	v_mul_f32_e32 v49, 0x3e38aa3b, v36
	v_mul_f32_e32 v50, 0x3e38aa3b, v32
	v_mul_f32_e32 v51, 0x3e38aa3b, v37
	v_mul_f32_e32 v54, 0x3e38aa3b, v33
	v_mul_f32_e32 v38, 0x3e38aa3b, v38
	v_mul_f32_e32 v55, 0x3e38aa3b, v34
	v_mul_f32_e32 v39, 0x3e38aa3b, v39
	v_mul_f32_e32 v56, 0x3e38aa3b, v35
	v_lshl_add_u64 v[36:37], v[52:53], 1, s[12:13]
	v_cvt_pk_bf16_f32 v32, v44, v45
	v_cvt_pk_bf16_f32 v33, v46, v47
	v_cvt_pk_bf16_f32 v34, v49, v51
	v_cvt_pk_bf16_f32 v35, v38, v39
	v_mul_f32_e32 v40, 0x3e38aa3b, v40
	v_mul_f32_e32 v41, 0x3e38aa3b, v41
	v_mul_f32_e32 v42, 0x3e38aa3b, v42
	v_mul_f32_e32 v43, 0x3e38aa3b, v43
	global_store_dwordx4 v[36:37], v[32:35], off nt
	s_nop 1
	v_cvt_pk_bf16_f32 v32, v40, v41
	v_cvt_pk_bf16_f32 v33, v42, v43
	v_cvt_pk_bf16_f32 v34, v50, v54
	v_cvt_pk_bf16_f32 v35, v55, v56
	global_store_dwordx4 v[36:37], v[32:35], off offset:64 nt

;     __device__ __forceinline__ void operator()(const f32x4 (&acc)[2][2][4][2], const Unit& u, int wr, int wc, int fr, int fq) const {
;     ...
;                     const int ch = 128 * (pn - 2) + c8; float uu[8];
; #pragma unroll
;                     for (int e = 0; e < 8; ++e) uu[e] = lo[e] * hi[e];
;                     store8_bf16(ub + (size_t)r * 512 + ch, uu);
;                     if (!samp) { const int t = rl & (SEQ - 1); if (t >= SEQ - 2) store8_f32(out + OFF_CM_P + (size_t)((rl >> 13) * 2 + (t - (SEQ - 2))) * 512 + ch, uu); }
;                     else { const int tt = rl & 7; if (tt >= 6) store8_f32(out + OFF_CM_S + (size_t)((rl >> 3) * 2 + (tt - 6)) * 512 + ch, uu); }
.LBB0_578:
	s_andn2_b64 vcc, exec, s[12:13]
	s_cbranch_vccnz .LBB0_590
	v_ashrrev_i32_e32 v49, 31, v48
	v_lshlrev_b64 v[40:41], 10, v[48:49]
	v_lshl_add_u64 v[40:41], s[88:89], 0, v[40:41]
	v_pk_mul_f32 v[36:37], v[28:29], v[20:21]
	v_pk_mul_f32 v[38:39], v[30:31], v[22:23]
	v_pk_mul_f32 v[32:33], v[24:25], v[16:17]
	v_pk_mul_f32 v[34:35], v[26:27], v[18:19]
	v_lshl_add_u64 v[44:45], v[172:173], 1, v[40:41]
	s_andn2_b64 vcc, exec, s[84:85]
	v_cvt_pk_bf16_f32 v40, v36, v37
	v_cvt_pk_bf16_f32 v41, v38, v39
	v_cvt_pk_bf16_f32 v42, v32, v33
	v_cvt_pk_bf16_f32 v43, v34, v35
	global_store_dwordx4 v[44:45], v[40:43], off nt
	s_cbranch_vccnz .LBB0_583
	s_movk_i32 s12, 0x1ffd
	v_cmp_lt_u32_e32 vcc, s12, v60
	s_mov_b64 s[26:27], 0
	s_mov_b64 s[12:13], 0
	s_and_saveexec_b64 s[28:29], vcc
	s_ashr_i32 s12, s58, 12
	s_and_b32 s12, s12, -2
	s_addk_i32 s12, 0xe002
	v_add_u32_e32 v40, s12, v60
	s_mov_b64 s[12:13], exec
	s_or_b64 exec, exec, s[28:29]
	s_mov_b64 s[28:29], 0x8800000
	s_and_b64 vcc, exec, s[26:27]
	s_cbranch_vccnz .LBB0_584
	s_branch .LBB0_587

;     __device__ __forceinline__ void operator()(const f32x4 (&acc)[2][2][4][2], const Unit& u, int wr, int wc, int fr, int fq) const {
;     ...
;                     if (!samp) { const int t = rl & (SEQ - 1); if (t >= SEQ - 2) store8_f32(out + OFF_CM_P + (size_t)((rl >> 13) * 2 + (t - (SEQ - 2))) * 512 + ch, uu); }
;                     else { const int tt = rl & 7; if (tt >= 6) store8_f32(out + OFF_CM_S + (size_t)((rl >> 3) * 2 + (tt - 6)) * 512 + ch, uu); }
.LBB0_587:
	s_and_saveexec_b64 s[26:27], s[12:13]
	s_cbranch_execz .LBB0_589
	v_readlane_b32 s60, v250, 0
	v_readlane_b32 s62, v250, 2
	v_readlane_b32 s63, v250, 3
	s_add_u32 s12, s62, s28
	v_ashrrev_i32_e32 v41, 31, v40
	s_addc_u32 s13, s63, s29
	v_lshlrev_b64 v[40:41], 11, v[40:41]
	v_lshl_add_u64 v[40:41], s[12:13], 0, v[40:41]
	v_lshl_add_u64 v[40:41], v[172:173], 2, v[40:41]
	v_readlane_b32 s61, v250, 1
	v_readlane_b32 s64, v250, 4
	v_readlane_b32 s65, v250, 5
	v_readlane_b32 s66, v250, 6
	v_readlane_b32 s67, v250, 7
	global_store_dwordx4 v[40:41], v[36:39], off nt
	global_store_dwordx4 v[40:41], v[32:35], off offset:16 nt

; #define EPI_GET(dst, ai, bj, m, s) do { _Pragma("unroll") for (int e_ = 0; e_ < 4; ++e_) { (dst)[e_] = acc[ai][bj][m][0][e_] * (s); (dst)[4 + e_] = acc[ai][bj][m][1][e_] * (s); } } while (0)
;     __device__ __forceinline__ void operator()(const f32x4 (&acc)[2][2][4][2], const Unit& u, int wr, int wc, int fr, int fq) const {
;     ...
;             for (int m = 0; m < 4; ++m) {
;                 const int r = EPI_ROWS(ai, m); const float rs = rsa[m];
;                 float lo[8], hi[8]; EPI_GET(lo, ai, 0, m, rs); EPI_GET(hi, ai, 1, m, rs);
;                 const int rl = samp ? r - MP : r; const int pos = samp ? PAST + (rl & 7) : (rl & (SEQ - 1));
;                 if (pn < 2) {
;                     store8_bf16(cbb + (size_t)r * 512 + pn * 256 + c8, lo); store8_bf16(cbb + (size_t)r * 512 + pn * 256 + 128 + c8, hi);
;                 } else if (pn < 6) {
;                     const int ch = 128 * (pn - 2) + c8; float uu[8];
; #pragma unroll
;                     for (int e = 0; e < 8; ++e) uu[e] = lo[e] * hi[e];
;                     store8_bf16(ub + (size_t)r * 512 + ch, uu);
;                     if (!samp) { const int t = rl & (SEQ - 1); if (t >= SEQ - 2) store8_f32(out + OFF_CM_P + (size_t)((rl >> 13) * 2 + (t - (SEQ - 2))) * 512 + ch, uu); }
;                     else { const int tt = rl & 7; if (tt >= 6) store8_f32(out + OFF_CM_S + (size_t)((rl >> 3) * 2 + (tt - 6)) * 512 + ch, uu); }
;                 } else if (pn < 10 || pn == 12 || pn == 13) {
;     ...
;                     } else if (wc == 1 && fq == 0) {
;                         store8_f32(iwf + (size_t)r * 8, lo);
.LBB0_591:
	s_andn2_b64 vcc, exec, s[12:13]
	s_cbranch_vccnz .LBB0_593
	v_ashrrev_i32_e32 v49, 31, v48
	v_lshlrev_b64 v[32:33], 10, v[48:49]
	v_lshl_add_u64 v[32:33], s[22:23], 0, v[32:33]
	v_lshl_add_u64 v[32:33], s[56:57], 1, v[32:33]
	v_lshl_add_u64 v[32:33], v[156:157], 1, v[32:33]
	v_cvt_pk_bf16_f32 v28, v28, v29
	v_cvt_pk_bf16_f32 v29, v30, v31
	v_cvt_pk_bf16_f32 v30, v24, v25
	v_cvt_pk_bf16_f32 v31, v26, v27
	global_store_dwordx4 v[32:33], v[28:31], off nt
	v_cvt_pk_bf16_f32 v20, v20, v21
	v_cvt_pk_bf16_f32 v21, v22, v23
	v_cvt_pk_bf16_f32 v22, v16, v17
	v_cvt_pk_bf16_f32 v23, v18, v19
	global_store_dwordx4 v[32:33], v[20:23], off offset:256 nt
.LBB0_593:
	s_waitcnt vmcnt(0)
	v_pk_mul_f32 v[12:13], v[12:13], v[80:81] op_sel_hi:[1,0]
	v_pk_mul_f32 v[4:5], v[4:5], v[80:81] op_sel_hi:[1,0]
	v_pk_mul_f32 v[8:9], v[8:9], v[80:81] op_sel_hi:[1,0]
	v_pk_mul_f32 v[0:1], v[0:1], v[80:81] op_sel_hi:[1,0]
	v_pk_mul_f32 v[14:15], v[14:15], v[80:81] op_sel_hi:[1,0]
	v_pk_mul_f32 v[6:7], v[6:7], v[80:81] op_sel_hi:[1,0]
	v_pk_mul_f32 v[10:11], v[10:11], v[80:81] op_sel_hi:[1,0]
	v_pk_mul_f32 v[2:3], v[2:3], v[80:81] op_sel_hi:[1,0]
	v_or_b32_e32 v32, 48, v82
	s_and_b64 vcc, exec, s[10:11]
	s_mov_b64 s[10:11], -1
	s_cbranch_vccnz .LBB0_632
	v_add_u32_e32 v42, 0xffffc030, v82
	v_cndmask_b32_e64 v34, v32, v42, s[6:7]
	v_and_b32_e32 v43, 7, v34
	v_and_b32_e32 v44, 0x1fff, v34
	s_and_b64 vcc, exec, s[8:9]
	s_mov_b64 s[8:9], -1
	s_cbranch_vccnz .LBB0_619
	v_or_b32_e32 v16, 0x800, v43
	v_cndmask_b32_e64 v36, v44, v16, s[6:7]
	s_andn2_b64 vcc, exec, s[20:21]
	s_mov_b64 s[6:7], -1
	s_cbranch_vccnz .LBB0_606
	s_andn2_b64 vcc, exec, s[16:17]
	s_cbranch_vccnz .LBB0_603
	v_readlane_b32 s6, v249, 14
	v_readlane_b32 s7, v249, 15
	s_andn2_b64 vcc, exec, s[6:7]
	s_cbranch_vccnz .LBB0_644
	s_mov_b64 s[6:7], exec
	v_readlane_b32 s8, v249, 16
	v_readlane_b32 s9, v249, 17
	s_and_b64 s[8:9], s[6:7], s[8:9]
	s_mov_b64 exec, s[8:9]
	s_cbranch_execz .LBB0_600
	v_ashrrev_i32_e32 v33, 31, v32
	v_readlane_b32 s8, v249, 12
	v_lshlrev_b64 v[16:17], 5, v[32:33]
	v_readlane_b32 s9, v249, 13
	s_nop 1
	v_lshl_add_u64 v[16:17], s[8:9], 0, v[16:17]
	global_store_dwordx4 v[16:17], v[12:15], off nt
	global_store_dwordx4 v[16:17], v[8:11], off offset:16 nt

;     __device__ __forceinline__ void operator()(const f32x4 (&acc)[2][2][4][2], const Unit& u, int wr, int wc, int fr, int fq) const {
;     ...
;                     if (wc == 0) {
;                         const int d0 = 8 * fq; float cs[8], sn[8]; load8_f32(cosT + (size_t)pos * 32 + d0, cs); load8_f32(sinT + (size_t)pos * 32 + d0, sn);
;                         float ol[8], oh[8];
; #pragma unroll
;                         for (int e = 0; e < 8; ++e) { ol[e] = lo[e] * cs[e] - hi[e] * sn[e]; oh[e] = hi[e] * cs[e] + lo[e] * sn[e]; }
;                         store8_bf16(kib + (size_t)r * 64 + d0, ol); store8_bf16(kib + (size_t)r * 64 + 32 + d0, oh);
;                         float* io = out + (samp ? OFF_IK_S : OFF_IK_P) + (size_t)rl * 64 + d0; store8_f32(io, ol); store8_f32(io + 32, oh);
.LBB0_601:
	v_lshlrev_b32_e32 v152, 7, v36
	v_lshl_add_u64 v[16:17], v[158:159], 0, v[152:153]
	v_lshl_add_u64 v[24:25], v[160:161], 0, v[152:153]
	global_load_dwordx4 v[28:31], v[16:17], off offset:16
	s_nop 0
	global_load_dwordx4 v[16:19], v[16:17], off
	s_nop 0
	global_load_dwordx4 v[20:23], v[24:25], off offset:16
	s_nop 0
	global_load_dwordx4 v[24:27], v[24:25], off
	v_mov_b32_e32 v38, v12
	v_mov_b32_e32 v39, v4
	v_mov_b32_e32 v46, v4
	v_mov_b32_e32 v47, v12
	v_ashrrev_i32_e32 v33, 31, v32
	v_readlane_b32 s60, v250, 0
	s_lshl_b32 s6, s69, 2
	v_readlane_b32 s62, v250, 2
	v_readlane_b32 s63, v250, 3
	s_add_u32 s6, s62, s6
	v_ashrrev_i32_e32 v35, 31, v34
	s_addc_u32 s7, s63, 0
	v_readlane_b32 s61, v250, 1
	v_readlane_b32 s64, v250, 4
	v_readlane_b32 s65, v250, 5
	v_readlane_b32 s66, v250, 6
	v_readlane_b32 s67, v250, 7
	s_waitcnt vmcnt(2)
	v_mov_b32_e32 v40, v16
	s_waitcnt vmcnt(0)
	v_mov_b32_e32 v41, v24
	v_pk_mul_f32 v[38:39], v[38:39], v[40:41]
	v_pk_mul_f32 v[40:41], v[46:47], v[40:41]
	v_mov_b32_e32 v46, v13
	v_mov_b32_e32 v47, v5
	v_mov_b32_e32 v24, v17
	v_pk_mul_f32 v[16:17], v[46:47], v[24:25]
	v_mov_b32_e32 v46, v38
	v_mov_b32_e32 v47, v16
	v_mov_b32_e32 v16, v39
	v_mov_b32_e32 v38, v5
	v_mov_b32_e32 v39, v13
	v_pk_mul_f32 v[24:25], v[38:39], v[24:25]
	v_mov_b32_e32 v38, v40
	v_mov_b32_e32 v39, v24
	v_mov_b32_e32 v24, v41
	v_pk_add_f32 v[16:17], v[46:47], v[16:17] neg_lo:[0,1] neg_hi:[0,1]
	v_pk_add_f32 v[24:25], v[38:39], v[24:25]
	v_mov_b32_e32 v38, v14
	v_mov_b32_e32 v39, v6
	v_mov_b32_e32 v40, v18
	v_mov_b32_e32 v41, v26
	v_mov_b32_e32 v46, v6
	v_mov_b32_e32 v47, v14
	v_pk_mul_f32 v[38:39], v[38:39], v[40:41]
	v_pk_mul_f32 v[40:41], v[46:47], v[40:41]
	v_mov_b32_e32 v46, v15
	v_mov_b32_e32 v47, v7
	v_mov_b32_e32 v26, v19
	v_pk_mul_f32 v[18:19], v[46:47], v[26:27]
	v_mov_b32_e32 v46, v38
	v_mov_b32_e32 v47, v18
	v_mov_b32_e32 v18, v39
	v_mov_b32_e32 v38, v7
	v_mov_b32_e32 v39, v15
	v_pk_mul_f32 v[26:27], v[38:39], v[26:27]
	v_mov_b32_e32 v38, v40
	v_mov_b32_e32 v39, v26
	v_mov_b32_e32 v26, v41
	v_pk_add_f32 v[18:19], v[46:47], v[18:19] neg_lo:[0,1] neg_hi:[0,1]
	v_pk_add_f32 v[26:27], v[38:39], v[26:27]
	v_mov_b32_e32 v38, v8
	v_mov_b32_e32 v39, v0
	v_mov_b32_e32 v40, v28
	v_mov_b32_e32 v41, v20
	v_mov_b32_e32 v46, v0
	v_mov_b32_e32 v47, v8
	v_pk_mul_f32 v[38:39], v[38:39], v[40:41]
	v_pk_mul_f32 v[40:41], v[46:47], v[40:41]
	v_mov_b32_e32 v46, v9
	v_mov_b32_e32 v47, v1
	v_mov_b32_e32 v20, v29
	v_pk_mul_f32 v[28:29], v[46:47], v[20:21]
	v_mov_b32_e32 v46, v38
	v_mov_b32_e32 v47, v28
	v_mov_b32_e32 v28, v39
	v_mov_b32_e32 v38, v1
	v_mov_b32_e32 v39, v9
	v_pk_mul_f32 v[20:21], v[38:39], v[20:21]
	v_mov_b32_e32 v38, v40
	v_mov_b32_e32 v39, v20
	v_mov_b32_e32 v20, v41
	v_pk_add_f32 v[28:29], v[46:47], v[28:29] neg_lo:[0,1] neg_hi:[0,1]
	v_pk_add_f32 v[20:21], v[38:39], v[20:21]
	v_mov_b32_e32 v38, v10
	v_mov_b32_e32 v39, v2
	v_mov_b32_e32 v40, v30
	v_mov_b32_e32 v41, v22
	v_mov_b32_e32 v46, v2
	v_mov_b32_e32 v47, v10
	v_pk_mul_f32 v[38:39], v[38:39], v[40:41]
	v_pk_mul_f32 v[40:41], v[46:47], v[40:41]
	v_mov_b32_e32 v46, v11
	v_mov_b32_e32 v47, v3
	v_mov_b32_e32 v22, v31
	v_pk_mul_f32 v[30:31], v[46:47], v[22:23]
	v_mov_b32_e32 v46, v38
	v_mov_b32_e32 v47, v30
	v_mov_b32_e32 v30, v39
	v_mov_b32_e32 v38, v3
	v_mov_b32_e32 v39, v11
	v_pk_mul_f32 v[22:23], v[38:39], v[22:23]
	v_mov_b32_e32 v38, v40
	v_mov_b32_e32 v39, v22
	v_mov_b32_e32 v22, v41
	v_pk_add_f32 v[22:23], v[38:39], v[22:23]
	v_lshlrev_b64 v[38:39], 7, v[32:33]
	v_pk_add_f32 v[30:31], v[46:47], v[30:31] neg_lo:[0,1] neg_hi:[0,1]
	v_lshl_add_u64 v[46:47], v[162:163], 0, v[38:39]
	v_cvt_pk_bf16_f32 v38, v16, v17
	v_cvt_pk_bf16_f32 v39, v18, v19
	v_cvt_pk_bf16_f32 v40, v28, v29
	v_cvt_pk_bf16_f32 v41, v30, v31
	global_store_dwordx4 v[46:47], v[38:41], off nt
	s_nop 1
	v_cvt_pk_bf16_f32 v38, v24, v25
	v_cvt_pk_bf16_f32 v39, v26, v27
	v_cvt_pk_bf16_f32 v40, v20, v21
	v_cvt_pk_bf16_f32 v41, v22, v23
	global_store_dwordx4 v[46:47], v[38:41], off offset:64 nt
	s_nop 1
	v_lshlrev_b64 v[38:39], 8, v[34:35]
	v_lshl_add_u64 v[38:39], s[6:7], 0, v[38:39]
	v_lshl_add_u64 v[38:39], v[154:155], 2, v[38:39]
	global_store_dwordx4 v[38:39], v[16:19], off nt
	global_store_dwordx4 v[38:39], v[28:31], off offset:16 nt
	global_store_dwordx4 v[38:39], v[24:27], off offset:128 nt
	global_store_dwordx4 v[38:39], v[20:23], off offset:144 nt

;     __device__ __forceinline__ void operator()(const f32x4 (&acc)[2][2][4][2], const Unit& u, int wr, int wc, int fr, int fq) const {
;     ...
;                 } else if (pn < 12) {
;                     const int c = 256 * (pn - 10) + c8;
;                     store8_bf16(vb + (size_t)r * 512 + c, lo); store8_bf16(vb + (size_t)r * 512 + c + 128, hi);
;                     float* vo = out + (samp ? OFF_V_S : OFF_V_P) + (size_t)rl * 512 + c; store8_f32(vo, lo); store8_f32(vo + 128, hi);
.LBB0_603:
	s_andn2_b64 vcc, exec, s[6:7]
	s_cbranch_vccnz .LBB0_605
	v_ashrrev_i32_e32 v33, 31, v32
	v_readlane_b32 s6, v249, 8
	v_lshlrev_b64 v[16:17], 10, v[32:33]
	v_readlane_b32 s7, v249, 9
	v_readlane_b32 s60, v250, 0
	v_readlane_b32 s62, v250, 2
	v_lshl_add_u64 v[16:17], s[6:7], 0, v[16:17]
	v_lshl_add_u64 v[20:21], v[176:177], 1, v[16:17]
	v_cvt_pk_bf16_f32 v16, v12, v13
	v_cvt_pk_bf16_f32 v17, v14, v15
	s_lshl_b32 s6, s55, 2
	v_cvt_pk_bf16_f32 v18, v8, v9
	v_cvt_pk_bf16_f32 v19, v10, v11
	global_store_dwordx4 v[20:21], v[16:19], off nt
	v_readlane_b32 s63, v250, 3
	s_add_u32 s6, s62, s6
	v_cvt_pk_bf16_f32 v16, v4, v5
	v_cvt_pk_bf16_f32 v17, v6, v7
	v_ashrrev_i32_e32 v35, 31, v34
	v_cvt_pk_bf16_f32 v18, v0, v1
	v_cvt_pk_bf16_f32 v19, v2, v3
	global_store_dwordx4 v[20:21], v[16:19], off offset:256 nt
	s_addc_u32 s7, s63, 0
	v_readlane_b32 s61, v250, 1
	v_lshlrev_b64 v[16:17], 11, v[34:35]
	v_lshl_add_u64 v[16:17], s[6:7], 0, v[16:17]
	v_lshl_add_u64 v[16:17], v[176:177], 2, v[16:17]
	v_readlane_b32 s64, v250, 4
	v_readlane_b32 s65, v250, 5
	v_readlane_b32 s66, v250, 6
	v_readlane_b32 s67, v250, 7
	global_store_dwordx4 v[16:17], v[12:15], off nt
	global_store_dwordx4 v[16:17], v[8:11], off offset:16 nt
	global_store_dwordx4 v[16:17], v[4:7], off offset:512 nt
	global_store_dwordx4 v[16:17], v[0:3], off offset:528 nt

;     __device__ __forceinline__ void operator()(const f32x4 (&acc)[2][2][4][2], const Unit& u, int wr, int wc, int fr, int fq) const {
;     ...
;                     float cs[8], sn[8]; load8_f32(cosT + (size_t)pos * 32 + d0, cs); load8_f32(sinT + (size_t)pos * 32 + d0, sn);
;                     float ol[8], oh[8];
; #pragma unroll
;                     for (int e = 0; e < 8; ++e) { ol[e] = lo[e] * cs[e] - hi[e] * sn[e]; oh[e] = hi[e] * cs[e] + lo[e] * sn[e]; }
;                     const size_t o512 = (size_t)r * 512 + head * 64 + d0;
;                     if (pn < 8) {
; #pragma unroll
;                         for (int e = 0; e < 8; ++e) { ol[e] *= 0.18033688011112042f; oh[e] *= 0.18033688011112042f; }
;                         store8_bf16(qb + o512, ol); store8_bf16(qb + o512 + 32, oh);
;                     } else if (pn < 10) {
;                         store8_bf16(kb + o512, ol); store8_bf16(kb + o512 + 32, oh);
;                         float* ko = out + (samp ? OFF_K_S : OFF_K_P) + (size_t)rl * 512 + head * 64 + d0; store8_f32(ko, ol); store8_f32(ko + 32, oh);
;                     } else {
;                         store8_bf16(qib + o512, ol); store8_bf16(qib + o512 + 32, oh);
;                     }
.LBB0_610:
	v_lshlrev_b32_e32 v152, 7, v36
	v_lshl_add_u64 v[36:37], v[160:161], 0, v[152:153]
	global_load_dwordx4 v[28:31], v[36:37], off
	global_load_dwordx4 v[46:49], v[36:37], off offset:16
	v_lshl_add_u64 v[36:37], v[158:159], 0, v[152:153]
	global_load_dwordx4 v[50:53], v[36:37], off
	global_load_dwordx4 v[54:57], v[36:37], off offset:16
	v_ashrrev_i32_e32 v33, 31, v32
	v_lshlrev_b64 v[36:37], 9, v[32:33]
	v_lshl_add_u64 v[36:37], v[36:37], 0, v[174:175]
	s_andn2_b64 vcc, exec, s[94:95]
	s_mov_b64 s[6:7], -1
	s_waitcnt vmcnt(3)
	v_pk_mul_f32 v[58:59], v[22:23], v[28:29]
	v_pk_mul_f32 v[60:61], v[24:25], v[28:29]
	v_pk_mul_f32 v[62:63], v[20:21], v[30:31]
	v_pk_mul_f32 v[64:65], v[26:27], v[30:31]
	s_waitcnt vmcnt(2)
	v_pk_mul_f32 v[66:67], v[16:17], v[46:47]
	v_pk_mul_f32 v[46:47], v[40:41], v[46:47]
	v_pk_mul_f32 v[68:69], v[18:19], v[48:49]
	v_pk_mul_f32 v[48:49], v[38:39], v[48:49]
	s_waitcnt vmcnt(1)
	v_pk_fma_f32 v[28:29], v[24:25], v[50:51], v[58:59] neg_lo:[0,0,1] neg_hi:[0,0,1]
	v_pk_fma_f32 v[24:25], v[22:23], v[50:51], v[60:61]
	v_pk_fma_f32 v[30:31], v[26:27], v[52:53], v[62:63] neg_lo:[0,0,1] neg_hi:[0,0,1]
	v_pk_fma_f32 v[26:27], v[20:21], v[52:53], v[64:65]
	s_waitcnt vmcnt(0)
	v_pk_fma_f32 v[20:21], v[40:41], v[54:55], v[66:67] neg_lo:[0,0,1] neg_hi:[0,0,1]
	v_pk_fma_f32 v[16:17], v[16:17], v[54:55], v[46:47]
	v_pk_fma_f32 v[22:23], v[38:39], v[56:57], v[68:69] neg_lo:[0,0,1] neg_hi:[0,0,1]
	v_pk_fma_f32 v[18:19], v[18:19], v[56:57], v[48:49]
	s_cbranch_vccnz .LBB0_616
	s_andn2_b64 vcc, exec, s[2:3]
	s_cbranch_vccnz .LBB0_613
	v_readlane_b32 s2, v249, 10
	v_readlane_b32 s3, v249, 11
	v_cvt_pk_bf16_f32 v38, v28, v29
	v_cvt_pk_bf16_f32 v39, v30, v31
	v_cvt_pk_bf16_f32 v40, v20, v21
	v_cvt_pk_bf16_f32 v41, v22, v23
	s_mov_b64 s[6:7], 0
	s_nop 0
	v_lshl_add_u64 v[46:47], v[36:37], 1, s[2:3]
	global_store_dwordx4 v[46:47], v[38:41], off nt
	s_nop 1
	v_cvt_pk_bf16_f32 v38, v24, v25
	v_cvt_pk_bf16_f32 v39, v26, v27
	v_cvt_pk_bf16_f32 v40, v16, v17
	v_cvt_pk_bf16_f32 v41, v18, v19
	global_store_dwordx4 v[46:47], v[38:41], off offset:64 nt
.LBB0_613:
	s_andn2_b64 vcc, exec, s[6:7]
	s_cbranch_vccnz .LBB0_615
	v_readlane_b32 s60, v250, 0
	s_lshl_b32 s6, s53, 2
	v_readlane_b32 s62, v250, 2
	v_readlane_b32 s63, v250, 3
	s_add_u32 s6, s62, s6
	v_ashrrev_i32_e32 v35, 31, v34
	s_addc_u32 s7, s63, 0
	v_lshlrev_b64 v[34:35], 11, v[34:35]
	v_readlane_b32 s2, v249, 6
	v_lshl_add_u64 v[34:35], s[6:7], 0, v[34:35]
	s_lshl_b32 s18, s18, 2
	v_readlane_b32 s3, v249, 7
	v_lshl_add_u64 v[34:35], v[34:35], 0, s[18:19]
	v_cvt_pk_bf16_f32 v38, v28, v29
	v_cvt_pk_bf16_f32 v39, v30, v31
	v_cvt_pk_bf16_f32 v40, v20, v21
	v_cvt_pk_bf16_f32 v41, v22, v23
	s_nop 0
	v_lshl_add_u64 v[46:47], v[36:37], 1, s[2:3]
	v_lshl_add_u64 v[34:35], v[154:155], 2, v[34:35]
	global_store_dwordx4 v[46:47], v[38:41], off nt
	v_readlane_b32 s61, v250, 1
	v_readlane_b32 s64, v250, 4
	v_cvt_pk_bf16_f32 v38, v24, v25
	v_cvt_pk_bf16_f32 v39, v26, v27
	v_cvt_pk_bf16_f32 v40, v16, v17
	v_cvt_pk_bf16_f32 v41, v18, v19
	global_store_dwordx4 v[46:47], v[38:41], off offset:64 nt
	v_readlane_b32 s65, v250, 5
	v_readlane_b32 s66, v250, 6
	v_readlane_b32 s67, v250, 7
	global_store_dwordx4 v[34:35], v[28:31], off nt
	global_store_dwordx4 v[34:35], v[20:23], off offset:16 nt
	global_store_dwordx4 v[34:35], v[24:27], off offset:128 nt
	global_store_dwordx4 v[34:35], v[16:19], off offset:144 nt

;     __device__ __forceinline__ void operator()(const f32x4 (&acc)[2][2][4][2], const Unit& u, int wr, int wc, int fr, int fq) const {
;     ...
;                     if (pn < 8) {
; #pragma unroll
;                         for (int e = 0; e < 8; ++e) { ol[e] *= 0.18033688011112042f; oh[e] *= 0.18033688011112042f; }
;                         store8_bf16(qb + o512, ol); store8_bf16(qb + o512 + 32, oh);
.LBB0_616:
	s_andn2_b64 vcc, exec, s[6:7]
	s_cbranch_vccnz .LBB0_618
	v_readlane_b32 s2, v249, 4
	v_readlane_b32 s3, v249, 5
	v_mul_f32_e32 v28, 0x3e38aa3b, v28
	v_mul_f32_e32 v29, 0x3e38aa3b, v29
	v_mul_f32_e32 v30, 0x3e38aa3b, v30
	v_mul_f32_e32 v31, 0x3e38aa3b, v31
	v_mul_f32_e32 v33, 0x3e38aa3b, v20
	v_mul_f32_e32 v34, 0x3e38aa3b, v16
	v_mul_f32_e32 v35, 0x3e38aa3b, v21
	v_mul_f32_e32 v38, 0x3e38aa3b, v17
	v_mul_f32_e32 v22, 0x3e38aa3b, v22
	v_mul_f32_e32 v39, 0x3e38aa3b, v18
	v_mul_f32_e32 v23, 0x3e38aa3b, v23
	v_mul_f32_e32 v40, 0x3e38aa3b, v19
	v_lshl_add_u64 v[20:21], v[36:37], 1, s[2:3]
	v_cvt_pk_bf16_f32 v16, v28, v29
	v_cvt_pk_bf16_f32 v17, v30, v31
	v_cvt_pk_bf16_f32 v18, v33, v35
	v_cvt_pk_bf16_f32 v19, v22, v23
	v_mul_f32_e32 v24, 0x3e38aa3b, v24
	v_mul_f32_e32 v25, 0x3e38aa3b, v25
	v_mul_f32_e32 v26, 0x3e38aa3b, v26
	v_mul_f32_e32 v27, 0x3e38aa3b, v27
	global_store_dwordx4 v[20:21], v[16:19], off nt
	s_nop 1
	v_cvt_pk_bf16_f32 v16, v24, v25
	v_cvt_pk_bf16_f32 v17, v26, v27
	v_cvt_pk_bf16_f32 v18, v34, v38
	v_cvt_pk_bf16_f32 v19, v39, v40
	global_store_dwordx4 v[20:21], v[16:19], off offset:64 nt

;     __device__ __forceinline__ void operator()(const f32x4 (&acc)[2][2][4][2], const Unit& u, int wr, int wc, int fr, int fq) const {
;     ...
;                     const int ch = 128 * (pn - 2) + c8; float uu[8];
; #pragma unroll
;                     for (int e = 0; e < 8; ++e) uu[e] = lo[e] * hi[e];
;                     store8_bf16(ub + (size_t)r * 512 + ch, uu);
;                     if (!samp) { const int t = rl & (SEQ - 1); if (t >= SEQ - 2) store8_f32(out + OFF_CM_P + (size_t)((rl >> 13) * 2 + (t - (SEQ - 2))) * 512 + ch, uu); }
;                     else { const int tt = rl & 7; if (tt >= 6) store8_f32(out + OFF_CM_S + (size_t)((rl >> 3) * 2 + (tt - 6)) * 512 + ch, uu); }
.LBB0_619:
	s_andn2_b64 vcc, exec, s[8:9]
	s_cbranch_vccnz .LBB0_631
	v_ashrrev_i32_e32 v33, 31, v32
	v_lshlrev_b64 v[24:25], 10, v[32:33]
	v_lshl_add_u64 v[24:25], s[88:89], 0, v[24:25]
	v_pk_mul_f32 v[20:21], v[12:13], v[4:5]
	v_pk_mul_f32 v[22:23], v[14:15], v[6:7]
	v_pk_mul_f32 v[16:17], v[8:9], v[0:1]
	v_pk_mul_f32 v[18:19], v[10:11], v[2:3]
	v_lshl_add_u64 v[28:29], v[172:173], 1, v[24:25]
	s_andn2_b64 vcc, exec, s[84:85]
	v_cvt_pk_bf16_f32 v24, v20, v21
	v_cvt_pk_bf16_f32 v25, v22, v23
	v_cvt_pk_bf16_f32 v26, v16, v17
	v_cvt_pk_bf16_f32 v27, v18, v19
	global_store_dwordx4 v[28:29], v[24:27], off nt
	s_cbranch_vccnz .LBB0_624
	s_movk_i32 s2, 0x1ffd
	v_cmp_lt_u32_e32 vcc, s2, v44
	s_mov_b64 s[8:9], 0
	s_mov_b64 s[6:7], 0
	s_and_saveexec_b64 s[10:11], vcc
	s_ashr_i32 s6, s58, 12
	s_and_b32 s6, s6, -2
	s_addk_i32 s6, 0xe002
	v_add_u32_e32 v24, s6, v44
	s_mov_b64 s[6:7], exec
	s_or_b64 exec, exec, s[10:11]
	s_mov_b64 s[10:11], 0x8800000
	s_and_b64 vcc, exec, s[8:9]
	s_cbranch_vccnz .LBB0_625
	s_branch .LBB0_628

;     __device__ __forceinline__ void operator()(const f32x4 (&acc)[2][2][4][2], const Unit& u, int wr, int wc, int fr, int fq) const {
;     ...
;                     if (!samp) { const int t = rl & (SEQ - 1); if (t >= SEQ - 2) store8_f32(out + OFF_CM_P + (size_t)((rl >> 13) * 2 + (t - (SEQ - 2))) * 512 + ch, uu); }
;                     else { const int tt = rl & 7; if (tt >= 6) store8_f32(out + OFF_CM_S + (size_t)((rl >> 3) * 2 + (tt - 6)) * 512 + ch, uu); }
.LBB0_628:
	s_and_saveexec_b64 s[8:9], s[6:7]
	s_cbranch_execz .LBB0_630
	v_readlane_b32 s60, v250, 0
	v_readlane_b32 s62, v250, 2
	v_readlane_b32 s63, v250, 3
	s_add_u32 s6, s62, s10
	v_ashrrev_i32_e32 v25, 31, v24
	s_addc_u32 s7, s63, s11
	v_lshlrev_b64 v[24:25], 11, v[24:25]
	v_lshl_add_u64 v[24:25], s[6:7], 0, v[24:25]
	v_lshl_add_u64 v[24:25], v[172:173], 2, v[24:25]
	v_readlane_b32 s61, v250, 1
	v_readlane_b32 s64, v250, 4
	v_readlane_b32 s65, v250, 5
	v_readlane_b32 s66, v250, 6
	v_readlane_b32 s67, v250, 7
	global_store_dwordx4 v[24:25], v[20:23], off nt
	global_store_dwordx4 v[24:25], v[16:19], off offset:16 nt

;     __device__ __forceinline__ void operator()(const f32x4 (&acc)[2][2][4][2], const Unit& u, int wr, int wc, int fr, int fq) const {
;     ...
;                 if (pn < 2) {
;                     store8_bf16(cbb + (size_t)r * 512 + pn * 256 + c8, lo); store8_bf16(cbb + (size_t)r * 512 + pn * 256 + 128 + c8, hi);
.LBB0_632:
	s_andn2_b64 vcc, exec, s[10:11]
	s_cbranch_vccnz .LBB0_634
	v_ashrrev_i32_e32 v33, 31, v32
	v_lshlrev_b64 v[16:17], 10, v[32:33]
	v_lshl_add_u64 v[16:17], s[22:23], 0, v[16:17]
	v_lshl_add_u64 v[16:17], s[56:57], 1, v[16:17]
	v_lshl_add_u64 v[16:17], v[156:157], 1, v[16:17]
	v_cvt_pk_bf16_f32 v12, v12, v13
	v_cvt_pk_bf16_f32 v13, v14, v15
	v_cvt_pk_bf16_f32 v14, v8, v9
	v_cvt_pk_bf16_f32 v15, v10, v11
	global_store_dwordx4 v[16:17], v[12:15], off nt
	v_cvt_pk_bf16_f32 v4, v4, v5
	v_cvt_pk_bf16_f32 v5, v6, v7
	v_cvt_pk_bf16_f32 v6, v0, v1
	v_cvt_pk_bf16_f32 v7, v2, v3
	global_store_dwordx4 v[16:17], v[4:7], off offset:256 nt
